# GEMM MFMA blocks: s_setprio 1 moved before the opening barrier, s_setprio 0 after the closing barrier (plus earlier wait cleanup edits)
# baseline (speedup 1.0000x reference)
; #define PG8_STAGE(bufoff, gbase, voff) do { _Pragma("unroll") for (int _i = 0; _i < 2; ++_i) { unsigned keep_; \
;         asm volatile("s_mov_b32 %0, m0\n\ts_mov_b32 m0, %3\n\ts_nop 0\n\tglobal_load_lds_dwordx4 %1, %2\n\ts_mov_b32 m0, %0" \
;             : "=&s"(keep_) : "v"((voff)[_i]), "s"((const void*)(gbase)), "s"(ldsb0 + (unsigned)(bufoff) + (unsigned)(_i * 8192)) : "memory"); } } while (0)
; #define PG8_LDA(dst, b, h) do { _Pragma("unroll") for (int m = 0; m < 4; ++m) _Pragma("unroll") for (int k = 0; k < 2; ++k) dst[m][k] = *(const LAS bf16x8*)(lds + PG8_SA(b, h) + aoff + m * 2048 + k * 1024); } while (0)
; #define PG8_LDB(dst, b, h) do { _Pragma("unroll") for (int n = 0; n < 2; ++n) _Pragma("unroll") for (int k = 0; k < 2; ++k) dst[n][k] = *(const LAS bf16x8*)(lds + PG8_SB(b, h) + boff + n * 2048 + k * 1024); } while (0)
; #define PG8_WAIT_V(n) asm volatile("s_waitcnt vmcnt(" #n ")" ::: "memory")
; #define PG8_WAIT_L(n) asm volatile("s_waitcnt lgkmcnt(" #n ")" ::: "memory")
; #define PG8_BAR __builtin_amdgcn_s_barrier()
; #define PG8_SCHED __builtin_amdgcn_sched_barrier(0)
; template <class Epi, class Sched, bool ALIGN_EPI>
; __device__ __forceinline__ void gemm_phase(LAS unsigned char* lds, const Gemm g, const Sched& S, const Epi& E) {
;     ...
;             PG8_LDB(B0, 0, 0); PG8_LDB(B1, 0, 1); PG8_SCHED; PG8_LDA(At, 0, 0); PG8_STAGE(PG8_SA(1, 1), a1 + hstepA, voffA);
;             PG8_WAIT_V(8); PG8_WAIT_L(0); PG8_BAR; PG8_MMA(0, 0, At, B0); PG8_MMA(0, 1, At, B1); PG8_BAR; PG8_SCHED;
;             PG8_LDA(At, 0, 1); PG8_STAGE(PG8_SB(0, 0), b2, voffB); PG8_STAGE(PG8_SB(0, 1), b2 + hstepB, voffB); PG8_STAGE(PG8_SA(0, 0), a2, voffA);
;             PG8_WAIT_V(8); PG8_WAIT_L(0); PG8_BAR; PG8_MMA(1, 0, At, B0); PG8_MMA(1, 1, At, B1); PG8_BAR; PG8_SCHED;
;             PG8_LDB(B0, 1, 0); PG8_LDB(B1, 1, 1); PG8_SCHED; PG8_LDA(At, 1, 0); PG8_STAGE(PG8_SA(0, 1), a2 + hstepA, voffA);
;             PG8_WAIT_V(8); PG8_WAIT_L(0); PG8_BAR; PG8_MMA(0, 0, At, B0); PG8_MMA(0, 1, At, B1); PG8_BAR; PG8_SCHED;
;             PG8_LDA(At, 1, 1); PG8_STAGE(PG8_SB(1, 0), b3, voffB); PG8_STAGE(PG8_SB(1, 1), b3 + hstepB, voffB); PG8_STAGE(PG8_SA(1, 0), a3, voffA);
;             PG8_WAIT_V(8); PG8_WAIT_L(0); PG8_BAR; PG8_MMA(1, 0, At, B0); PG8_MMA(1, 1, At, B1); PG8_BAR; PG8_SCHED;
.LBB0_113:
	ds_read_b128 v[136:139], v157
	ds_read_b128 v[140:143], v157 offset:1024
	ds_read_b128 v[144:147], v157 offset:2048
	ds_read_b128 v[172:175], v157 offset:3072
	ds_read_b128 v[180:183], v158
	ds_read_b128 v[184:187], v158 offset:1024
	ds_read_b128 v[188:191], v158 offset:2048
	ds_read_b128 v[192:195], v158 offset:3072
	s_add_u32 s6, s4, 0x100
	s_addc_u32 s7, s5, 0
	s_cmp_eq_u32 s81, 28
	s_cselect_b32 s50, s39, s6
	s_cselect_b32 s51, s24, s7
	s_cselect_b32 s48, s58, s59
	s_cselect_b32 s49, s41, s80
	s_add_u32 s8, s50, 0x80
	s_addc_u32 s9, s51, 0
	ds_read_b128 v[196:199], v159
	ds_read_b128 v[206:209], v159 offset:1024
	ds_read_b128 v[210:213], v159 offset:2048
	ds_read_b128 v[214:217], v159 offset:3072
	ds_read_b128 v[218:221], v159 offset:4096
	ds_read_b128 v[222:225], v159 offset:5120
	ds_read_b128 v[226:229], v159 offset:6144
	ds_read_b128 v[230:233], v159 offset:7168
	s_add_u32 s4, s4, 0x80080
	s_addc_u32 s5, s5, 0
	s_mov_b32 m0, s75
	s_nop 0
	global_load_lds_dwordx4 v151, s[4:5]
	s_nop 0
	s_mov_b32 m0, s77
	s_nop 0
	global_load_lds_dwordx4 v153, s[4:5]
	s_waitcnt vmcnt(8)
	s_waitcnt lgkmcnt(0)
	s_setprio 1
	s_barrier
	v_mfma_f32_16x16x32_bf16 v[126:129], v[136:139], v[196:199], v[126:129]
	v_mfma_f32_16x16x32_bf16 v[122:125], v[144:147], v[196:199], v[122:125]
	v_mfma_f32_16x16x32_bf16 v[110:113], v[136:139], v[210:213], v[110:113]
	v_mfma_f32_16x16x32_bf16 v[106:109], v[144:147], v[210:213], v[106:109]
	v_mfma_f32_16x16x32_bf16 v[94:97], v[136:139], v[218:221], v[94:97]
	v_mfma_f32_16x16x32_bf16 v[90:93], v[144:147], v[218:221], v[90:93]
	v_mfma_f32_16x16x32_bf16 v[78:81], v[136:139], v[226:229], v[78:81]
	v_mfma_f32_16x16x32_bf16 v[74:77], v[144:147], v[226:229], v[74:77]
	v_mfma_f32_16x16x32_bf16 v[126:129], v[140:143], v[206:209], v[126:129]
	v_mfma_f32_16x16x32_bf16 v[122:125], v[172:175], v[206:209], v[122:125]
	v_mfma_f32_16x16x32_bf16 v[110:113], v[140:143], v[214:217], v[110:113]
	v_mfma_f32_16x16x32_bf16 v[106:109], v[172:175], v[214:217], v[106:109]
	v_mfma_f32_16x16x32_bf16 v[94:97], v[140:143], v[222:225], v[94:97]
	v_mfma_f32_16x16x32_bf16 v[90:93], v[172:175], v[222:225], v[90:93]
	v_mfma_f32_16x16x32_bf16 v[78:81], v[140:143], v[230:233], v[78:81]
	v_mfma_f32_16x16x32_bf16 v[74:77], v[172:175], v[230:233], v[74:77]
	v_mfma_f32_16x16x32_bf16 v[118:121], v[180:183], v[196:199], v[118:121]
	v_mfma_f32_16x16x32_bf16 v[114:117], v[188:191], v[196:199], v[114:117]
	v_mfma_f32_16x16x32_bf16 v[102:105], v[180:183], v[210:213], v[102:105]
	v_mfma_f32_16x16x32_bf16 v[98:101], v[188:191], v[210:213], v[98:101]
	v_mfma_f32_16x16x32_bf16 v[86:89], v[180:183], v[218:221], v[86:89]
	v_mfma_f32_16x16x32_bf16 v[82:85], v[188:191], v[218:221], v[82:85]
	v_mfma_f32_16x16x32_bf16 v[70:73], v[180:183], v[226:229], v[70:73]
	v_mfma_f32_16x16x32_bf16 v[66:69], v[188:191], v[226:229], v[66:69]
	v_mfma_f32_16x16x32_bf16 v[118:121], v[184:187], v[206:209], v[118:121]
	v_mfma_f32_16x16x32_bf16 v[114:117], v[192:195], v[206:209], v[114:117]
	v_mfma_f32_16x16x32_bf16 v[102:105], v[184:187], v[214:217], v[102:105]
	v_mfma_f32_16x16x32_bf16 v[98:101], v[192:195], v[214:217], v[98:101]
	v_mfma_f32_16x16x32_bf16 v[86:89], v[184:187], v[222:225], v[86:89]
	v_mfma_f32_16x16x32_bf16 v[82:85], v[192:195], v[222:225], v[82:85]
	v_mfma_f32_16x16x32_bf16 v[70:73], v[184:187], v[230:233], v[70:73]
	v_mfma_f32_16x16x32_bf16 v[66:69], v[192:195], v[230:233], v[66:69]
	s_barrier
	s_setprio 0
	ds_read_b128 v[196:199], v159 offset:16384
	ds_read_b128 v[206:209], v159 offset:17408
	ds_read_b128 v[210:213], v159 offset:18432
	ds_read_b128 v[214:217], v159 offset:19456
	ds_read_b128 v[218:221], v159 offset:20480
	ds_read_b128 v[222:225], v159 offset:21504
	ds_read_b128 v[226:229], v159 offset:22528
	ds_read_b128 v[230:233], v159 offset:23552
	s_mov_b32 m0, s23
	s_nop 0
	global_load_lds_dwordx4 v152, s[48:49]
	s_nop 0
	s_mov_b32 m0, s62
	s_nop 0
	global_load_lds_dwordx4 v154, s[48:49]
	s_add_u32 s4, s48, 0x80000
	s_addc_u32 s5, s49, 0
	s_mov_b32 m0, s63
	s_nop 0
	global_load_lds_dwordx4 v152, s[4:5]
	s_nop 0
	s_mov_b32 m0, s64
	s_nop 0
	global_load_lds_dwordx4 v154, s[4:5]
	s_mov_b32 m0, s61
	s_nop 0
	global_load_lds_dwordx4 v151, s[50:51]
	s_nop 0
	s_mov_b32 m0, s65
	s_nop 0
	global_load_lds_dwordx4 v153, s[50:51]
	s_waitcnt vmcnt(8)
	s_waitcnt lgkmcnt(0)
	s_setprio 1
	s_barrier
	v_mfma_f32_16x16x32_bf16 v[62:65], v[136:139], v[196:199], v[62:65]
	v_mfma_f32_16x16x32_bf16 v[58:61], v[144:147], v[196:199], v[58:61]
	v_mfma_f32_16x16x32_bf16 v[46:49], v[136:139], v[210:213], v[46:49]
	v_mfma_f32_16x16x32_bf16 v[42:45], v[144:147], v[210:213], v[42:45]
	v_mfma_f32_16x16x32_bf16 v[30:33], v[136:139], v[218:221], v[30:33]
	v_mfma_f32_16x16x32_bf16 v[26:29], v[144:147], v[218:221], v[26:29]
	v_mfma_f32_16x16x32_bf16 v[14:17], v[136:139], v[226:229], v[14:17]
	v_mfma_f32_16x16x32_bf16 v[10:13], v[144:147], v[226:229], v[10:13]
	v_mfma_f32_16x16x32_bf16 v[62:65], v[140:143], v[206:209], v[62:65]
	v_mfma_f32_16x16x32_bf16 v[58:61], v[172:175], v[206:209], v[58:61]
	v_mfma_f32_16x16x32_bf16 v[46:49], v[140:143], v[214:217], v[46:49]
	v_mfma_f32_16x16x32_bf16 v[42:45], v[172:175], v[214:217], v[42:45]
	v_mfma_f32_16x16x32_bf16 v[30:33], v[140:143], v[222:225], v[30:33]
	v_mfma_f32_16x16x32_bf16 v[26:29], v[172:175], v[222:225], v[26:29]
	v_mfma_f32_16x16x32_bf16 v[14:17], v[140:143], v[230:233], v[14:17]
	v_mfma_f32_16x16x32_bf16 v[10:13], v[172:175], v[230:233], v[10:13]
	v_mfma_f32_16x16x32_bf16 v[54:57], v[180:183], v[196:199], v[54:57]
	v_mfma_f32_16x16x32_bf16 v[50:53], v[188:191], v[196:199], v[50:53]
	v_mfma_f32_16x16x32_bf16 v[38:41], v[180:183], v[210:213], v[38:41]
	v_mfma_f32_16x16x32_bf16 v[34:37], v[188:191], v[210:213], v[34:37]
	v_mfma_f32_16x16x32_bf16 v[22:25], v[180:183], v[218:221], v[22:25]
	v_mfma_f32_16x16x32_bf16 v[18:21], v[188:191], v[218:221], v[18:21]
	v_mfma_f32_16x16x32_bf16 v[6:9], v[180:183], v[226:229], v[6:9]
	v_mfma_f32_16x16x32_bf16 v[2:5], v[188:191], v[226:229], v[2:5]
	v_mfma_f32_16x16x32_bf16 v[54:57], v[184:187], v[206:209], v[54:57]
	v_mfma_f32_16x16x32_bf16 v[50:53], v[192:195], v[206:209], v[50:53]
	v_mfma_f32_16x16x32_bf16 v[38:41], v[184:187], v[214:217], v[38:41]
	v_mfma_f32_16x16x32_bf16 v[34:37], v[192:195], v[214:217], v[34:37]
	v_mfma_f32_16x16x32_bf16 v[22:25], v[184:187], v[222:225], v[22:25]
	v_mfma_f32_16x16x32_bf16 v[18:21], v[192:195], v[222:225], v[18:21]
	v_mfma_f32_16x16x32_bf16 v[6:9], v[184:187], v[230:233], v[6:9]
	v_mfma_f32_16x16x32_bf16 v[2:5], v[192:195], v[230:233], v[2:5]
	s_barrier
; #define PG8_STAGE(bufoff, gbase, voff) do { _Pragma("unroll") for (int _i = 0; _i < 2; ++_i) { unsigned keep_; \
;         asm volatile("s_mov_b32 %0, m0\n\ts_mov_b32 m0, %3\n\ts_nop 0\n\tglobal_load_lds_dwordx4 %1, %2\n\ts_mov_b32 m0, %0" \
;             : "=&s"(keep_) : "v"((voff)[_i]), "s"((const void*)(gbase)), "s"(ldsb0 + (unsigned)(bufoff) + (unsigned)(_i * 8192)) : "memory"); } } while (0)
; #define PG8_LDA(dst, b, h) do { _Pragma("unroll") for (int m = 0; m < 4; ++m) _Pragma("unroll") for (int k = 0; k < 2; ++k) dst[m][k] = *(const LAS bf16x8*)(lds + PG8_SA(b, h) + aoff + m * 2048 + k * 1024); } while (0)
; #define PG8_LDB(dst, b, h) do { _Pragma("unroll") for (int n = 0; n < 2; ++n) _Pragma("unroll") for (int k = 0; k < 2; ++k) dst[n][k] = *(const LAS bf16x8*)(lds + PG8_SB(b, h) + boff + n * 2048 + k * 1024); } while (0)
; #define PG8_WAIT_V(n) asm volatile("s_waitcnt vmcnt(" #n ")" ::: "memory")
; #define PG8_WAIT_L(n) asm volatile("s_waitcnt lgkmcnt(" #n ")" ::: "memory")
; #define PG8_BAR __builtin_amdgcn_s_barrier()
; #define PG8_SCHED __builtin_amdgcn_sched_barrier(0)
; template <class Epi, class Sched, bool ALIGN_EPI>
; __device__ __forceinline__ void gemm_phase(LAS unsigned char* lds, const Gemm g, const Sched& S, const Epi& E) {
;     ...
;             PG8_LDB(B0, 0, 0); PG8_LDB(B1, 0, 1); PG8_SCHED; PG8_LDA(At, 0, 0); PG8_STAGE(PG8_SA(1, 1), a1 + hstepA, voffA);
;             PG8_WAIT_V(8); PG8_WAIT_L(0); PG8_BAR; PG8_MMA(0, 0, At, B0); PG8_MMA(0, 1, At, B1); PG8_BAR; PG8_SCHED;
;             PG8_LDA(At, 0, 1); PG8_STAGE(PG8_SB(0, 0), b2, voffB); PG8_STAGE(PG8_SB(0, 1), b2 + hstepB, voffB); PG8_STAGE(PG8_SA(0, 0), a2, voffA);
;             PG8_WAIT_V(8); PG8_WAIT_L(0); PG8_BAR; PG8_MMA(1, 0, At, B0); PG8_MMA(1, 1, At, B1); PG8_BAR; PG8_SCHED;
;             PG8_LDB(B0, 1, 0); PG8_LDB(B1, 1, 1); PG8_SCHED; PG8_LDA(At, 1, 0); PG8_STAGE(PG8_SA(0, 1), a2 + hstepA, voffA);
;             PG8_WAIT_V(8); PG8_WAIT_L(0); PG8_BAR; PG8_MMA(0, 0, At, B0); PG8_MMA(0, 1, At, B1); PG8_BAR; PG8_SCHED;
;             PG8_LDA(At, 1, 1); PG8_STAGE(PG8_SB(1, 0), b3, voffB); PG8_STAGE(PG8_SB(1, 1), b3 + hstepB, voffB); PG8_STAGE(PG8_SA(1, 0), a3, voffA);
;             PG8_WAIT_V(8); PG8_WAIT_L(0); PG8_BAR; PG8_MMA(1, 0, At, B0); PG8_MMA(1, 1, At, B1); PG8_BAR; PG8_SCHED;
	s_setprio 0
	ds_read_b128 v[136:139], v160
	ds_read_b128 v[140:143], v160 offset:1024
	ds_read_b128 v[144:147], v160 offset:2048
	ds_read_b128 v[172:175], v160 offset:3072
	ds_read_b128 v[180:183], v161
	ds_read_b128 v[184:187], v161 offset:1024
	ds_read_b128 v[188:191], v161 offset:2048
	ds_read_b128 v[192:195], v161 offset:3072
	ds_read_b128 v[196:199], v159 offset:32768
	ds_read_b128 v[206:209], v159 offset:33792
	ds_read_b128 v[210:213], v159 offset:34816
	ds_read_b128 v[214:217], v159 offset:35840
	ds_read_b128 v[218:221], v159 offset:36864
	ds_read_b128 v[222:225], v159 offset:37888
	ds_read_b128 v[226:229], v159 offset:38912
	ds_read_b128 v[230:233], v159 offset:39936
	s_add_u32 s4, s50, 0x80000
	s_addc_u32 s5, s51, 0
	s_mov_b32 m0, s66
	s_nop 0
	global_load_lds_dwordx4 v151, s[4:5]
	s_nop 0
	s_mov_b32 m0, s67
	s_nop 0
	global_load_lds_dwordx4 v153, s[4:5]
	s_waitcnt vmcnt(8)
	s_waitcnt lgkmcnt(0)
	s_setprio 1
	s_barrier
	v_mfma_f32_16x16x32_bf16 v[126:129], v[136:139], v[196:199], v[126:129]
	v_mfma_f32_16x16x32_bf16 v[122:125], v[144:147], v[196:199], v[122:125]
	v_mfma_f32_16x16x32_bf16 v[110:113], v[136:139], v[210:213], v[110:113]
	v_mfma_f32_16x16x32_bf16 v[106:109], v[144:147], v[210:213], v[106:109]
	v_mfma_f32_16x16x32_bf16 v[94:97], v[136:139], v[218:221], v[94:97]
	v_mfma_f32_16x16x32_bf16 v[90:93], v[144:147], v[218:221], v[90:93]
	v_mfma_f32_16x16x32_bf16 v[78:81], v[136:139], v[226:229], v[78:81]
	v_mfma_f32_16x16x32_bf16 v[74:77], v[144:147], v[226:229], v[74:77]
	v_mfma_f32_16x16x32_bf16 v[126:129], v[140:143], v[206:209], v[126:129]
	v_mfma_f32_16x16x32_bf16 v[122:125], v[172:175], v[206:209], v[122:125]
	v_mfma_f32_16x16x32_bf16 v[110:113], v[140:143], v[214:217], v[110:113]
	v_mfma_f32_16x16x32_bf16 v[106:109], v[172:175], v[214:217], v[106:109]
	v_mfma_f32_16x16x32_bf16 v[94:97], v[140:143], v[222:225], v[94:97]
	v_mfma_f32_16x16x32_bf16 v[90:93], v[172:175], v[222:225], v[90:93]
	v_mfma_f32_16x16x32_bf16 v[78:81], v[140:143], v[230:233], v[78:81]
	v_mfma_f32_16x16x32_bf16 v[74:77], v[172:175], v[230:233], v[74:77]
	v_mfma_f32_16x16x32_bf16 v[118:121], v[180:183], v[196:199], v[118:121]
	v_mfma_f32_16x16x32_bf16 v[114:117], v[188:191], v[196:199], v[114:117]
	v_mfma_f32_16x16x32_bf16 v[102:105], v[180:183], v[210:213], v[102:105]
	v_mfma_f32_16x16x32_bf16 v[98:101], v[188:191], v[210:213], v[98:101]
	v_mfma_f32_16x16x32_bf16 v[86:89], v[180:183], v[218:221], v[86:89]
	v_mfma_f32_16x16x32_bf16 v[82:85], v[188:191], v[218:221], v[82:85]
	v_mfma_f32_16x16x32_bf16 v[70:73], v[180:183], v[226:229], v[70:73]
	v_mfma_f32_16x16x32_bf16 v[66:69], v[188:191], v[226:229], v[66:69]
	v_mfma_f32_16x16x32_bf16 v[118:121], v[184:187], v[206:209], v[118:121]
	v_mfma_f32_16x16x32_bf16 v[114:117], v[192:195], v[206:209], v[114:117]
	v_mfma_f32_16x16x32_bf16 v[102:105], v[184:187], v[214:217], v[102:105]
	v_mfma_f32_16x16x32_bf16 v[98:101], v[192:195], v[214:217], v[98:101]
	v_mfma_f32_16x16x32_bf16 v[86:89], v[184:187], v[222:225], v[86:89]
	v_mfma_f32_16x16x32_bf16 v[82:85], v[192:195], v[222:225], v[82:85]
	v_mfma_f32_16x16x32_bf16 v[70:73], v[184:187], v[230:233], v[70:73]
	v_mfma_f32_16x16x32_bf16 v[66:69], v[192:195], v[230:233], v[66:69]
	s_barrier
	s_setprio 0
	ds_read_b128 v[196:199], v159 offset:49152
	ds_read_b128 v[206:209], v159 offset:50176
	ds_read_b128 v[210:213], v159 offset:51200
	ds_read_b128 v[214:217], v159 offset:52224
	ds_read_b128 v[218:221], v159 offset:53248
	ds_read_b128 v[222:225], v159 offset:54272
	ds_read_b128 v[226:229], v159 offset:55296
	ds_read_b128 v[230:233], v159 offset:56320
	s_add_u32 s4, s48, 0x80
	s_addc_u32 s5, s49, 0
	s_mov_b32 m0, s69
	s_nop 0
	global_load_lds_dwordx4 v152, s[4:5]
	s_nop 0
	s_mov_b32 m0, s70
	s_nop 0
	global_load_lds_dwordx4 v154, s[4:5]
	s_add_u32 s4, s48, 0x80080
	s_addc_u32 s5, s49, 0
	s_mov_b32 m0, s73
	s_nop 0
	global_load_lds_dwordx4 v152, s[4:5]
	s_nop 0
	s_mov_b32 m0, s74
	s_nop 0
	global_load_lds_dwordx4 v154, s[4:5]
	s_mov_b32 m0, s71
	s_nop 0
	global_load_lds_dwordx4 v151, s[8:9]
	s_nop 0
	s_mov_b32 m0, s72
	s_nop 0
	global_load_lds_dwordx4 v153, s[8:9]
	s_waitcnt vmcnt(8)
	s_waitcnt lgkmcnt(0)
	s_setprio 1
	s_barrier
	v_mfma_f32_16x16x32_bf16 v[62:65], v[136:139], v[196:199], v[62:65]
	v_mfma_f32_16x16x32_bf16 v[58:61], v[144:147], v[196:199], v[58:61]
	v_mfma_f32_16x16x32_bf16 v[46:49], v[136:139], v[210:213], v[46:49]
	v_mfma_f32_16x16x32_bf16 v[42:45], v[144:147], v[210:213], v[42:45]
	v_mfma_f32_16x16x32_bf16 v[30:33], v[136:139], v[218:221], v[30:33]
	v_mfma_f32_16x16x32_bf16 v[26:29], v[144:147], v[218:221], v[26:29]
	v_mfma_f32_16x16x32_bf16 v[14:17], v[136:139], v[226:229], v[14:17]
	v_mfma_f32_16x16x32_bf16 v[10:13], v[144:147], v[226:229], v[10:13]
	v_mfma_f32_16x16x32_bf16 v[62:65], v[140:143], v[206:209], v[62:65]
	v_mfma_f32_16x16x32_bf16 v[58:61], v[172:175], v[206:209], v[58:61]
	v_mfma_f32_16x16x32_bf16 v[46:49], v[140:143], v[214:217], v[46:49]
	v_mfma_f32_16x16x32_bf16 v[42:45], v[172:175], v[214:217], v[42:45]
	v_mfma_f32_16x16x32_bf16 v[30:33], v[140:143], v[222:225], v[30:33]
	v_mfma_f32_16x16x32_bf16 v[26:29], v[172:175], v[222:225], v[26:29]
	v_mfma_f32_16x16x32_bf16 v[14:17], v[140:143], v[230:233], v[14:17]
	v_mfma_f32_16x16x32_bf16 v[10:13], v[172:175], v[230:233], v[10:13]
	v_mfma_f32_16x16x32_bf16 v[54:57], v[180:183], v[196:199], v[54:57]
	v_mfma_f32_16x16x32_bf16 v[50:53], v[188:191], v[196:199], v[50:53]
	v_mfma_f32_16x16x32_bf16 v[38:41], v[180:183], v[210:213], v[38:41]
	v_mfma_f32_16x16x32_bf16 v[34:37], v[188:191], v[210:213], v[34:37]
	v_mfma_f32_16x16x32_bf16 v[22:25], v[180:183], v[218:221], v[22:25]
	v_mfma_f32_16x16x32_bf16 v[18:21], v[188:191], v[218:221], v[18:21]
	v_mfma_f32_16x16x32_bf16 v[6:9], v[180:183], v[226:229], v[6:9]
	v_mfma_f32_16x16x32_bf16 v[2:5], v[188:191], v[226:229], v[2:5]
	v_mfma_f32_16x16x32_bf16 v[54:57], v[184:187], v[206:209], v[54:57]
	v_mfma_f32_16x16x32_bf16 v[50:53], v[192:195], v[206:209], v[50:53]
	v_mfma_f32_16x16x32_bf16 v[38:41], v[184:187], v[214:217], v[38:41]
	v_mfma_f32_16x16x32_bf16 v[34:37], v[192:195], v[214:217], v[34:37]
	v_mfma_f32_16x16x32_bf16 v[22:25], v[184:187], v[222:225], v[22:25]
	v_mfma_f32_16x16x32_bf16 v[18:21], v[192:195], v[222:225], v[18:21]
	v_mfma_f32_16x16x32_bf16 v[6:9], v[184:187], v[230:233], v[6:9]
	v_mfma_f32_16x16x32_bf16 v[2:5], v[192:195], v[230:233], v[2:5]
	s_barrier
	s_setprio 0
	s_add_i32 s81, s81, 2
	s_add_u32 s59, s59, 0x100
	s_addc_u32 s80, s80, 0
	s_cmp_gt_u32 s81, 29
	s_mov_b64 s[4:5], s[6:7]
	s_cbranch_scc0 .LBB0_113
	s_and_b64 vcc, exec, s[36:37]
	s_cbranch_vccz .LBB0_116
	s_barrier

; #define PG8_STAGE(bufoff, gbase, voff) do { _Pragma("unroll") for (int _i = 0; _i < 2; ++_i) { unsigned keep_; \
;         asm volatile("s_mov_b32 %0, m0\n\ts_mov_b32 m0, %3\n\ts_nop 0\n\tglobal_load_lds_dwordx4 %1, %2\n\ts_mov_b32 m0, %0" \
;             : "=&s"(keep_) : "v"((voff)[_i]), "s"((const void*)(gbase)), "s"(ldsb0 + (unsigned)(bufoff) + (unsigned)(_i * 8192)) : "memory"); } } while (0)
; #define PG8_LDA(dst, b, h) do { _Pragma("unroll") for (int m = 0; m < 4; ++m) _Pragma("unroll") for (int k = 0; k < 2; ++k) dst[m][k] = *(const LAS bf16x8*)(lds + PG8_SA(b, h) + aoff + m * 2048 + k * 1024); } while (0)
; #define PG8_LDB(dst, b, h) do { _Pragma("unroll") for (int n = 0; n < 2; ++n) _Pragma("unroll") for (int k = 0; k < 2; ++k) dst[n][k] = *(const LAS bf16x8*)(lds + PG8_SB(b, h) + boff + n * 2048 + k * 1024); } while (0)
; #define PG8_WAIT_V(n) asm volatile("s_waitcnt vmcnt(" #n ")" ::: "memory")
; #define PG8_WAIT_L(n) asm volatile("s_waitcnt lgkmcnt(" #n ")" ::: "memory")
; #define PG8_BAR __builtin_amdgcn_s_barrier()
; #define PG8_SCHED __builtin_amdgcn_sched_barrier(0)
; template <class Epi, class Sched, bool ALIGN_EPI>
; __device__ __forceinline__ void gemm_phase(LAS unsigned char* lds, const Gemm g, const Sched& S, const Epi& E) {
;     ...
;             PG8_LDB(B0, 0, 0); PG8_LDB(B1, 0, 1); PG8_SCHED; PG8_LDA(At, 0, 0); PG8_STAGE(PG8_SA(1, 1), a1 + hstepA, voffA);
;             PG8_WAIT_V(8); PG8_WAIT_L(0); PG8_BAR; PG8_MMA(0, 0, At, B0); PG8_MMA(0, 1, At, B1); PG8_BAR; PG8_SCHED;
;             PG8_LDA(At, 0, 1); PG8_STAGE(PG8_SB(0, 0), b2, voffB); PG8_STAGE(PG8_SB(0, 1), b2 + hstepB, voffB); PG8_STAGE(PG8_SA(0, 0), a2, voffA);
;             PG8_WAIT_V(8); PG8_WAIT_L(0); PG8_BAR; PG8_MMA(1, 0, At, B0); PG8_MMA(1, 1, At, B1); PG8_BAR; PG8_SCHED;
;             PG8_LDB(B0, 1, 0); PG8_LDB(B1, 1, 1); PG8_SCHED; PG8_LDA(At, 1, 0); PG8_STAGE(PG8_SA(0, 1), a2 + hstepA, voffA);
;             PG8_WAIT_V(8); PG8_WAIT_L(0); PG8_BAR; PG8_MMA(0, 0, At, B0); PG8_MMA(0, 1, At, B1); PG8_BAR; PG8_SCHED;
;             PG8_LDA(At, 1, 1); PG8_STAGE(PG8_SB(1, 0), b3, voffB); PG8_STAGE(PG8_SB(1, 1), b3 + hstepB, voffB); PG8_STAGE(PG8_SA(1, 0), a3, voffA);
;             PG8_WAIT_V(8); PG8_WAIT_L(0); PG8_BAR; PG8_MMA(1, 0, At, B0); PG8_MMA(1, 1, At, B1); PG8_BAR; PG8_SCHED;
.LBB0_805:
	s_add_u32 s48, s34, s40
	s_addc_u32 s49, s35, s41
	s_add_u32 s44, s48, 0x100
	s_addc_u32 s45, s49, 0
	s_and_b64 s[42:43], s[38:39], exec
	s_cselect_b32 s45, s3, s45
	s_cselect_b32 s44, s17, s44
	s_add_u32 s40, s30, s40
	s_addc_u32 s41, s31, s41
	s_add_u32 s42, s40, 0x100
	s_addc_u32 s43, s41, 0
	s_add_u32 s40, s44, 0x80
	s_addc_u32 s41, s45, 0
	ds_read_b128 v[130:133], v151
	s_waitcnt vmcnt(7)
	ds_read_b128 v[134:137], v151 offset:1024
	ds_read_b128 v[156:159], v151 offset:2048
	s_waitcnt vmcnt(0)
	ds_read_b128 v[160:163], v151 offset:3072
	ds_read_b128 v[164:167], v152
	ds_read_b128 v[168:171], v152 offset:1024
	ds_read_b128 v[172:175], v152 offset:2048
	ds_read_b128 v[180:183], v152 offset:3072
	s_and_b64 s[38:39], s[38:39], exec
	s_cselect_b32 s47, s15, s43
	s_cselect_b32 s46, s72, s42
	s_add_u32 s52, s48, 0x40080
	s_addc_u32 s53, s49, 0
	s_add_u32 s48, s46, 0x10000
	s_addc_u32 s49, s47, 0
	s_add_u32 s42, s44, 0x40000
	s_addc_u32 s43, s45, 0
	s_add_u32 s38, s46, 0x80
	s_addc_u32 s39, s47, 0
	s_add_u32 s50, s46, 0x10080
	s_addc_u32 s51, s47, 0
	ds_read_b128 v[184:187], v153
	ds_read_b128 v[188:191], v153 offset:1024
	ds_read_b128 v[192:195], v153 offset:2048
	ds_read_b128 v[196:199], v153 offset:3072
	ds_read_b128 v[200:203], v153 offset:4096
	ds_read_b128 v[204:207], v153 offset:5120
	ds_read_b128 v[208:211], v153 offset:6144
	ds_read_b128 v[212:215], v153 offset:7168
	s_mov_b32 m0, s70
	s_nop 0
	global_load_lds_dwordx4 v144, s[52:53]
	s_nop 0
	s_mov_b32 m0, s71
	s_nop 0
	global_load_lds_dwordx4 v146, s[52:53]
	s_waitcnt vmcnt(8)
	s_waitcnt lgkmcnt(0)
	s_setprio 1
	s_barrier
	v_mfma_f32_16x16x32_bf16 v[126:129], v[130:133], v[184:187], v[126:129]
	v_mfma_f32_16x16x32_bf16 v[122:125], v[156:159], v[184:187], v[122:125]
	v_mfma_f32_16x16x32_bf16 v[118:121], v[130:133], v[192:195], v[118:121]
	v_mfma_f32_16x16x32_bf16 v[114:117], v[156:159], v[192:195], v[114:117]
	v_mfma_f32_16x16x32_bf16 v[110:113], v[130:133], v[200:203], v[110:113]
	v_mfma_f32_16x16x32_bf16 v[106:109], v[156:159], v[200:203], v[106:109]
	v_mfma_f32_16x16x32_bf16 v[102:105], v[130:133], v[208:211], v[102:105]
	v_mfma_f32_16x16x32_bf16 v[98:101], v[156:159], v[208:211], v[98:101]
	v_mfma_f32_16x16x32_bf16 v[126:129], v[134:137], v[188:191], v[126:129]
	v_mfma_f32_16x16x32_bf16 v[122:125], v[160:163], v[188:191], v[122:125]
	v_mfma_f32_16x16x32_bf16 v[118:121], v[134:137], v[196:199], v[118:121]
	v_mfma_f32_16x16x32_bf16 v[114:117], v[160:163], v[196:199], v[114:117]
	v_mfma_f32_16x16x32_bf16 v[110:113], v[134:137], v[204:207], v[110:113]
	v_mfma_f32_16x16x32_bf16 v[106:109], v[160:163], v[204:207], v[106:109]
	v_mfma_f32_16x16x32_bf16 v[102:105], v[134:137], v[212:215], v[102:105]
	v_mfma_f32_16x16x32_bf16 v[98:101], v[160:163], v[212:215], v[98:101]
	v_mfma_f32_16x16x32_bf16 v[70:73], v[164:167], v[184:187], v[70:73]
	v_mfma_f32_16x16x32_bf16 v[66:69], v[172:175], v[184:187], v[66:69]
	v_mfma_f32_16x16x32_bf16 v[58:61], v[164:167], v[192:195], v[58:61]
	v_mfma_f32_16x16x32_bf16 v[50:53], v[172:175], v[192:195], v[50:53]
	v_mfma_f32_16x16x32_bf16 v[46:49], v[164:167], v[200:203], v[46:49]
	v_mfma_f32_16x16x32_bf16 v[42:45], v[172:175], v[200:203], v[42:45]
	v_mfma_f32_16x16x32_bf16 v[38:41], v[164:167], v[208:211], v[38:41]
	v_mfma_f32_16x16x32_bf16 v[34:37], v[172:175], v[208:211], v[34:37]
	v_mfma_f32_16x16x32_bf16 v[70:73], v[168:171], v[188:191], v[70:73]
	v_mfma_f32_16x16x32_bf16 v[66:69], v[180:183], v[188:191], v[66:69]
	v_mfma_f32_16x16x32_bf16 v[58:61], v[168:171], v[196:199], v[58:61]
	v_mfma_f32_16x16x32_bf16 v[50:53], v[180:183], v[196:199], v[50:53]
	v_mfma_f32_16x16x32_bf16 v[46:49], v[168:171], v[204:207], v[46:49]
	v_mfma_f32_16x16x32_bf16 v[42:45], v[180:183], v[204:207], v[42:45]
	v_mfma_f32_16x16x32_bf16 v[38:41], v[168:171], v[212:215], v[38:41]
	v_mfma_f32_16x16x32_bf16 v[34:37], v[180:183], v[212:215], v[34:37]
	s_barrier
	s_setprio 0
	ds_read_b128 v[184:187], v153 offset:16384
	ds_read_b128 v[188:191], v153 offset:17408
	ds_read_b128 v[192:195], v153 offset:18432
	ds_read_b128 v[196:199], v153 offset:19456
	ds_read_b128 v[200:203], v153 offset:20480
	ds_read_b128 v[204:207], v153 offset:21504
	ds_read_b128 v[208:211], v153 offset:22528
	ds_read_b128 v[212:215], v153 offset:23552
	s_mov_b32 m0, s29
	s_nop 0
	global_load_lds_dwordx4 v145, s[46:47]
	s_nop 0
	s_mov_b32 m0, s57
	s_nop 0
	global_load_lds_dwordx4 v147, s[46:47]
	s_mov_b32 m0, s58
	s_nop 0
	global_load_lds_dwordx4 v145, s[48:49]
	s_nop 0
	s_mov_b32 m0, s59
	s_nop 0
	global_load_lds_dwordx4 v147, s[48:49]
	s_nop 0
	s_mov_b32 m0, s56
	s_nop 0
	global_load_lds_dwordx4 v144, s[44:45]
	s_nop 0
	s_mov_b32 m0, s61
	s_nop 0
	global_load_lds_dwordx4 v146, s[44:45]
	s_waitcnt vmcnt(8)
	s_waitcnt lgkmcnt(0)
	s_setprio 1
	s_barrier
; #define PG8_STAGE(bufoff, gbase, voff) do { _Pragma("unroll") for (int _i = 0; _i < 2; ++_i) { unsigned keep_; \
;         asm volatile("s_mov_b32 %0, m0\n\ts_mov_b32 m0, %3\n\ts_nop 0\n\tglobal_load_lds_dwordx4 %1, %2\n\ts_mov_b32 m0, %0" \
;             : "=&s"(keep_) : "v"((voff)[_i]), "s"((const void*)(gbase)), "s"(ldsb0 + (unsigned)(bufoff) + (unsigned)(_i * 8192)) : "memory"); } } while (0)
; #define PG8_LDA(dst, b, h) do { _Pragma("unroll") for (int m = 0; m < 4; ++m) _Pragma("unroll") for (int k = 0; k < 2; ++k) dst[m][k] = *(const LAS bf16x8*)(lds + PG8_SA(b, h) + aoff + m * 2048 + k * 1024); } while (0)
; #define PG8_LDB(dst, b, h) do { _Pragma("unroll") for (int n = 0; n < 2; ++n) _Pragma("unroll") for (int k = 0; k < 2; ++k) dst[n][k] = *(const LAS bf16x8*)(lds + PG8_SB(b, h) + boff + n * 2048 + k * 1024); } while (0)
; #define PG8_WAIT_V(n) asm volatile("s_waitcnt vmcnt(" #n ")" ::: "memory")
; #define PG8_WAIT_L(n) asm volatile("s_waitcnt lgkmcnt(" #n ")" ::: "memory")
; #define PG8_BAR __builtin_amdgcn_s_barrier()
; #define PG8_SCHED __builtin_amdgcn_sched_barrier(0)
; template <class Epi, class Sched, bool ALIGN_EPI>
; __device__ __forceinline__ void gemm_phase(LAS unsigned char* lds, const Gemm g, const Sched& S, const Epi& E) {
;     ...
;             PG8_LDB(B0, 0, 0); PG8_LDB(B1, 0, 1); PG8_SCHED; PG8_LDA(At, 0, 0); PG8_STAGE(PG8_SA(1, 1), a1 + hstepA, voffA);
;             PG8_WAIT_V(8); PG8_WAIT_L(0); PG8_BAR; PG8_MMA(0, 0, At, B0); PG8_MMA(0, 1, At, B1); PG8_BAR; PG8_SCHED;
;             PG8_LDA(At, 0, 1); PG8_STAGE(PG8_SB(0, 0), b2, voffB); PG8_STAGE(PG8_SB(0, 1), b2 + hstepB, voffB); PG8_STAGE(PG8_SA(0, 0), a2, voffA);
;             PG8_WAIT_V(8); PG8_WAIT_L(0); PG8_BAR; PG8_MMA(1, 0, At, B0); PG8_MMA(1, 1, At, B1); PG8_BAR; PG8_SCHED;
;             PG8_LDB(B0, 1, 0); PG8_LDB(B1, 1, 1); PG8_SCHED; PG8_LDA(At, 1, 0); PG8_STAGE(PG8_SA(0, 1), a2 + hstepA, voffA);
;             PG8_WAIT_V(8); PG8_WAIT_L(0); PG8_BAR; PG8_MMA(0, 0, At, B0); PG8_MMA(0, 1, At, B1); PG8_BAR; PG8_SCHED;
;             PG8_LDA(At, 1, 1); PG8_STAGE(PG8_SB(1, 0), b3, voffB); PG8_STAGE(PG8_SB(1, 1), b3 + hstepB, voffB); PG8_STAGE(PG8_SA(1, 0), a3, voffA);
;             PG8_WAIT_V(8); PG8_WAIT_L(0); PG8_BAR; PG8_MMA(1, 0, At, B0); PG8_MMA(1, 1, At, B1); PG8_BAR; PG8_SCHED;
	v_mfma_f32_16x16x32_bf16 v[94:97], v[130:133], v[184:187], v[94:97]
	v_mfma_f32_16x16x32_bf16 v[90:93], v[156:159], v[184:187], v[90:93]
	v_mfma_f32_16x16x32_bf16 v[86:89], v[130:133], v[192:195], v[86:89]
	v_mfma_f32_16x16x32_bf16 v[82:85], v[156:159], v[192:195], v[82:85]
	v_mfma_f32_16x16x32_bf16 v[78:81], v[130:133], v[200:203], v[78:81]
	v_mfma_f32_16x16x32_bf16 v[74:77], v[156:159], v[200:203], v[74:77]
	v_mfma_f32_16x16x32_bf16 v[62:65], v[130:133], v[208:211], v[62:65]
	v_mfma_f32_16x16x32_bf16 v[54:57], v[156:159], v[208:211], v[54:57]
	v_mfma_f32_16x16x32_bf16 v[94:97], v[134:137], v[188:191], v[94:97]
	v_mfma_f32_16x16x32_bf16 v[90:93], v[160:163], v[188:191], v[90:93]
	v_mfma_f32_16x16x32_bf16 v[86:89], v[134:137], v[196:199], v[86:89]
	v_mfma_f32_16x16x32_bf16 v[82:85], v[160:163], v[196:199], v[82:85]
	v_mfma_f32_16x16x32_bf16 v[78:81], v[134:137], v[204:207], v[78:81]
	v_mfma_f32_16x16x32_bf16 v[74:77], v[160:163], v[204:207], v[74:77]
	v_mfma_f32_16x16x32_bf16 v[62:65], v[134:137], v[212:215], v[62:65]
	v_mfma_f32_16x16x32_bf16 v[54:57], v[160:163], v[212:215], v[54:57]
	v_mfma_f32_16x16x32_bf16 v[30:33], v[164:167], v[184:187], v[30:33]
	v_mfma_f32_16x16x32_bf16 v[26:29], v[172:175], v[184:187], v[26:29]
	v_mfma_f32_16x16x32_bf16 v[22:25], v[164:167], v[192:195], v[22:25]
	v_mfma_f32_16x16x32_bf16 v[18:21], v[172:175], v[192:195], v[18:21]
	v_mfma_f32_16x16x32_bf16 v[14:17], v[164:167], v[200:203], v[14:17]
	v_mfma_f32_16x16x32_bf16 v[10:13], v[172:175], v[200:203], v[10:13]
	v_mfma_f32_16x16x32_bf16 v[6:9], v[164:167], v[208:211], v[6:9]
	v_mfma_f32_16x16x32_bf16 v[2:5], v[172:175], v[208:211], v[2:5]
	v_mfma_f32_16x16x32_bf16 v[30:33], v[168:171], v[188:191], v[30:33]
	v_mfma_f32_16x16x32_bf16 v[26:29], v[180:183], v[188:191], v[26:29]
	v_mfma_f32_16x16x32_bf16 v[22:25], v[168:171], v[196:199], v[22:25]
	v_mfma_f32_16x16x32_bf16 v[18:21], v[180:183], v[196:199], v[18:21]
	v_mfma_f32_16x16x32_bf16 v[14:17], v[168:171], v[204:207], v[14:17]
	v_mfma_f32_16x16x32_bf16 v[10:13], v[180:183], v[204:207], v[10:13]
	v_mfma_f32_16x16x32_bf16 v[6:9], v[168:171], v[212:215], v[6:9]
	v_mfma_f32_16x16x32_bf16 v[2:5], v[180:183], v[212:215], v[2:5]
	s_barrier
	s_setprio 0
	ds_read_b128 v[130:133], v154
	ds_read_b128 v[134:137], v154 offset:1024
	ds_read_b128 v[156:159], v154 offset:2048
	ds_read_b128 v[160:163], v154 offset:3072
	ds_read_b128 v[164:167], v155
	ds_read_b128 v[168:171], v155 offset:1024
	ds_read_b128 v[172:175], v155 offset:2048
	ds_read_b128 v[180:183], v155 offset:3072
	ds_read_b128 v[184:187], v153 offset:32768
	ds_read_b128 v[188:191], v153 offset:33792
	ds_read_b128 v[192:195], v153 offset:34816
	ds_read_b128 v[196:199], v153 offset:35840
	ds_read_b128 v[200:203], v153 offset:36864
	ds_read_b128 v[204:207], v153 offset:37888
	ds_read_b128 v[208:211], v153 offset:38912
	ds_read_b128 v[212:215], v153 offset:39936
	s_mov_b32 m0, s62
	s_nop 0
	global_load_lds_dwordx4 v144, s[42:43]
	s_nop 0
	s_mov_b32 m0, s63
	s_nop 0
	global_load_lds_dwordx4 v146, s[42:43]
	s_waitcnt vmcnt(8)
	s_waitcnt lgkmcnt(0)
	s_setprio 1
	s_barrier
	v_mfma_f32_16x16x32_bf16 v[126:129], v[130:133], v[184:187], v[126:129]
	v_mfma_f32_16x16x32_bf16 v[122:125], v[156:159], v[184:187], v[122:125]
	v_mfma_f32_16x16x32_bf16 v[118:121], v[130:133], v[192:195], v[118:121]
	v_mfma_f32_16x16x32_bf16 v[114:117], v[156:159], v[192:195], v[114:117]
	v_mfma_f32_16x16x32_bf16 v[110:113], v[130:133], v[200:203], v[110:113]
	v_mfma_f32_16x16x32_bf16 v[106:109], v[156:159], v[200:203], v[106:109]
	v_mfma_f32_16x16x32_bf16 v[102:105], v[130:133], v[208:211], v[102:105]
	v_mfma_f32_16x16x32_bf16 v[98:101], v[156:159], v[208:211], v[98:101]
	v_mfma_f32_16x16x32_bf16 v[126:129], v[134:137], v[188:191], v[126:129]
	v_mfma_f32_16x16x32_bf16 v[122:125], v[160:163], v[188:191], v[122:125]
	v_mfma_f32_16x16x32_bf16 v[118:121], v[134:137], v[196:199], v[118:121]
	v_mfma_f32_16x16x32_bf16 v[114:117], v[160:163], v[196:199], v[114:117]
	v_mfma_f32_16x16x32_bf16 v[110:113], v[134:137], v[204:207], v[110:113]
	v_mfma_f32_16x16x32_bf16 v[106:109], v[160:163], v[204:207], v[106:109]
	v_mfma_f32_16x16x32_bf16 v[102:105], v[134:137], v[212:215], v[102:105]
	v_mfma_f32_16x16x32_bf16 v[98:101], v[160:163], v[212:215], v[98:101]
	v_mfma_f32_16x16x32_bf16 v[70:73], v[164:167], v[184:187], v[70:73]
	v_mfma_f32_16x16x32_bf16 v[66:69], v[172:175], v[184:187], v[66:69]
	v_mfma_f32_16x16x32_bf16 v[58:61], v[164:167], v[192:195], v[58:61]
	v_mfma_f32_16x16x32_bf16 v[50:53], v[172:175], v[192:195], v[50:53]
	v_mfma_f32_16x16x32_bf16 v[46:49], v[164:167], v[200:203], v[46:49]
	v_mfma_f32_16x16x32_bf16 v[42:45], v[172:175], v[200:203], v[42:45]
	v_mfma_f32_16x16x32_bf16 v[38:41], v[164:167], v[208:211], v[38:41]
	v_mfma_f32_16x16x32_bf16 v[34:37], v[172:175], v[208:211], v[34:37]
	v_mfma_f32_16x16x32_bf16 v[70:73], v[168:171], v[188:191], v[70:73]
	v_mfma_f32_16x16x32_bf16 v[66:69], v[180:183], v[188:191], v[66:69]
	v_mfma_f32_16x16x32_bf16 v[58:61], v[168:171], v[196:199], v[58:61]
	v_mfma_f32_16x16x32_bf16 v[50:53], v[180:183], v[196:199], v[50:53]
	v_mfma_f32_16x16x32_bf16 v[46:49], v[168:171], v[204:207], v[46:49]
	v_mfma_f32_16x16x32_bf16 v[42:45], v[180:183], v[204:207], v[42:45]
	v_mfma_f32_16x16x32_bf16 v[38:41], v[168:171], v[212:215], v[38:41]
	v_mfma_f32_16x16x32_bf16 v[34:37], v[180:183], v[212:215], v[34:37]
	s_barrier
; #define PG8_STAGE(bufoff, gbase, voff) do { _Pragma("unroll") for (int _i = 0; _i < 2; ++_i) { unsigned keep_; \
;         asm volatile("s_mov_b32 %0, m0\n\ts_mov_b32 m0, %3\n\ts_nop 0\n\tglobal_load_lds_dwordx4 %1, %2\n\ts_mov_b32 m0, %0" \
;             : "=&s"(keep_) : "v"((voff)[_i]), "s"((const void*)(gbase)), "s"(ldsb0 + (unsigned)(bufoff) + (unsigned)(_i * 8192)) : "memory"); } } while (0)
; #define PG8_LDA(dst, b, h) do { _Pragma("unroll") for (int m = 0; m < 4; ++m) _Pragma("unroll") for (int k = 0; k < 2; ++k) dst[m][k] = *(const LAS bf16x8*)(lds + PG8_SA(b, h) + aoff + m * 2048 + k * 1024); } while (0)
; #define PG8_MMA(ai, bj, At, Bt) do { __builtin_amdgcn_s_setprio(1); _Pragma("unroll") for (int m = 0; m < 4; ++m) _Pragma("unroll") for (int n = 0; n < 2; ++n) _Pragma("unroll") for (int k = 0; k < 2; ++k) \
;         acc[ai][bj][m][n] = __builtin_amdgcn_mfma_f32_16x16x32_bf16(Bt[n][k], At[m][k], acc[ai][bj][m][n], 0, 0, 0); __builtin_amdgcn_s_setprio(0); } while (0)
; #define PG8_WAIT_V(n) asm volatile("s_waitcnt vmcnt(" #n ")" ::: "memory")
; #define PG8_WAIT_L(n) asm volatile("s_waitcnt lgkmcnt(" #n ")" ::: "memory")
; #define PG8_BAR __builtin_amdgcn_s_barrier()
; #define PG8_SCHED __builtin_amdgcn_sched_barrier(0)
; template <class Epi, class Sched, bool ALIGN_EPI>
; __device__ __forceinline__ void gemm_phase(LAS unsigned char* lds, const Gemm g, const Sched& S, const Epi& E) {
;     ...
;             PG8_LDA(At, 1, 1); PG8_STAGE(PG8_SB(1, 0), b3, voffB); PG8_STAGE(PG8_SB(1, 1), b3 + hstepB, voffB); PG8_STAGE(PG8_SA(1, 0), a3, voffA);
;             PG8_WAIT_V(8); PG8_WAIT_L(0); PG8_BAR; PG8_MMA(1, 0, At, B0); PG8_MMA(1, 1, At, B1); PG8_BAR; PG8_SCHED;
	s_setprio 0
	ds_read_b128 v[184:187], v153 offset:49152
	ds_read_b128 v[188:191], v153 offset:50176
	ds_read_b128 v[192:195], v153 offset:51200
	ds_read_b128 v[196:199], v153 offset:52224
	ds_read_b128 v[200:203], v153 offset:53248
	ds_read_b128 v[204:207], v153 offset:54272
	ds_read_b128 v[208:211], v153 offset:55296
	ds_read_b128 v[212:215], v153 offset:56320
	s_mov_b32 m0, s64
	s_nop 0
	global_load_lds_dwordx4 v145, s[38:39]
	s_nop 0
	s_mov_b32 m0, s65
	s_nop 0
	global_load_lds_dwordx4 v147, s[38:39]
	s_mov_b32 m0, s68
	s_nop 0
	global_load_lds_dwordx4 v145, s[50:51]
	s_nop 0
	s_mov_b32 m0, s69
	s_nop 0
	global_load_lds_dwordx4 v147, s[50:51]
	s_nop 0
	s_mov_b32 m0, s66
	s_nop 0
	global_load_lds_dwordx4 v144, s[40:41]
	s_nop 0
	s_mov_b32 m0, s67
	s_nop 0
	global_load_lds_dwordx4 v146, s[40:41]
	s_waitcnt vmcnt(8)
	s_waitcnt lgkmcnt(0)
	s_setprio 1
	s_barrier
	v_mfma_f32_16x16x32_bf16 v[94:97], v[130:133], v[184:187], v[94:97]
	v_mfma_f32_16x16x32_bf16 v[90:93], v[156:159], v[184:187], v[90:93]
	v_mfma_f32_16x16x32_bf16 v[86:89], v[130:133], v[192:195], v[86:89]
	v_mfma_f32_16x16x32_bf16 v[82:85], v[156:159], v[192:195], v[82:85]
	v_mfma_f32_16x16x32_bf16 v[78:81], v[130:133], v[200:203], v[78:81]
	v_mfma_f32_16x16x32_bf16 v[74:77], v[156:159], v[200:203], v[74:77]
	v_mfma_f32_16x16x32_bf16 v[62:65], v[130:133], v[208:211], v[62:65]
	v_mfma_f32_16x16x32_bf16 v[54:57], v[156:159], v[208:211], v[54:57]
	v_mfma_f32_16x16x32_bf16 v[94:97], v[134:137], v[188:191], v[94:97]
	v_mfma_f32_16x16x32_bf16 v[90:93], v[160:163], v[188:191], v[90:93]
	v_mfma_f32_16x16x32_bf16 v[86:89], v[134:137], v[196:199], v[86:89]
	v_mfma_f32_16x16x32_bf16 v[82:85], v[160:163], v[196:199], v[82:85]
	v_mfma_f32_16x16x32_bf16 v[78:81], v[134:137], v[204:207], v[78:81]
	v_mfma_f32_16x16x32_bf16 v[74:77], v[160:163], v[204:207], v[74:77]
	v_mfma_f32_16x16x32_bf16 v[62:65], v[134:137], v[212:215], v[62:65]
	v_mfma_f32_16x16x32_bf16 v[54:57], v[160:163], v[212:215], v[54:57]
	v_mfma_f32_16x16x32_bf16 v[30:33], v[164:167], v[184:187], v[30:33]
	v_mfma_f32_16x16x32_bf16 v[26:29], v[172:175], v[184:187], v[26:29]
	v_mfma_f32_16x16x32_bf16 v[22:25], v[164:167], v[192:195], v[22:25]
	v_mfma_f32_16x16x32_bf16 v[18:21], v[172:175], v[192:195], v[18:21]
	v_mfma_f32_16x16x32_bf16 v[14:17], v[164:167], v[200:203], v[14:17]
	v_mfma_f32_16x16x32_bf16 v[10:13], v[172:175], v[200:203], v[10:13]
	v_mfma_f32_16x16x32_bf16 v[6:9], v[164:167], v[208:211], v[6:9]
	v_mfma_f32_16x16x32_bf16 v[2:5], v[172:175], v[208:211], v[2:5]
	v_mfma_f32_16x16x32_bf16 v[30:33], v[168:171], v[188:191], v[30:33]
	v_mfma_f32_16x16x32_bf16 v[26:29], v[180:183], v[188:191], v[26:29]
	v_mfma_f32_16x16x32_bf16 v[22:25], v[168:171], v[196:199], v[22:25]
	v_mfma_f32_16x16x32_bf16 v[18:21], v[180:183], v[196:199], v[18:21]
	v_mfma_f32_16x16x32_bf16 v[14:17], v[168:171], v[204:207], v[14:17]
	v_mfma_f32_16x16x32_bf16 v[10:13], v[180:183], v[204:207], v[10:13]
	v_mfma_f32_16x16x32_bf16 v[6:9], v[168:171], v[212:215], v[6:9]
	v_mfma_f32_16x16x32_bf16 v[2:5], v[180:183], v[212:215], v[2:5]
	s_barrier
	s_setprio 0
	s_andn2_b64 vcc, exec, s[36:37]
	s_mov_b64 s[38:39], -1
	s_mov_b64 s[36:37], 0
	s_mov_b64 s[40:41], 0x100
	s_cbranch_vccz .LBB0_805
	s_and_b64 vcc, exec, s[12:13]
	s_cbranch_vccz .LBB0_808
	s_barrier

; #define PG8_STAGE(bufoff, gbase, voff) do { _Pragma("unroll") for (int _i = 0; _i < 2; ++_i) { unsigned keep_; \
;         asm volatile("s_mov_b32 %0, m0\n\ts_mov_b32 m0, %3\n\ts_nop 0\n\tglobal_load_lds_dwordx4 %1, %2\n\ts_mov_b32 m0, %0" \
;             : "=&s"(keep_) : "v"((voff)[_i]), "s"((const void*)(gbase)), "s"(ldsb0 + (unsigned)(bufoff) + (unsigned)(_i * 8192)) : "memory"); } } while (0)
; #define PG8_LDA(dst, b, h) do { _Pragma("unroll") for (int m = 0; m < 4; ++m) _Pragma("unroll") for (int k = 0; k < 2; ++k) dst[m][k] = *(const LAS bf16x8*)(lds + PG8_SA(b, h) + aoff + m * 2048 + k * 1024); } while (0)
; #define PG8_LDB(dst, b, h) do { _Pragma("unroll") for (int n = 0; n < 2; ++n) _Pragma("unroll") for (int k = 0; k < 2; ++k) dst[n][k] = *(const LAS bf16x8*)(lds + PG8_SB(b, h) + boff + n * 2048 + k * 1024); } while (0)
; #define PG8_MMA(ai, bj, At, Bt) do { __builtin_amdgcn_s_setprio(1); _Pragma("unroll") for (int m = 0; m < 4; ++m) _Pragma("unroll") for (int n = 0; n < 2; ++n) _Pragma("unroll") for (int k = 0; k < 2; ++k) \
;         acc[ai][bj][m][n] = __builtin_amdgcn_mfma_f32_16x16x32_bf16(Bt[n][k], At[m][k], acc[ai][bj][m][n], 0, 0, 0); __builtin_amdgcn_s_setprio(0); } while (0)
; #define PG8_WAIT_V(n) asm volatile("s_waitcnt vmcnt(" #n ")" ::: "memory")
; #define PG8_WAIT_L(n) asm volatile("s_waitcnt lgkmcnt(" #n ")" ::: "memory")
; template <class Epi, class Sched, bool ALIGN_EPI>
; __device__ __forceinline__ void gemm_phase(LAS unsigned char* lds, const Gemm g, const Sched& S, const Epi& E) {
;     ...
;             const bool last = (t == nt - 2);
;             const char* a1 = cA + (size_t)(t + 1) * kstep;
;             const char* a2 = last ? nA : cA + (size_t)(t + 2) * kstep; const char* b2 = last ? nB : cB + (size_t)(t + 2) * kstep;
;             const char* a3 = a2 + kstep; const char* b3 = b2 + kstep;
;             PG8_LDB(B0, 0, 0); PG8_LDB(B1, 0, 1); PG8_SCHED; PG8_LDA(At, 0, 0); PG8_STAGE(PG8_SA(1, 1), a1 + hstepA, voffA);
;             PG8_WAIT_V(8); PG8_WAIT_L(0); PG8_BAR; PG8_MMA(0, 0, At, B0); PG8_MMA(0, 1, At, B1); PG8_BAR; PG8_SCHED;
;             PG8_LDA(At, 0, 1); PG8_STAGE(PG8_SB(0, 0), b2, voffB); PG8_STAGE(PG8_SB(0, 1), b2 + hstepB, voffB); PG8_STAGE(PG8_SA(0, 0), a2, voffA);
;             PG8_WAIT_V(8); PG8_WAIT_L(0); PG8_BAR; PG8_MMA(1, 0, At, B0); PG8_MMA(1, 1, At, B1); PG8_BAR; PG8_SCHED;
.LBB0_1137:
	ds_read_b128 v[110:113], v206
	ds_read_b128 v[126:129], v206 offset:1024
	ds_read_b128 v[130:133], v206 offset:2048
	ds_read_b128 v[142:145], v206 offset:3072
	ds_read_b128 v[146:149], v207
	ds_read_b128 v[150:153], v207 offset:1024
	ds_read_b128 v[154:157], v207 offset:2048
	ds_read_b128 v[158:161], v207 offset:3072
	s_cmp_eq_u32 s63, 28
	s_cselect_b32 s40, s5, s19
	s_cselect_b32 s41, s3, s27
	s_cselect_b32 s38, s7, s61
	s_cselect_b32 s39, s6, s62
	s_add_u32 s36, s40, 0x80
	s_addc_u32 s37, s41, 0
	ds_read_b128 v[162:165], v208
	ds_read_b128 v[166:169], v208 offset:1024
	ds_read_b128 v[170:173], v208 offset:2048
	ds_read_b128 v[174:177], v208 offset:3072
	ds_read_b128 v[188:191], v208 offset:4096
	ds_read_b128 v[192:195], v208 offset:5120
	ds_read_b128 v[196:199], v208 offset:6144
	ds_read_b128 v[212:215], v208 offset:7168
	s_mov_b32 m0, s58
	s_nop 0
	global_load_lds_dwordx4 v179, s[34:35]
	s_nop 0
	s_mov_b32 m0, s59
	s_nop 0
	global_load_lds_dwordx4 v201, s[34:35]
	s_waitcnt vmcnt(8)
	s_waitcnt lgkmcnt(0)
	s_setprio 1
	s_barrier
	v_mfma_f32_16x16x32_bf16 v[138:141], v[110:113], v[162:165], v[138:141]
	v_mfma_f32_16x16x32_bf16 v[134:137], v[130:133], v[162:165], v[134:137]
	v_mfma_f32_16x16x32_bf16 v[114:117], v[110:113], v[170:173], v[114:117]
	v_mfma_f32_16x16x32_bf16 v[106:109], v[130:133], v[170:173], v[106:109]
	v_mfma_f32_16x16x32_bf16 v[94:97], v[110:113], v[188:191], v[94:97]
	v_mfma_f32_16x16x32_bf16 v[90:93], v[130:133], v[188:191], v[90:93]
	v_mfma_f32_16x16x32_bf16 v[78:81], v[110:113], v[196:199], v[78:81]
	v_mfma_f32_16x16x32_bf16 v[74:77], v[130:133], v[196:199], v[74:77]
	v_mfma_f32_16x16x32_bf16 v[138:141], v[126:129], v[166:169], v[138:141]
	v_mfma_f32_16x16x32_bf16 v[134:137], v[142:145], v[166:169], v[134:137]
	v_mfma_f32_16x16x32_bf16 v[114:117], v[126:129], v[174:177], v[114:117]
	v_mfma_f32_16x16x32_bf16 v[106:109], v[142:145], v[174:177], v[106:109]
	v_mfma_f32_16x16x32_bf16 v[94:97], v[126:129], v[192:195], v[94:97]
	v_mfma_f32_16x16x32_bf16 v[90:93], v[142:145], v[192:195], v[90:93]
	v_mfma_f32_16x16x32_bf16 v[78:81], v[126:129], v[212:215], v[78:81]
	v_mfma_f32_16x16x32_bf16 v[74:77], v[142:145], v[212:215], v[74:77]
	v_mfma_f32_16x16x32_bf16 v[122:125], v[146:149], v[162:165], v[122:125]
	v_mfma_f32_16x16x32_bf16 v[118:121], v[154:157], v[162:165], v[118:121]
	v_mfma_f32_16x16x32_bf16 v[102:105], v[146:149], v[170:173], v[102:105]
	v_mfma_f32_16x16x32_bf16 v[98:101], v[154:157], v[170:173], v[98:101]
	v_mfma_f32_16x16x32_bf16 v[86:89], v[146:149], v[188:191], v[86:89]
	v_mfma_f32_16x16x32_bf16 v[82:85], v[154:157], v[188:191], v[82:85]
	v_mfma_f32_16x16x32_bf16 v[70:73], v[146:149], v[196:199], v[70:73]
	v_mfma_f32_16x16x32_bf16 v[66:69], v[154:157], v[196:199], v[66:69]
	v_mfma_f32_16x16x32_bf16 v[122:125], v[150:153], v[166:169], v[122:125]
	v_mfma_f32_16x16x32_bf16 v[118:121], v[158:161], v[166:169], v[118:121]
	v_mfma_f32_16x16x32_bf16 v[102:105], v[150:153], v[174:177], v[102:105]
	v_mfma_f32_16x16x32_bf16 v[98:101], v[158:161], v[174:177], v[98:101]
	v_mfma_f32_16x16x32_bf16 v[86:89], v[150:153], v[192:195], v[86:89]
	v_mfma_f32_16x16x32_bf16 v[82:85], v[158:161], v[192:195], v[82:85]
	v_mfma_f32_16x16x32_bf16 v[70:73], v[150:153], v[212:215], v[70:73]
	v_mfma_f32_16x16x32_bf16 v[66:69], v[158:161], v[212:215], v[66:69]
	s_barrier
	s_setprio 0
	ds_read_b128 v[162:165], v208 offset:16384
	ds_read_b128 v[166:169], v208 offset:17408
	ds_read_b128 v[170:173], v208 offset:18432
	ds_read_b128 v[174:177], v208 offset:19456
	ds_read_b128 v[188:191], v208 offset:20480
	ds_read_b128 v[192:195], v208 offset:21504
	ds_read_b128 v[196:199], v208 offset:22528
	ds_read_b128 v[212:215], v208 offset:23552
	s_mov_b32 m0, s45
	s_nop 0
	global_load_lds_dwordx4 v200, s[38:39]
	s_nop 0
	s_mov_b32 m0, s46
	s_nop 0
	global_load_lds_dwordx4 v203, s[38:39]
	s_add_u32 s64, s38, 0x80000
	s_addc_u32 s65, s39, 0
	s_mov_b32 m0, s47
	s_nop 0
	global_load_lds_dwordx4 v200, s[64:65]
	s_nop 0
	s_mov_b32 m0, s48
	s_nop 0
	global_load_lds_dwordx4 v203, s[64:65]
	s_mov_b32 m0, s44
	s_nop 0
	global_load_lds_dwordx4 v179, s[40:41]
	s_nop 0
	s_mov_b32 m0, s49
	s_nop 0
	global_load_lds_dwordx4 v201, s[40:41]
	s_waitcnt vmcnt(8)
	s_waitcnt lgkmcnt(0)
	s_setprio 1
	s_barrier
	v_mfma_f32_16x16x32_bf16 v[62:65], v[110:113], v[162:165], v[62:65]
	v_mfma_f32_16x16x32_bf16 v[58:61], v[130:133], v[162:165], v[58:61]
	v_mfma_f32_16x16x32_bf16 v[46:49], v[110:113], v[170:173], v[46:49]
	v_mfma_f32_16x16x32_bf16 v[42:45], v[130:133], v[170:173], v[42:45]
	v_mfma_f32_16x16x32_bf16 v[30:33], v[110:113], v[188:191], v[30:33]
	v_mfma_f32_16x16x32_bf16 v[26:29], v[130:133], v[188:191], v[26:29]
	v_mfma_f32_16x16x32_bf16 v[14:17], v[110:113], v[196:199], v[14:17]
	v_mfma_f32_16x16x32_bf16 v[10:13], v[130:133], v[196:199], v[10:13]
	v_mfma_f32_16x16x32_bf16 v[62:65], v[126:129], v[166:169], v[62:65]
	v_mfma_f32_16x16x32_bf16 v[58:61], v[142:145], v[166:169], v[58:61]
	v_mfma_f32_16x16x32_bf16 v[46:49], v[126:129], v[174:177], v[46:49]
	v_mfma_f32_16x16x32_bf16 v[42:45], v[142:145], v[174:177], v[42:45]
	v_mfma_f32_16x16x32_bf16 v[30:33], v[126:129], v[192:195], v[30:33]
	v_mfma_f32_16x16x32_bf16 v[26:29], v[142:145], v[192:195], v[26:29]
	v_mfma_f32_16x16x32_bf16 v[14:17], v[126:129], v[212:215], v[14:17]
	v_mfma_f32_16x16x32_bf16 v[10:13], v[142:145], v[212:215], v[10:13]
	v_mfma_f32_16x16x32_bf16 v[54:57], v[146:149], v[162:165], v[54:57]
	v_mfma_f32_16x16x32_bf16 v[50:53], v[154:157], v[162:165], v[50:53]
	v_mfma_f32_16x16x32_bf16 v[38:41], v[146:149], v[170:173], v[38:41]
	v_mfma_f32_16x16x32_bf16 v[34:37], v[154:157], v[170:173], v[34:37]
	v_mfma_f32_16x16x32_bf16 v[22:25], v[146:149], v[188:191], v[22:25]
	v_mfma_f32_16x16x32_bf16 v[18:21], v[154:157], v[188:191], v[18:21]
	v_mfma_f32_16x16x32_bf16 v[6:9], v[146:149], v[196:199], v[6:9]
	v_mfma_f32_16x16x32_bf16 v[2:5], v[154:157], v[196:199], v[2:5]
	v_mfma_f32_16x16x32_bf16 v[54:57], v[150:153], v[166:169], v[54:57]
	v_mfma_f32_16x16x32_bf16 v[50:53], v[158:161], v[166:169], v[50:53]
	v_mfma_f32_16x16x32_bf16 v[38:41], v[150:153], v[174:177], v[38:41]
	v_mfma_f32_16x16x32_bf16 v[34:37], v[158:161], v[174:177], v[34:37]
	v_mfma_f32_16x16x32_bf16 v[22:25], v[150:153], v[192:195], v[22:25]
	v_mfma_f32_16x16x32_bf16 v[18:21], v[158:161], v[192:195], v[18:21]
	v_mfma_f32_16x16x32_bf16 v[6:9], v[150:153], v[212:215], v[6:9]
	v_mfma_f32_16x16x32_bf16 v[2:5], v[158:161], v[212:215], v[2:5]
	s_barrier
; #define PG8_STAGE(bufoff, gbase, voff) do { _Pragma("unroll") for (int _i = 0; _i < 2; ++_i) { unsigned keep_; \
;         asm volatile("s_mov_b32 %0, m0\n\ts_mov_b32 m0, %3\n\ts_nop 0\n\tglobal_load_lds_dwordx4 %1, %2\n\ts_mov_b32 m0, %0" \
;             : "=&s"(keep_) : "v"((voff)[_i]), "s"((const void*)(gbase)), "s"(ldsb0 + (unsigned)(bufoff) + (unsigned)(_i * 8192)) : "memory"); } } while (0)
; #define PG8_LDA(dst, b, h) do { _Pragma("unroll") for (int m = 0; m < 4; ++m) _Pragma("unroll") for (int k = 0; k < 2; ++k) dst[m][k] = *(const LAS bf16x8*)(lds + PG8_SA(b, h) + aoff + m * 2048 + k * 1024); } while (0)
; #define PG8_LDB(dst, b, h) do { _Pragma("unroll") for (int n = 0; n < 2; ++n) _Pragma("unroll") for (int k = 0; k < 2; ++k) dst[n][k] = *(const LAS bf16x8*)(lds + PG8_SB(b, h) + boff + n * 2048 + k * 1024); } while (0)
; #define PG8_MMA(ai, bj, At, Bt) do { __builtin_amdgcn_s_setprio(1); _Pragma("unroll") for (int m = 0; m < 4; ++m) _Pragma("unroll") for (int n = 0; n < 2; ++n) _Pragma("unroll") for (int k = 0; k < 2; ++k) \
;         acc[ai][bj][m][n] = __builtin_amdgcn_mfma_f32_16x16x32_bf16(Bt[n][k], At[m][k], acc[ai][bj][m][n], 0, 0, 0); __builtin_amdgcn_s_setprio(0); } while (0)
; #define PG8_WAIT_V(n) asm volatile("s_waitcnt vmcnt(" #n ")" ::: "memory")
; #define PG8_WAIT_L(n) asm volatile("s_waitcnt lgkmcnt(" #n ")" ::: "memory")
; #define PG8_BAR __builtin_amdgcn_s_barrier()
; #define PG8_SCHED __builtin_amdgcn_sched_barrier(0)
; template <class Epi, class Sched, bool ALIGN_EPI>
; __device__ __forceinline__ void gemm_phase(LAS unsigned char* lds, const Gemm g, const Sched& S, const Epi& E) {
;     ...
;             PG8_LDB(B0, 1, 0); PG8_LDB(B1, 1, 1); PG8_SCHED; PG8_LDA(At, 1, 0); PG8_STAGE(PG8_SA(0, 1), a2 + hstepA, voffA);
;             PG8_WAIT_V(8); PG8_WAIT_L(0); PG8_BAR; PG8_MMA(0, 0, At, B0); PG8_MMA(0, 1, At, B1); PG8_BAR; PG8_SCHED;
;             PG8_LDA(At, 1, 1); PG8_STAGE(PG8_SB(1, 0), b3, voffB); PG8_STAGE(PG8_SB(1, 1), b3 + hstepB, voffB); PG8_STAGE(PG8_SA(1, 0), a3, voffA);
;             PG8_WAIT_V(8); PG8_WAIT_L(0); PG8_BAR; PG8_MMA(1, 0, At, B0); PG8_MMA(1, 1, At, B1); PG8_BAR; PG8_SCHED;
;         }
	s_setprio 0
	ds_read_b128 v[110:113], v209
	ds_read_b128 v[126:129], v209 offset:1024
	ds_read_b128 v[130:133], v209 offset:2048
	ds_read_b128 v[142:145], v209 offset:3072
	ds_read_b128 v[146:149], v210
	ds_read_b128 v[150:153], v210 offset:1024
	ds_read_b128 v[154:157], v210 offset:2048
	ds_read_b128 v[158:161], v210 offset:3072
	ds_read_b128 v[162:165], v208 offset:32768
	ds_read_b128 v[166:169], v208 offset:33792
	ds_read_b128 v[170:173], v208 offset:34816
	ds_read_b128 v[174:177], v208 offset:35840
	ds_read_b128 v[188:191], v208 offset:36864
	ds_read_b128 v[192:195], v208 offset:37888
	ds_read_b128 v[196:199], v208 offset:38912
	ds_read_b128 v[212:215], v208 offset:39936
	s_add_u32 s40, s40, 0x80000
	s_addc_u32 s41, s41, 0
	s_mov_b32 m0, s50
	s_nop 0
	global_load_lds_dwordx4 v179, s[40:41]
	s_nop 0
	s_mov_b32 m0, s51
	s_nop 0
	global_load_lds_dwordx4 v201, s[40:41]
	s_waitcnt vmcnt(8)
	s_waitcnt lgkmcnt(0)
	s_setprio 1
	s_barrier
	v_mfma_f32_16x16x32_bf16 v[138:141], v[110:113], v[162:165], v[138:141]
	v_mfma_f32_16x16x32_bf16 v[134:137], v[130:133], v[162:165], v[134:137]
	v_mfma_f32_16x16x32_bf16 v[114:117], v[110:113], v[170:173], v[114:117]
	v_mfma_f32_16x16x32_bf16 v[106:109], v[130:133], v[170:173], v[106:109]
	v_mfma_f32_16x16x32_bf16 v[94:97], v[110:113], v[188:191], v[94:97]
	v_mfma_f32_16x16x32_bf16 v[90:93], v[130:133], v[188:191], v[90:93]
	v_mfma_f32_16x16x32_bf16 v[78:81], v[110:113], v[196:199], v[78:81]
	v_mfma_f32_16x16x32_bf16 v[74:77], v[130:133], v[196:199], v[74:77]
	v_mfma_f32_16x16x32_bf16 v[138:141], v[126:129], v[166:169], v[138:141]
	v_mfma_f32_16x16x32_bf16 v[134:137], v[142:145], v[166:169], v[134:137]
	v_mfma_f32_16x16x32_bf16 v[114:117], v[126:129], v[174:177], v[114:117]
	v_mfma_f32_16x16x32_bf16 v[106:109], v[142:145], v[174:177], v[106:109]
	v_mfma_f32_16x16x32_bf16 v[94:97], v[126:129], v[192:195], v[94:97]
	v_mfma_f32_16x16x32_bf16 v[90:93], v[142:145], v[192:195], v[90:93]
	v_mfma_f32_16x16x32_bf16 v[78:81], v[126:129], v[212:215], v[78:81]
	v_mfma_f32_16x16x32_bf16 v[74:77], v[142:145], v[212:215], v[74:77]
	v_mfma_f32_16x16x32_bf16 v[122:125], v[146:149], v[162:165], v[122:125]
	v_mfma_f32_16x16x32_bf16 v[118:121], v[154:157], v[162:165], v[118:121]
	v_mfma_f32_16x16x32_bf16 v[102:105], v[146:149], v[170:173], v[102:105]
	v_mfma_f32_16x16x32_bf16 v[98:101], v[154:157], v[170:173], v[98:101]
	v_mfma_f32_16x16x32_bf16 v[86:89], v[146:149], v[188:191], v[86:89]
	v_mfma_f32_16x16x32_bf16 v[82:85], v[154:157], v[188:191], v[82:85]
	v_mfma_f32_16x16x32_bf16 v[70:73], v[146:149], v[196:199], v[70:73]
	v_mfma_f32_16x16x32_bf16 v[66:69], v[154:157], v[196:199], v[66:69]
	v_mfma_f32_16x16x32_bf16 v[122:125], v[150:153], v[166:169], v[122:125]
	v_mfma_f32_16x16x32_bf16 v[118:121], v[158:161], v[166:169], v[118:121]
	v_mfma_f32_16x16x32_bf16 v[102:105], v[150:153], v[174:177], v[102:105]
	v_mfma_f32_16x16x32_bf16 v[98:101], v[158:161], v[174:177], v[98:101]
	v_mfma_f32_16x16x32_bf16 v[86:89], v[150:153], v[192:195], v[86:89]
	v_mfma_f32_16x16x32_bf16 v[82:85], v[158:161], v[192:195], v[82:85]
	v_mfma_f32_16x16x32_bf16 v[70:73], v[150:153], v[212:215], v[70:73]
	v_mfma_f32_16x16x32_bf16 v[66:69], v[158:161], v[212:215], v[66:69]
	s_barrier
	s_setprio 0
	ds_read_b128 v[162:165], v208 offset:49152
	ds_read_b128 v[166:169], v208 offset:50176
	ds_read_b128 v[170:173], v208 offset:51200
	ds_read_b128 v[174:177], v208 offset:52224
	ds_read_b128 v[188:191], v208 offset:53248
	ds_read_b128 v[192:195], v208 offset:54272
	ds_read_b128 v[196:199], v208 offset:55296
	ds_read_b128 v[212:215], v208 offset:56320
	s_add_u32 s40, s38, 0x80
	s_addc_u32 s41, s39, 0
	s_mov_b32 m0, s52
	s_nop 0
	global_load_lds_dwordx4 v200, s[40:41]
	s_add_u32 s38, s38, 0x80080
	s_mov_b32 m0, s53
	s_nop 0
	global_load_lds_dwordx4 v203, s[40:41]
	s_addc_u32 s39, s39, 0
	s_mov_b32 m0, s56
	s_nop 0
	global_load_lds_dwordx4 v200, s[38:39]
	s_nop 0
	s_mov_b32 m0, s57
	s_nop 0
	global_load_lds_dwordx4 v203, s[38:39]
	s_mov_b32 m0, s54
	s_nop 0
	global_load_lds_dwordx4 v179, s[36:37]
	s_nop 0
	s_mov_b32 m0, s55
	s_nop 0
	global_load_lds_dwordx4 v201, s[36:37]
	s_waitcnt vmcnt(8)
	s_waitcnt lgkmcnt(0)
	s_setprio 1
	s_barrier
	v_mfma_f32_16x16x32_bf16 v[62:65], v[110:113], v[162:165], v[62:65]
	v_mfma_f32_16x16x32_bf16 v[58:61], v[130:133], v[162:165], v[58:61]
	v_mfma_f32_16x16x32_bf16 v[46:49], v[110:113], v[170:173], v[46:49]
	v_mfma_f32_16x16x32_bf16 v[42:45], v[130:133], v[170:173], v[42:45]
	v_mfma_f32_16x16x32_bf16 v[30:33], v[110:113], v[188:191], v[30:33]
	v_mfma_f32_16x16x32_bf16 v[26:29], v[130:133], v[188:191], v[26:29]
	v_mfma_f32_16x16x32_bf16 v[14:17], v[110:113], v[196:199], v[14:17]
	v_mfma_f32_16x16x32_bf16 v[10:13], v[130:133], v[196:199], v[10:13]
	v_mfma_f32_16x16x32_bf16 v[62:65], v[126:129], v[166:169], v[62:65]
	v_mfma_f32_16x16x32_bf16 v[58:61], v[142:145], v[166:169], v[58:61]
	v_mfma_f32_16x16x32_bf16 v[46:49], v[126:129], v[174:177], v[46:49]
	v_mfma_f32_16x16x32_bf16 v[42:45], v[142:145], v[174:177], v[42:45]
	v_mfma_f32_16x16x32_bf16 v[30:33], v[126:129], v[192:195], v[30:33]
	v_mfma_f32_16x16x32_bf16 v[26:29], v[142:145], v[192:195], v[26:29]
	v_mfma_f32_16x16x32_bf16 v[14:17], v[126:129], v[212:215], v[14:17]
	v_mfma_f32_16x16x32_bf16 v[10:13], v[142:145], v[212:215], v[10:13]
	v_mfma_f32_16x16x32_bf16 v[54:57], v[146:149], v[162:165], v[54:57]
	v_mfma_f32_16x16x32_bf16 v[50:53], v[154:157], v[162:165], v[50:53]
	v_mfma_f32_16x16x32_bf16 v[38:41], v[146:149], v[170:173], v[38:41]
	v_mfma_f32_16x16x32_bf16 v[34:37], v[154:157], v[170:173], v[34:37]
	v_mfma_f32_16x16x32_bf16 v[22:25], v[146:149], v[188:191], v[22:25]
	v_mfma_f32_16x16x32_bf16 v[18:21], v[154:157], v[188:191], v[18:21]
	v_mfma_f32_16x16x32_bf16 v[6:9], v[146:149], v[196:199], v[6:9]
	v_mfma_f32_16x16x32_bf16 v[2:5], v[154:157], v[196:199], v[2:5]
	v_mfma_f32_16x16x32_bf16 v[54:57], v[150:153], v[166:169], v[54:57]
	v_mfma_f32_16x16x32_bf16 v[50:53], v[158:161], v[166:169], v[50:53]
	v_mfma_f32_16x16x32_bf16 v[38:41], v[150:153], v[174:177], v[38:41]
	v_mfma_f32_16x16x32_bf16 v[34:37], v[158:161], v[174:177], v[34:37]
	v_mfma_f32_16x16x32_bf16 v[22:25], v[150:153], v[192:195], v[22:25]
	v_mfma_f32_16x16x32_bf16 v[18:21], v[158:161], v[192:195], v[18:21]
	v_mfma_f32_16x16x32_bf16 v[6:9], v[150:153], v[212:215], v[6:9]
	v_mfma_f32_16x16x32_bf16 v[2:5], v[158:161], v[212:215], v[2:5]
	s_barrier
	s_setprio 0
	s_add_i32 s63, s63, 2
	s_add_u32 s19, s19, 0x100
	s_addc_u32 s27, s27, 0
	s_add_u32 s61, s61, 0x100
	s_addc_u32 s62, s62, 0
	s_add_u32 s34, s34, 0x100
	s_addc_u32 s35, s35, 0
	s_cmp_gt_u32 s63, 29
	s_cbranch_scc0 .LBB0_1137
	s_and_b64 vcc, exec, s[16:17]
	s_cbranch_vccz .LBB0_1140
	s_barrier

; #define PG8_STAGE(bufoff, gbase, voff) do { _Pragma("unroll") for (int _i = 0; _i < 2; ++_i) { unsigned keep_; \
;         asm volatile("s_mov_b32 %0, m0\n\ts_mov_b32 m0, %3\n\ts_nop 0\n\tglobal_load_lds_dwordx4 %1, %2\n\ts_mov_b32 m0, %0" \
;             : "=&s"(keep_) : "v"((voff)[_i]), "s"((const void*)(gbase)), "s"(ldsb0 + (unsigned)(bufoff) + (unsigned)(_i * 8192)) : "memory"); } } while (0)
; #define PG8_LDA(dst, b, h) do { _Pragma("unroll") for (int m = 0; m < 4; ++m) _Pragma("unroll") for (int k = 0; k < 2; ++k) dst[m][k] = *(const LAS bf16x8*)(lds + PG8_SA(b, h) + aoff + m * 2048 + k * 1024); } while (0)
; #define PG8_LDB(dst, b, h) do { _Pragma("unroll") for (int n = 0; n < 2; ++n) _Pragma("unroll") for (int k = 0; k < 2; ++k) dst[n][k] = *(const LAS bf16x8*)(lds + PG8_SB(b, h) + boff + n * 2048 + k * 1024); } while (0)
; #define PG8_MMA(ai, bj, At, Bt) do { __builtin_amdgcn_s_setprio(1); _Pragma("unroll") for (int m = 0; m < 4; ++m) _Pragma("unroll") for (int n = 0; n < 2; ++n) _Pragma("unroll") for (int k = 0; k < 2; ++k) \
;         acc[ai][bj][m][n] = __builtin_amdgcn_mfma_f32_16x16x32_bf16(Bt[n][k], At[m][k], acc[ai][bj][m][n], 0, 0, 0); __builtin_amdgcn_s_setprio(0); } while (0)
; #define PG8_WAIT_V(n) asm volatile("s_waitcnt vmcnt(" #n ")" ::: "memory")
; #define PG8_WAIT_L(n) asm volatile("s_waitcnt lgkmcnt(" #n ")" ::: "memory")
; template <class Epi, class Sched, bool ALIGN_EPI>
; __device__ __forceinline__ void gemm_phase(LAS unsigned char* lds, const Gemm g, const Sched& S, const Epi& E) {
;     ...
;             const bool last = (t == nt - 2);
;             const char* a1 = cA + (size_t)(t + 1) * kstep;
;             const char* a2 = last ? nA : cA + (size_t)(t + 2) * kstep; const char* b2 = last ? nB : cB + (size_t)(t + 2) * kstep;
;             const char* a3 = a2 + kstep; const char* b3 = b2 + kstep;
;             PG8_LDB(B0, 0, 0); PG8_LDB(B1, 0, 1); PG8_SCHED; PG8_LDA(At, 0, 0); PG8_STAGE(PG8_SA(1, 1), a1 + hstepA, voffA);
;             PG8_WAIT_V(8); PG8_WAIT_L(0); PG8_BAR; PG8_MMA(0, 0, At, B0); PG8_MMA(0, 1, At, B1); PG8_BAR; PG8_SCHED;
;             PG8_LDA(At, 0, 1); PG8_STAGE(PG8_SB(0, 0), b2, voffB); PG8_STAGE(PG8_SB(0, 1), b2 + hstepB, voffB); PG8_STAGE(PG8_SA(0, 0), a2, voffA);
;             PG8_WAIT_V(8); PG8_WAIT_L(0); PG8_BAR; PG8_MMA(1, 0, At, B0); PG8_MMA(1, 1, At, B1); PG8_BAR; PG8_SCHED;
.LBB0_1218:
	ds_read_b128 v[154:157], v141
	ds_read_b128 v[158:161], v141 offset:1024
	ds_read_b128 v[162:165], v141 offset:2048
	ds_read_b128 v[166:169], v141 offset:3072
	ds_read_b128 v[170:173], v142
	ds_read_b128 v[174:177], v142 offset:1024
	ds_read_b128 v[180:183], v142 offset:2048
	ds_read_b128 v[184:187], v142 offset:3072
	s_add_u32 s36, s34, 0x100
	s_addc_u32 s37, s35, 0
	s_cmp_eq_u32 s64, 28
	s_cselect_b32 s42, s5, s36
	s_cselect_b32 s43, s3, s37
	s_cselect_b32 s40, s7, s19
	s_cselect_b32 s41, s6, s27
	s_add_u32 s38, s42, 0x80
	s_addc_u32 s39, s43, 0
	ds_read_b128 v[188:191], v143
	ds_read_b128 v[192:195], v143 offset:1024
	ds_read_b128 v[196:199], v143 offset:2048
	ds_read_b128 v[204:207], v143 offset:3072
	ds_read_b128 v[208:211], v143 offset:4096
	ds_read_b128 v[212:215], v143 offset:5120
	ds_read_b128 v[216:219], v143 offset:6144
	ds_read_b128 v[220:223], v143 offset:7168
	s_add_u32 s34, s34, 0x80080
	s_addc_u32 s35, s35, 0
	s_mov_b32 m0, s61
	s_nop 0
	global_load_lds_dwordx4 v134, s[34:35]
	s_nop 0
	s_mov_b32 m0, s62
	s_nop 0
	global_load_lds_dwordx4 v136, s[34:35]
	s_waitcnt vmcnt(8)
	s_waitcnt lgkmcnt(0)
	s_setprio 1
	s_barrier
	v_mfma_f32_16x16x32_bf16 v[126:129], v[154:157], v[188:191], v[126:129]
	v_mfma_f32_16x16x32_bf16 v[122:125], v[162:165], v[188:191], v[122:125]
	v_mfma_f32_16x16x32_bf16 v[110:113], v[154:157], v[196:199], v[110:113]
	v_mfma_f32_16x16x32_bf16 v[106:109], v[162:165], v[196:199], v[106:109]
	v_mfma_f32_16x16x32_bf16 v[94:97], v[154:157], v[208:211], v[94:97]
	v_mfma_f32_16x16x32_bf16 v[90:93], v[162:165], v[208:211], v[90:93]
	v_mfma_f32_16x16x32_bf16 v[78:81], v[154:157], v[216:219], v[78:81]
	v_mfma_f32_16x16x32_bf16 v[74:77], v[162:165], v[216:219], v[74:77]
	v_mfma_f32_16x16x32_bf16 v[126:129], v[158:161], v[192:195], v[126:129]
	v_mfma_f32_16x16x32_bf16 v[122:125], v[166:169], v[192:195], v[122:125]
	v_mfma_f32_16x16x32_bf16 v[110:113], v[158:161], v[204:207], v[110:113]
	v_mfma_f32_16x16x32_bf16 v[106:109], v[166:169], v[204:207], v[106:109]
	v_mfma_f32_16x16x32_bf16 v[94:97], v[158:161], v[212:215], v[94:97]
	v_mfma_f32_16x16x32_bf16 v[90:93], v[166:169], v[212:215], v[90:93]
	v_mfma_f32_16x16x32_bf16 v[78:81], v[158:161], v[220:223], v[78:81]
	v_mfma_f32_16x16x32_bf16 v[74:77], v[166:169], v[220:223], v[74:77]
	v_mfma_f32_16x16x32_bf16 v[118:121], v[170:173], v[188:191], v[118:121]
	v_mfma_f32_16x16x32_bf16 v[114:117], v[180:183], v[188:191], v[114:117]
	v_mfma_f32_16x16x32_bf16 v[102:105], v[170:173], v[196:199], v[102:105]
	v_mfma_f32_16x16x32_bf16 v[98:101], v[180:183], v[196:199], v[98:101]
	v_mfma_f32_16x16x32_bf16 v[86:89], v[170:173], v[208:211], v[86:89]
	v_mfma_f32_16x16x32_bf16 v[82:85], v[180:183], v[208:211], v[82:85]
	v_mfma_f32_16x16x32_bf16 v[70:73], v[170:173], v[216:219], v[70:73]
	v_mfma_f32_16x16x32_bf16 v[66:69], v[180:183], v[216:219], v[66:69]
	v_mfma_f32_16x16x32_bf16 v[118:121], v[174:177], v[192:195], v[118:121]
	v_mfma_f32_16x16x32_bf16 v[114:117], v[184:187], v[192:195], v[114:117]
	v_mfma_f32_16x16x32_bf16 v[102:105], v[174:177], v[204:207], v[102:105]
	v_mfma_f32_16x16x32_bf16 v[98:101], v[184:187], v[204:207], v[98:101]
	v_mfma_f32_16x16x32_bf16 v[86:89], v[174:177], v[212:215], v[86:89]
	v_mfma_f32_16x16x32_bf16 v[82:85], v[184:187], v[212:215], v[82:85]
	v_mfma_f32_16x16x32_bf16 v[70:73], v[174:177], v[220:223], v[70:73]
	v_mfma_f32_16x16x32_bf16 v[66:69], v[184:187], v[220:223], v[66:69]
	s_barrier
	s_setprio 0
	ds_read_b128 v[188:191], v143 offset:16384
	ds_read_b128 v[192:195], v143 offset:17408
	ds_read_b128 v[196:199], v143 offset:18432
	ds_read_b128 v[204:207], v143 offset:19456
	ds_read_b128 v[208:211], v143 offset:20480
	ds_read_b128 v[212:215], v143 offset:21504
	ds_read_b128 v[216:219], v143 offset:22528
	ds_read_b128 v[220:223], v143 offset:23552
	s_mov_b32 m0, s47
	s_nop 0
	global_load_lds_dwordx4 v135, s[40:41]
	s_nop 0
	s_mov_b32 m0, s48
	s_nop 0
	global_load_lds_dwordx4 v137, s[40:41]
	s_add_u32 s34, s40, 0x80000
	s_addc_u32 s35, s41, 0
	s_mov_b32 m0, s49
	s_nop 0
	global_load_lds_dwordx4 v135, s[34:35]
	s_nop 0
	s_mov_b32 m0, s50
	s_nop 0
	global_load_lds_dwordx4 v137, s[34:35]
	s_mov_b32 m0, s45
	s_nop 0
	global_load_lds_dwordx4 v134, s[42:43]
	s_nop 0
	s_mov_b32 m0, s51
	s_nop 0
	global_load_lds_dwordx4 v136, s[42:43]
	s_waitcnt vmcnt(8)
	s_waitcnt lgkmcnt(0)
	s_setprio 1
	s_barrier
	v_mfma_f32_16x16x32_bf16 v[62:65], v[154:157], v[188:191], v[62:65]
	v_mfma_f32_16x16x32_bf16 v[58:61], v[162:165], v[188:191], v[58:61]
	v_mfma_f32_16x16x32_bf16 v[46:49], v[154:157], v[196:199], v[46:49]
	v_mfma_f32_16x16x32_bf16 v[42:45], v[162:165], v[196:199], v[42:45]
	v_mfma_f32_16x16x32_bf16 v[30:33], v[154:157], v[208:211], v[30:33]
	v_mfma_f32_16x16x32_bf16 v[26:29], v[162:165], v[208:211], v[26:29]
	v_mfma_f32_16x16x32_bf16 v[14:17], v[154:157], v[216:219], v[14:17]
	v_mfma_f32_16x16x32_bf16 v[10:13], v[162:165], v[216:219], v[10:13]
	v_mfma_f32_16x16x32_bf16 v[62:65], v[158:161], v[192:195], v[62:65]
	v_mfma_f32_16x16x32_bf16 v[58:61], v[166:169], v[192:195], v[58:61]
	v_mfma_f32_16x16x32_bf16 v[46:49], v[158:161], v[204:207], v[46:49]
	v_mfma_f32_16x16x32_bf16 v[42:45], v[166:169], v[204:207], v[42:45]
	v_mfma_f32_16x16x32_bf16 v[30:33], v[158:161], v[212:215], v[30:33]
	v_mfma_f32_16x16x32_bf16 v[26:29], v[166:169], v[212:215], v[26:29]
	v_mfma_f32_16x16x32_bf16 v[14:17], v[158:161], v[220:223], v[14:17]
	v_mfma_f32_16x16x32_bf16 v[10:13], v[166:169], v[220:223], v[10:13]
	v_mfma_f32_16x16x32_bf16 v[54:57], v[170:173], v[188:191], v[54:57]
	v_mfma_f32_16x16x32_bf16 v[50:53], v[180:183], v[188:191], v[50:53]
	v_mfma_f32_16x16x32_bf16 v[38:41], v[170:173], v[196:199], v[38:41]
	v_mfma_f32_16x16x32_bf16 v[34:37], v[180:183], v[196:199], v[34:37]
	v_mfma_f32_16x16x32_bf16 v[22:25], v[170:173], v[208:211], v[22:25]
	v_mfma_f32_16x16x32_bf16 v[18:21], v[180:183], v[208:211], v[18:21]
	v_mfma_f32_16x16x32_bf16 v[6:9], v[170:173], v[216:219], v[6:9]
	v_mfma_f32_16x16x32_bf16 v[2:5], v[180:183], v[216:219], v[2:5]
	v_mfma_f32_16x16x32_bf16 v[54:57], v[174:177], v[192:195], v[54:57]
	v_mfma_f32_16x16x32_bf16 v[50:53], v[184:187], v[192:195], v[50:53]
	v_mfma_f32_16x16x32_bf16 v[38:41], v[174:177], v[204:207], v[38:41]
	v_mfma_f32_16x16x32_bf16 v[34:37], v[184:187], v[204:207], v[34:37]
	v_mfma_f32_16x16x32_bf16 v[22:25], v[174:177], v[212:215], v[22:25]
	v_mfma_f32_16x16x32_bf16 v[18:21], v[184:187], v[212:215], v[18:21]
	v_mfma_f32_16x16x32_bf16 v[6:9], v[174:177], v[220:223], v[6:9]
	v_mfma_f32_16x16x32_bf16 v[2:5], v[184:187], v[220:223], v[2:5]
	s_barrier
; #define PG8_STAGE(bufoff, gbase, voff) do { _Pragma("unroll") for (int _i = 0; _i < 2; ++_i) { unsigned keep_; \
;         asm volatile("s_mov_b32 %0, m0\n\ts_mov_b32 m0, %3\n\ts_nop 0\n\tglobal_load_lds_dwordx4 %1, %2\n\ts_mov_b32 m0, %0" \
;             : "=&s"(keep_) : "v"((voff)[_i]), "s"((const void*)(gbase)), "s"(ldsb0 + (unsigned)(bufoff) + (unsigned)(_i * 8192)) : "memory"); } } while (0)
; #define PG8_LDA(dst, b, h) do { _Pragma("unroll") for (int m = 0; m < 4; ++m) _Pragma("unroll") for (int k = 0; k < 2; ++k) dst[m][k] = *(const LAS bf16x8*)(lds + PG8_SA(b, h) + aoff + m * 2048 + k * 1024); } while (0)
; #define PG8_LDB(dst, b, h) do { _Pragma("unroll") for (int n = 0; n < 2; ++n) _Pragma("unroll") for (int k = 0; k < 2; ++k) dst[n][k] = *(const LAS bf16x8*)(lds + PG8_SB(b, h) + boff + n * 2048 + k * 1024); } while (0)
; #define PG8_MMA(ai, bj, At, Bt) do { __builtin_amdgcn_s_setprio(1); _Pragma("unroll") for (int m = 0; m < 4; ++m) _Pragma("unroll") for (int n = 0; n < 2; ++n) _Pragma("unroll") for (int k = 0; k < 2; ++k) \
;         acc[ai][bj][m][n] = __builtin_amdgcn_mfma_f32_16x16x32_bf16(Bt[n][k], At[m][k], acc[ai][bj][m][n], 0, 0, 0); __builtin_amdgcn_s_setprio(0); } while (0)
; #define PG8_WAIT_V(n) asm volatile("s_waitcnt vmcnt(" #n ")" ::: "memory")
; #define PG8_WAIT_L(n) asm volatile("s_waitcnt lgkmcnt(" #n ")" ::: "memory")
; #define PG8_BAR __builtin_amdgcn_s_barrier()
; #define PG8_SCHED __builtin_amdgcn_sched_barrier(0)
; template <class Epi, class Sched, bool ALIGN_EPI>
; __device__ __forceinline__ void gemm_phase(LAS unsigned char* lds, const Gemm g, const Sched& S, const Epi& E) {
;     ...
;             PG8_LDB(B0, 1, 0); PG8_LDB(B1, 1, 1); PG8_SCHED; PG8_LDA(At, 1, 0); PG8_STAGE(PG8_SA(0, 1), a2 + hstepA, voffA);
;             PG8_WAIT_V(8); PG8_WAIT_L(0); PG8_BAR; PG8_MMA(0, 0, At, B0); PG8_MMA(0, 1, At, B1); PG8_BAR; PG8_SCHED;
;             PG8_LDA(At, 1, 1); PG8_STAGE(PG8_SB(1, 0), b3, voffB); PG8_STAGE(PG8_SB(1, 1), b3 + hstepB, voffB); PG8_STAGE(PG8_SA(1, 0), a3, voffA);
;             PG8_WAIT_V(8); PG8_WAIT_L(0); PG8_BAR; PG8_MMA(1, 0, At, B0); PG8_MMA(1, 1, At, B1); PG8_BAR; PG8_SCHED;
;         }
	s_setprio 0
	ds_read_b128 v[154:157], v144
	ds_read_b128 v[158:161], v144 offset:1024
	ds_read_b128 v[162:165], v144 offset:2048
	ds_read_b128 v[166:169], v144 offset:3072
	ds_read_b128 v[170:173], v145
	ds_read_b128 v[174:177], v145 offset:1024
	ds_read_b128 v[180:183], v145 offset:2048
	ds_read_b128 v[184:187], v145 offset:3072
	ds_read_b128 v[188:191], v143 offset:32768
	ds_read_b128 v[192:195], v143 offset:33792
	ds_read_b128 v[196:199], v143 offset:34816
	ds_read_b128 v[204:207], v143 offset:35840
	ds_read_b128 v[208:211], v143 offset:36864
	ds_read_b128 v[212:215], v143 offset:37888
	ds_read_b128 v[216:219], v143 offset:38912
	ds_read_b128 v[220:223], v143 offset:39936
	s_add_u32 s34, s42, 0x80000
	s_addc_u32 s35, s43, 0
	s_mov_b32 m0, s52
	s_nop 0
	global_load_lds_dwordx4 v134, s[34:35]
	s_nop 0
	s_mov_b32 m0, s53
	s_nop 0
	global_load_lds_dwordx4 v136, s[34:35]
	s_waitcnt vmcnt(8)
	s_waitcnt lgkmcnt(0)
	s_setprio 1
	s_barrier
	v_mfma_f32_16x16x32_bf16 v[126:129], v[154:157], v[188:191], v[126:129]
	v_mfma_f32_16x16x32_bf16 v[122:125], v[162:165], v[188:191], v[122:125]
	v_mfma_f32_16x16x32_bf16 v[110:113], v[154:157], v[196:199], v[110:113]
	v_mfma_f32_16x16x32_bf16 v[106:109], v[162:165], v[196:199], v[106:109]
	v_mfma_f32_16x16x32_bf16 v[94:97], v[154:157], v[208:211], v[94:97]
	v_mfma_f32_16x16x32_bf16 v[90:93], v[162:165], v[208:211], v[90:93]
	v_mfma_f32_16x16x32_bf16 v[78:81], v[154:157], v[216:219], v[78:81]
	v_mfma_f32_16x16x32_bf16 v[74:77], v[162:165], v[216:219], v[74:77]
	v_mfma_f32_16x16x32_bf16 v[126:129], v[158:161], v[192:195], v[126:129]
	v_mfma_f32_16x16x32_bf16 v[122:125], v[166:169], v[192:195], v[122:125]
	v_mfma_f32_16x16x32_bf16 v[110:113], v[158:161], v[204:207], v[110:113]
	v_mfma_f32_16x16x32_bf16 v[106:109], v[166:169], v[204:207], v[106:109]
	v_mfma_f32_16x16x32_bf16 v[94:97], v[158:161], v[212:215], v[94:97]
	v_mfma_f32_16x16x32_bf16 v[90:93], v[166:169], v[212:215], v[90:93]
	v_mfma_f32_16x16x32_bf16 v[78:81], v[158:161], v[220:223], v[78:81]
	v_mfma_f32_16x16x32_bf16 v[74:77], v[166:169], v[220:223], v[74:77]
	v_mfma_f32_16x16x32_bf16 v[118:121], v[170:173], v[188:191], v[118:121]
	v_mfma_f32_16x16x32_bf16 v[114:117], v[180:183], v[188:191], v[114:117]
	v_mfma_f32_16x16x32_bf16 v[102:105], v[170:173], v[196:199], v[102:105]
	v_mfma_f32_16x16x32_bf16 v[98:101], v[180:183], v[196:199], v[98:101]
	v_mfma_f32_16x16x32_bf16 v[86:89], v[170:173], v[208:211], v[86:89]
	v_mfma_f32_16x16x32_bf16 v[82:85], v[180:183], v[208:211], v[82:85]
	v_mfma_f32_16x16x32_bf16 v[70:73], v[170:173], v[216:219], v[70:73]
	v_mfma_f32_16x16x32_bf16 v[66:69], v[180:183], v[216:219], v[66:69]
	v_mfma_f32_16x16x32_bf16 v[118:121], v[174:177], v[192:195], v[118:121]
	v_mfma_f32_16x16x32_bf16 v[114:117], v[184:187], v[192:195], v[114:117]
	v_mfma_f32_16x16x32_bf16 v[102:105], v[174:177], v[204:207], v[102:105]
	v_mfma_f32_16x16x32_bf16 v[98:101], v[184:187], v[204:207], v[98:101]
	v_mfma_f32_16x16x32_bf16 v[86:89], v[174:177], v[212:215], v[86:89]
	v_mfma_f32_16x16x32_bf16 v[82:85], v[184:187], v[212:215], v[82:85]
	v_mfma_f32_16x16x32_bf16 v[70:73], v[174:177], v[220:223], v[70:73]
	v_mfma_f32_16x16x32_bf16 v[66:69], v[184:187], v[220:223], v[66:69]
	s_barrier
	s_setprio 0
	ds_read_b128 v[188:191], v143 offset:49152
	ds_read_b128 v[192:195], v143 offset:50176
	ds_read_b128 v[196:199], v143 offset:51200
	ds_read_b128 v[204:207], v143 offset:52224
	ds_read_b128 v[208:211], v143 offset:53248
	ds_read_b128 v[212:215], v143 offset:54272
	ds_read_b128 v[216:219], v143 offset:55296
	ds_read_b128 v[220:223], v143 offset:56320
	s_add_u32 s34, s40, 0x80
	s_addc_u32 s35, s41, 0
	s_mov_b32 m0, s54
	s_nop 0
	global_load_lds_dwordx4 v135, s[34:35]
	s_nop 0
	s_mov_b32 m0, s55
	s_nop 0
	global_load_lds_dwordx4 v137, s[34:35]
	s_add_u32 s34, s40, 0x80080
	s_addc_u32 s35, s41, 0
	s_mov_b32 m0, s58
	s_nop 0
	global_load_lds_dwordx4 v135, s[34:35]
	s_nop 0
	s_mov_b32 m0, s59
	s_nop 0
	global_load_lds_dwordx4 v137, s[34:35]
	s_mov_b32 m0, s56
	s_nop 0
	global_load_lds_dwordx4 v134, s[38:39]
	s_nop 0
	s_mov_b32 m0, s57
	s_nop 0
	global_load_lds_dwordx4 v136, s[38:39]
	s_waitcnt vmcnt(8)
	s_waitcnt lgkmcnt(0)
	s_setprio 1
	s_barrier
	v_mfma_f32_16x16x32_bf16 v[62:65], v[154:157], v[188:191], v[62:65]
	v_mfma_f32_16x16x32_bf16 v[58:61], v[162:165], v[188:191], v[58:61]
	v_mfma_f32_16x16x32_bf16 v[46:49], v[154:157], v[196:199], v[46:49]
	v_mfma_f32_16x16x32_bf16 v[42:45], v[162:165], v[196:199], v[42:45]
	v_mfma_f32_16x16x32_bf16 v[30:33], v[154:157], v[208:211], v[30:33]
	v_mfma_f32_16x16x32_bf16 v[26:29], v[162:165], v[208:211], v[26:29]
	v_mfma_f32_16x16x32_bf16 v[14:17], v[154:157], v[216:219], v[14:17]
	v_mfma_f32_16x16x32_bf16 v[10:13], v[162:165], v[216:219], v[10:13]
	v_mfma_f32_16x16x32_bf16 v[62:65], v[158:161], v[192:195], v[62:65]
	v_mfma_f32_16x16x32_bf16 v[58:61], v[166:169], v[192:195], v[58:61]
	v_mfma_f32_16x16x32_bf16 v[46:49], v[158:161], v[204:207], v[46:49]
	v_mfma_f32_16x16x32_bf16 v[42:45], v[166:169], v[204:207], v[42:45]
	v_mfma_f32_16x16x32_bf16 v[30:33], v[158:161], v[212:215], v[30:33]
	v_mfma_f32_16x16x32_bf16 v[26:29], v[166:169], v[212:215], v[26:29]
	v_mfma_f32_16x16x32_bf16 v[14:17], v[158:161], v[220:223], v[14:17]
	v_mfma_f32_16x16x32_bf16 v[10:13], v[166:169], v[220:223], v[10:13]
	v_mfma_f32_16x16x32_bf16 v[54:57], v[170:173], v[188:191], v[54:57]
	v_mfma_f32_16x16x32_bf16 v[50:53], v[180:183], v[188:191], v[50:53]
	v_mfma_f32_16x16x32_bf16 v[38:41], v[170:173], v[196:199], v[38:41]
	v_mfma_f32_16x16x32_bf16 v[34:37], v[180:183], v[196:199], v[34:37]
	v_mfma_f32_16x16x32_bf16 v[22:25], v[170:173], v[208:211], v[22:25]
	v_mfma_f32_16x16x32_bf16 v[18:21], v[180:183], v[208:211], v[18:21]
	v_mfma_f32_16x16x32_bf16 v[6:9], v[170:173], v[216:219], v[6:9]
	v_mfma_f32_16x16x32_bf16 v[2:5], v[180:183], v[216:219], v[2:5]
	v_mfma_f32_16x16x32_bf16 v[54:57], v[174:177], v[192:195], v[54:57]
	v_mfma_f32_16x16x32_bf16 v[50:53], v[184:187], v[192:195], v[50:53]
	v_mfma_f32_16x16x32_bf16 v[38:41], v[174:177], v[204:207], v[38:41]
	v_mfma_f32_16x16x32_bf16 v[34:37], v[184:187], v[204:207], v[34:37]
	v_mfma_f32_16x16x32_bf16 v[22:25], v[174:177], v[212:215], v[22:25]
	v_mfma_f32_16x16x32_bf16 v[18:21], v[184:187], v[212:215], v[18:21]
	v_mfma_f32_16x16x32_bf16 v[6:9], v[174:177], v[220:223], v[6:9]
	v_mfma_f32_16x16x32_bf16 v[2:5], v[184:187], v[220:223], v[2:5]
	s_barrier
	s_setprio 0
	s_add_i32 s64, s64, 2
	s_add_u32 s19, s19, 0x100
	s_addc_u32 s27, s27, 0
	s_cmp_gt_u32 s64, 29
	s_mov_b64 s[34:35], s[36:37]
	s_cbranch_scc0 .LBB0_1218
	s_and_b64 vcc, exec, s[16:17]
	s_cbranch_vccz .LBB0_1221
	s_barrier

; #define PG8_STAGE(bufoff, gbase, voff) do { _Pragma("unroll") for (int _i = 0; _i < 2; ++_i) { unsigned keep_; \
;         asm volatile("s_mov_b32 %0, m0\n\ts_mov_b32 m0, %3\n\ts_nop 0\n\tglobal_load_lds_dwordx4 %1, %2\n\ts_mov_b32 m0, %0" \
;             : "=&s"(keep_) : "v"((voff)[_i]), "s"((const void*)(gbase)), "s"(ldsb0 + (unsigned)(bufoff) + (unsigned)(_i * 8192)) : "memory"); } } while (0)
; #define PG8_LDA(dst, b, h) do { _Pragma("unroll") for (int m = 0; m < 4; ++m) _Pragma("unroll") for (int k = 0; k < 2; ++k) dst[m][k] = *(const LAS bf16x8*)(lds + PG8_SA(b, h) + aoff + m * 2048 + k * 1024); } while (0)
; #define PG8_LDB(dst, b, h) do { _Pragma("unroll") for (int n = 0; n < 2; ++n) _Pragma("unroll") for (int k = 0; k < 2; ++k) dst[n][k] = *(const LAS bf16x8*)(lds + PG8_SB(b, h) + boff + n * 2048 + k * 1024); } while (0)
; #define PG8_MMA(ai, bj, At, Bt) do { __builtin_amdgcn_s_setprio(1); _Pragma("unroll") for (int m = 0; m < 4; ++m) _Pragma("unroll") for (int n = 0; n < 2; ++n) _Pragma("unroll") for (int k = 0; k < 2; ++k) \
;         acc[ai][bj][m][n] = __builtin_amdgcn_mfma_f32_16x16x32_bf16(Bt[n][k], At[m][k], acc[ai][bj][m][n], 0, 0, 0); __builtin_amdgcn_s_setprio(0); } while (0)
; #define PG8_WAIT_V(n) asm volatile("s_waitcnt vmcnt(" #n ")" ::: "memory")
; #define PG8_WAIT_L(n) asm volatile("s_waitcnt lgkmcnt(" #n ")" ::: "memory")
; template <class Epi, class Sched, bool ALIGN_EPI>
; __device__ __forceinline__ void gemm_phase(LAS unsigned char* lds, const Gemm g, const Sched& S, const Epi& E) {
;     ...
;             const bool last = (t == nt - 2);
;             const char* a1 = cA + (size_t)(t + 1) * kstep;
;             const char* a2 = last ? nA : cA + (size_t)(t + 2) * kstep; const char* b2 = last ? nB : cB + (size_t)(t + 2) * kstep;
;             const char* a3 = a2 + kstep; const char* b3 = b2 + kstep;
;             PG8_LDB(B0, 0, 0); PG8_LDB(B1, 0, 1); PG8_SCHED; PG8_LDA(At, 0, 0); PG8_STAGE(PG8_SA(1, 1), a1 + hstepA, voffA);
;             PG8_WAIT_V(8); PG8_WAIT_L(0); PG8_BAR; PG8_MMA(0, 0, At, B0); PG8_MMA(0, 1, At, B1); PG8_BAR; PG8_SCHED;
;             PG8_LDA(At, 0, 1); PG8_STAGE(PG8_SB(0, 0), b2, voffB); PG8_STAGE(PG8_SB(0, 1), b2 + hstepB, voffB); PG8_STAGE(PG8_SA(0, 0), a2, voffA);
;             PG8_WAIT_V(8); PG8_WAIT_L(0); PG8_BAR; PG8_MMA(1, 0, At, B0); PG8_MMA(1, 1, At, B1); PG8_BAR; PG8_SCHED;
.LBB0_1317:
	ds_read_b128 v[110:113], v206
	ds_read_b128 v[126:129], v206 offset:1024
	ds_read_b128 v[130:133], v206 offset:2048
	ds_read_b128 v[142:145], v206 offset:3072
	ds_read_b128 v[146:149], v207
	ds_read_b128 v[150:153], v207 offset:1024
	ds_read_b128 v[154:157], v207 offset:2048
	ds_read_b128 v[158:161], v207 offset:3072
	s_cmpk_eq_i32 s58, 0x54
	s_cselect_b32 s34, s14, s6
	s_cselect_b32 s35, s15, s7
	s_cselect_b32 s30, s26, s56
	s_cselect_b32 s31, s27, s57
	s_add_u32 s28, s34, 0x80
	s_addc_u32 s29, s35, 0
	ds_read_b128 v[162:165], v208
	ds_read_b128 v[166:169], v208 offset:1024
	ds_read_b128 v[170:173], v208 offset:2048
	ds_read_b128 v[174:177], v208 offset:3072
	ds_read_b128 v[188:191], v208 offset:4096
	ds_read_b128 v[192:195], v208 offset:5120
	ds_read_b128 v[196:199], v208 offset:6144
	ds_read_b128 v[212:215], v208 offset:7168
	s_mov_b32 m0, s52
	s_nop 0
	global_load_lds_dwordx4 v179, s[4:5]
	s_nop 0
	s_mov_b32 m0, s53
	s_nop 0
	global_load_lds_dwordx4 v201, s[4:5]
	s_waitcnt vmcnt(8)
	s_waitcnt lgkmcnt(0)
	s_setprio 1
	s_barrier
	v_mfma_f32_16x16x32_bf16 v[138:141], v[110:113], v[162:165], v[138:141]
	v_mfma_f32_16x16x32_bf16 v[134:137], v[130:133], v[162:165], v[134:137]
	v_mfma_f32_16x16x32_bf16 v[114:117], v[110:113], v[170:173], v[114:117]
	v_mfma_f32_16x16x32_bf16 v[106:109], v[130:133], v[170:173], v[106:109]
	v_mfma_f32_16x16x32_bf16 v[94:97], v[110:113], v[188:191], v[94:97]
	v_mfma_f32_16x16x32_bf16 v[90:93], v[130:133], v[188:191], v[90:93]
	v_mfma_f32_16x16x32_bf16 v[78:81], v[110:113], v[196:199], v[78:81]
	v_mfma_f32_16x16x32_bf16 v[74:77], v[130:133], v[196:199], v[74:77]
	v_mfma_f32_16x16x32_bf16 v[138:141], v[126:129], v[166:169], v[138:141]
	v_mfma_f32_16x16x32_bf16 v[134:137], v[142:145], v[166:169], v[134:137]
	v_mfma_f32_16x16x32_bf16 v[114:117], v[126:129], v[174:177], v[114:117]
	v_mfma_f32_16x16x32_bf16 v[106:109], v[142:145], v[174:177], v[106:109]
	v_mfma_f32_16x16x32_bf16 v[94:97], v[126:129], v[192:195], v[94:97]
	v_mfma_f32_16x16x32_bf16 v[90:93], v[142:145], v[192:195], v[90:93]
	v_mfma_f32_16x16x32_bf16 v[78:81], v[126:129], v[212:215], v[78:81]
	v_mfma_f32_16x16x32_bf16 v[74:77], v[142:145], v[212:215], v[74:77]
	v_mfma_f32_16x16x32_bf16 v[122:125], v[146:149], v[162:165], v[122:125]
	v_mfma_f32_16x16x32_bf16 v[118:121], v[154:157], v[162:165], v[118:121]
	v_mfma_f32_16x16x32_bf16 v[102:105], v[146:149], v[170:173], v[102:105]
	v_mfma_f32_16x16x32_bf16 v[98:101], v[154:157], v[170:173], v[98:101]
	v_mfma_f32_16x16x32_bf16 v[86:89], v[146:149], v[188:191], v[86:89]
	v_mfma_f32_16x16x32_bf16 v[82:85], v[154:157], v[188:191], v[82:85]
	v_mfma_f32_16x16x32_bf16 v[70:73], v[146:149], v[196:199], v[70:73]
	v_mfma_f32_16x16x32_bf16 v[66:69], v[154:157], v[196:199], v[66:69]
	v_mfma_f32_16x16x32_bf16 v[122:125], v[150:153], v[166:169], v[122:125]
	v_mfma_f32_16x16x32_bf16 v[118:121], v[158:161], v[166:169], v[118:121]
	v_mfma_f32_16x16x32_bf16 v[102:105], v[150:153], v[174:177], v[102:105]
	v_mfma_f32_16x16x32_bf16 v[98:101], v[158:161], v[174:177], v[98:101]
	v_mfma_f32_16x16x32_bf16 v[86:89], v[150:153], v[192:195], v[86:89]
	v_mfma_f32_16x16x32_bf16 v[82:85], v[158:161], v[192:195], v[82:85]
	v_mfma_f32_16x16x32_bf16 v[70:73], v[150:153], v[212:215], v[70:73]
	v_mfma_f32_16x16x32_bf16 v[66:69], v[158:161], v[212:215], v[66:69]
	s_barrier
	s_setprio 0
	ds_read_b128 v[162:165], v208 offset:16384
	ds_read_b128 v[166:169], v208 offset:17408
	ds_read_b128 v[170:173], v208 offset:18432
	ds_read_b128 v[174:177], v208 offset:19456
	ds_read_b128 v[188:191], v208 offset:20480
	ds_read_b128 v[192:195], v208 offset:21504
	ds_read_b128 v[196:199], v208 offset:22528
	ds_read_b128 v[212:215], v208 offset:23552
	s_mov_b32 m0, s39
	s_nop 0
	global_load_lds_dwordx4 v200, s[30:31]
	s_add_u32 s62, s30, 0x160000
	s_mov_b32 m0, s40
	s_nop 0
	global_load_lds_dwordx4 v203, s[30:31]
	s_addc_u32 s63, s31, 0
	s_mov_b32 m0, s41
	s_nop 0
	global_load_lds_dwordx4 v200, s[62:63]
	s_nop 0
	s_mov_b32 m0, s42
	s_nop 0
	global_load_lds_dwordx4 v203, s[62:63]
	s_nop 0
	s_mov_b32 m0, s38
	s_nop 0
	global_load_lds_dwordx4 v179, s[34:35]
	s_nop 0
	s_mov_b32 m0, s43
	s_nop 0
	global_load_lds_dwordx4 v201, s[34:35]
	s_waitcnt vmcnt(8)
	s_waitcnt lgkmcnt(0)
	s_setprio 1
	s_barrier
	v_mfma_f32_16x16x32_bf16 v[62:65], v[110:113], v[162:165], v[62:65]
	v_mfma_f32_16x16x32_bf16 v[58:61], v[130:133], v[162:165], v[58:61]
	v_mfma_f32_16x16x32_bf16 v[46:49], v[110:113], v[170:173], v[46:49]
	v_mfma_f32_16x16x32_bf16 v[42:45], v[130:133], v[170:173], v[42:45]
	v_mfma_f32_16x16x32_bf16 v[30:33], v[110:113], v[188:191], v[30:33]
	v_mfma_f32_16x16x32_bf16 v[26:29], v[130:133], v[188:191], v[26:29]
	v_mfma_f32_16x16x32_bf16 v[14:17], v[110:113], v[196:199], v[14:17]
	v_mfma_f32_16x16x32_bf16 v[10:13], v[130:133], v[196:199], v[10:13]
	v_mfma_f32_16x16x32_bf16 v[62:65], v[126:129], v[166:169], v[62:65]
	v_mfma_f32_16x16x32_bf16 v[58:61], v[142:145], v[166:169], v[58:61]
	v_mfma_f32_16x16x32_bf16 v[46:49], v[126:129], v[174:177], v[46:49]
	v_mfma_f32_16x16x32_bf16 v[42:45], v[142:145], v[174:177], v[42:45]
	v_mfma_f32_16x16x32_bf16 v[30:33], v[126:129], v[192:195], v[30:33]
	v_mfma_f32_16x16x32_bf16 v[26:29], v[142:145], v[192:195], v[26:29]
	v_mfma_f32_16x16x32_bf16 v[14:17], v[126:129], v[212:215], v[14:17]
	v_mfma_f32_16x16x32_bf16 v[10:13], v[142:145], v[212:215], v[10:13]
	v_mfma_f32_16x16x32_bf16 v[54:57], v[146:149], v[162:165], v[54:57]
	v_mfma_f32_16x16x32_bf16 v[50:53], v[154:157], v[162:165], v[50:53]
	v_mfma_f32_16x16x32_bf16 v[38:41], v[146:149], v[170:173], v[38:41]
	v_mfma_f32_16x16x32_bf16 v[34:37], v[154:157], v[170:173], v[34:37]
	v_mfma_f32_16x16x32_bf16 v[22:25], v[146:149], v[188:191], v[22:25]
	v_mfma_f32_16x16x32_bf16 v[18:21], v[154:157], v[188:191], v[18:21]
	v_mfma_f32_16x16x32_bf16 v[6:9], v[146:149], v[196:199], v[6:9]
	v_mfma_f32_16x16x32_bf16 v[2:5], v[154:157], v[196:199], v[2:5]
	v_mfma_f32_16x16x32_bf16 v[54:57], v[150:153], v[166:169], v[54:57]
	v_mfma_f32_16x16x32_bf16 v[50:53], v[158:161], v[166:169], v[50:53]
	v_mfma_f32_16x16x32_bf16 v[38:41], v[150:153], v[174:177], v[38:41]
	v_mfma_f32_16x16x32_bf16 v[34:37], v[158:161], v[174:177], v[34:37]
	v_mfma_f32_16x16x32_bf16 v[22:25], v[150:153], v[192:195], v[22:25]
	v_mfma_f32_16x16x32_bf16 v[18:21], v[158:161], v[192:195], v[18:21]
	v_mfma_f32_16x16x32_bf16 v[6:9], v[150:153], v[212:215], v[6:9]
	v_mfma_f32_16x16x32_bf16 v[2:5], v[158:161], v[212:215], v[2:5]
	s_barrier
; #define PG8_STAGE(bufoff, gbase, voff) do { _Pragma("unroll") for (int _i = 0; _i < 2; ++_i) { unsigned keep_; \
;         asm volatile("s_mov_b32 %0, m0\n\ts_mov_b32 m0, %3\n\ts_nop 0\n\tglobal_load_lds_dwordx4 %1, %2\n\ts_mov_b32 m0, %0" \
;             : "=&s"(keep_) : "v"((voff)[_i]), "s"((const void*)(gbase)), "s"(ldsb0 + (unsigned)(bufoff) + (unsigned)(_i * 8192)) : "memory"); } } while (0)
; #define PG8_LDA(dst, b, h) do { _Pragma("unroll") for (int m = 0; m < 4; ++m) _Pragma("unroll") for (int k = 0; k < 2; ++k) dst[m][k] = *(const LAS bf16x8*)(lds + PG8_SA(b, h) + aoff + m * 2048 + k * 1024); } while (0)
; #define PG8_LDB(dst, b, h) do { _Pragma("unroll") for (int n = 0; n < 2; ++n) _Pragma("unroll") for (int k = 0; k < 2; ++k) dst[n][k] = *(const LAS bf16x8*)(lds + PG8_SB(b, h) + boff + n * 2048 + k * 1024); } while (0)
; #define PG8_MMA(ai, bj, At, Bt) do { __builtin_amdgcn_s_setprio(1); _Pragma("unroll") for (int m = 0; m < 4; ++m) _Pragma("unroll") for (int n = 0; n < 2; ++n) _Pragma("unroll") for (int k = 0; k < 2; ++k) \
;         acc[ai][bj][m][n] = __builtin_amdgcn_mfma_f32_16x16x32_bf16(Bt[n][k], At[m][k], acc[ai][bj][m][n], 0, 0, 0); __builtin_amdgcn_s_setprio(0); } while (0)
; #define PG8_WAIT_V(n) asm volatile("s_waitcnt vmcnt(" #n ")" ::: "memory")
; #define PG8_WAIT_L(n) asm volatile("s_waitcnt lgkmcnt(" #n ")" ::: "memory")
; #define PG8_BAR __builtin_amdgcn_s_barrier()
; #define PG8_SCHED __builtin_amdgcn_sched_barrier(0)
; template <class Epi, class Sched, bool ALIGN_EPI>
; __device__ __forceinline__ void gemm_phase(LAS unsigned char* lds, const Gemm g, const Sched& S, const Epi& E) {
;     ...
;             PG8_LDB(B0, 1, 0); PG8_LDB(B1, 1, 1); PG8_SCHED; PG8_LDA(At, 1, 0); PG8_STAGE(PG8_SA(0, 1), a2 + hstepA, voffA);
;             PG8_WAIT_V(8); PG8_WAIT_L(0); PG8_BAR; PG8_MMA(0, 0, At, B0); PG8_MMA(0, 1, At, B1); PG8_BAR; PG8_SCHED;
;             PG8_LDA(At, 1, 1); PG8_STAGE(PG8_SB(1, 0), b3, voffB); PG8_STAGE(PG8_SB(1, 1), b3 + hstepB, voffB); PG8_STAGE(PG8_SA(1, 0), a3, voffA);
;             PG8_WAIT_V(8); PG8_WAIT_L(0); PG8_BAR; PG8_MMA(1, 0, At, B0); PG8_MMA(1, 1, At, B1); PG8_BAR; PG8_SCHED;
;         }
	s_setprio 0
	ds_read_b128 v[110:113], v209
	ds_read_b128 v[126:129], v209 offset:1024
	ds_read_b128 v[130:133], v209 offset:2048
	ds_read_b128 v[142:145], v209 offset:3072
	ds_read_b128 v[146:149], v210
	ds_read_b128 v[150:153], v210 offset:1024
	ds_read_b128 v[154:157], v210 offset:2048
	ds_read_b128 v[158:161], v210 offset:3072
	ds_read_b128 v[162:165], v208 offset:32768
	ds_read_b128 v[166:169], v208 offset:33792
	ds_read_b128 v[170:173], v208 offset:34816
	ds_read_b128 v[174:177], v208 offset:35840
	ds_read_b128 v[188:191], v208 offset:36864
	ds_read_b128 v[192:195], v208 offset:37888
	ds_read_b128 v[196:199], v208 offset:38912
	ds_read_b128 v[212:215], v208 offset:39936
	s_add_u32 s34, s34, 0x160000
	s_addc_u32 s35, s35, 0
	s_mov_b32 m0, s44
	s_nop 0
	global_load_lds_dwordx4 v179, s[34:35]
	s_nop 0
	s_mov_b32 m0, s45
	s_nop 0
	global_load_lds_dwordx4 v201, s[34:35]
	s_waitcnt vmcnt(8)
	s_waitcnt lgkmcnt(0)
	s_setprio 1
	s_barrier
	v_mfma_f32_16x16x32_bf16 v[138:141], v[110:113], v[162:165], v[138:141]
	v_mfma_f32_16x16x32_bf16 v[134:137], v[130:133], v[162:165], v[134:137]
	v_mfma_f32_16x16x32_bf16 v[114:117], v[110:113], v[170:173], v[114:117]
	v_mfma_f32_16x16x32_bf16 v[106:109], v[130:133], v[170:173], v[106:109]
	v_mfma_f32_16x16x32_bf16 v[94:97], v[110:113], v[188:191], v[94:97]
	v_mfma_f32_16x16x32_bf16 v[90:93], v[130:133], v[188:191], v[90:93]
	v_mfma_f32_16x16x32_bf16 v[78:81], v[110:113], v[196:199], v[78:81]
	v_mfma_f32_16x16x32_bf16 v[74:77], v[130:133], v[196:199], v[74:77]
	v_mfma_f32_16x16x32_bf16 v[138:141], v[126:129], v[166:169], v[138:141]
	v_mfma_f32_16x16x32_bf16 v[134:137], v[142:145], v[166:169], v[134:137]
	v_mfma_f32_16x16x32_bf16 v[114:117], v[126:129], v[174:177], v[114:117]
	v_mfma_f32_16x16x32_bf16 v[106:109], v[142:145], v[174:177], v[106:109]
	v_mfma_f32_16x16x32_bf16 v[94:97], v[126:129], v[192:195], v[94:97]
	v_mfma_f32_16x16x32_bf16 v[90:93], v[142:145], v[192:195], v[90:93]
	v_mfma_f32_16x16x32_bf16 v[78:81], v[126:129], v[212:215], v[78:81]
	v_mfma_f32_16x16x32_bf16 v[74:77], v[142:145], v[212:215], v[74:77]
	v_mfma_f32_16x16x32_bf16 v[122:125], v[146:149], v[162:165], v[122:125]
	v_mfma_f32_16x16x32_bf16 v[118:121], v[154:157], v[162:165], v[118:121]
	v_mfma_f32_16x16x32_bf16 v[102:105], v[146:149], v[170:173], v[102:105]
	v_mfma_f32_16x16x32_bf16 v[98:101], v[154:157], v[170:173], v[98:101]
	v_mfma_f32_16x16x32_bf16 v[86:89], v[146:149], v[188:191], v[86:89]
	v_mfma_f32_16x16x32_bf16 v[82:85], v[154:157], v[188:191], v[82:85]
	v_mfma_f32_16x16x32_bf16 v[70:73], v[146:149], v[196:199], v[70:73]
	v_mfma_f32_16x16x32_bf16 v[66:69], v[154:157], v[196:199], v[66:69]
	v_mfma_f32_16x16x32_bf16 v[122:125], v[150:153], v[166:169], v[122:125]
	v_mfma_f32_16x16x32_bf16 v[118:121], v[158:161], v[166:169], v[118:121]
	v_mfma_f32_16x16x32_bf16 v[102:105], v[150:153], v[174:177], v[102:105]
	v_mfma_f32_16x16x32_bf16 v[98:101], v[158:161], v[174:177], v[98:101]
	v_mfma_f32_16x16x32_bf16 v[86:89], v[150:153], v[192:195], v[86:89]
	v_mfma_f32_16x16x32_bf16 v[82:85], v[158:161], v[192:195], v[82:85]
	v_mfma_f32_16x16x32_bf16 v[70:73], v[150:153], v[212:215], v[70:73]
	v_mfma_f32_16x16x32_bf16 v[66:69], v[158:161], v[212:215], v[66:69]
	s_barrier
	s_setprio 0
	ds_read_b128 v[162:165], v208 offset:49152
	ds_read_b128 v[166:169], v208 offset:50176
	ds_read_b128 v[170:173], v208 offset:51200
	ds_read_b128 v[174:177], v208 offset:52224
	ds_read_b128 v[188:191], v208 offset:53248
	ds_read_b128 v[192:195], v208 offset:54272
	ds_read_b128 v[196:199], v208 offset:55296
	ds_read_b128 v[212:215], v208 offset:56320
	s_add_u32 s34, s30, 0x80
	s_addc_u32 s35, s31, 0
	s_mov_b32 m0, s46
	s_nop 0
	global_load_lds_dwordx4 v200, s[34:35]
	s_add_u32 s30, s30, 0x160080
	s_mov_b32 m0, s47
	s_nop 0
	global_load_lds_dwordx4 v203, s[34:35]
	s_addc_u32 s31, s31, 0
	s_mov_b32 m0, s50
	s_nop 0
	global_load_lds_dwordx4 v200, s[30:31]
	s_nop 0
	s_mov_b32 m0, s51
	s_nop 0
	global_load_lds_dwordx4 v203, s[30:31]
	s_mov_b32 m0, s48
	s_nop 0
	global_load_lds_dwordx4 v179, s[28:29]
	s_nop 0
	s_mov_b32 m0, s49
	s_nop 0
	global_load_lds_dwordx4 v201, s[28:29]
	s_waitcnt vmcnt(8)
	s_waitcnt lgkmcnt(0)
	s_setprio 1
	s_barrier
	v_mfma_f32_16x16x32_bf16 v[62:65], v[110:113], v[162:165], v[62:65]
	v_mfma_f32_16x16x32_bf16 v[58:61], v[130:133], v[162:165], v[58:61]
	v_mfma_f32_16x16x32_bf16 v[46:49], v[110:113], v[170:173], v[46:49]
	v_mfma_f32_16x16x32_bf16 v[42:45], v[130:133], v[170:173], v[42:45]
	v_mfma_f32_16x16x32_bf16 v[30:33], v[110:113], v[188:191], v[30:33]
	v_mfma_f32_16x16x32_bf16 v[26:29], v[130:133], v[188:191], v[26:29]
	v_mfma_f32_16x16x32_bf16 v[14:17], v[110:113], v[196:199], v[14:17]
	v_mfma_f32_16x16x32_bf16 v[10:13], v[130:133], v[196:199], v[10:13]
	v_mfma_f32_16x16x32_bf16 v[62:65], v[126:129], v[166:169], v[62:65]
	v_mfma_f32_16x16x32_bf16 v[58:61], v[142:145], v[166:169], v[58:61]
	v_mfma_f32_16x16x32_bf16 v[46:49], v[126:129], v[174:177], v[46:49]
	v_mfma_f32_16x16x32_bf16 v[42:45], v[142:145], v[174:177], v[42:45]
	v_mfma_f32_16x16x32_bf16 v[30:33], v[126:129], v[192:195], v[30:33]
	v_mfma_f32_16x16x32_bf16 v[26:29], v[142:145], v[192:195], v[26:29]
	v_mfma_f32_16x16x32_bf16 v[14:17], v[126:129], v[212:215], v[14:17]
	v_mfma_f32_16x16x32_bf16 v[10:13], v[142:145], v[212:215], v[10:13]
	v_mfma_f32_16x16x32_bf16 v[54:57], v[146:149], v[162:165], v[54:57]
	v_mfma_f32_16x16x32_bf16 v[50:53], v[154:157], v[162:165], v[50:53]
	v_mfma_f32_16x16x32_bf16 v[38:41], v[146:149], v[170:173], v[38:41]
	v_mfma_f32_16x16x32_bf16 v[34:37], v[154:157], v[170:173], v[34:37]
	v_mfma_f32_16x16x32_bf16 v[22:25], v[146:149], v[188:191], v[22:25]
	v_mfma_f32_16x16x32_bf16 v[18:21], v[154:157], v[188:191], v[18:21]
	v_mfma_f32_16x16x32_bf16 v[6:9], v[146:149], v[196:199], v[6:9]
	v_mfma_f32_16x16x32_bf16 v[2:5], v[154:157], v[196:199], v[2:5]
	v_mfma_f32_16x16x32_bf16 v[54:57], v[150:153], v[166:169], v[54:57]
	v_mfma_f32_16x16x32_bf16 v[50:53], v[158:161], v[166:169], v[50:53]
	v_mfma_f32_16x16x32_bf16 v[38:41], v[150:153], v[174:177], v[38:41]
	v_mfma_f32_16x16x32_bf16 v[34:37], v[158:161], v[174:177], v[34:37]
	v_mfma_f32_16x16x32_bf16 v[22:25], v[150:153], v[192:195], v[22:25]
	v_mfma_f32_16x16x32_bf16 v[18:21], v[158:161], v[192:195], v[18:21]
	v_mfma_f32_16x16x32_bf16 v[6:9], v[150:153], v[212:215], v[6:9]
	v_mfma_f32_16x16x32_bf16 v[2:5], v[158:161], v[212:215], v[2:5]
	s_barrier
	s_setprio 0
	s_add_i32 s58, s58, 2
	s_add_u32 s6, s6, 0x100
	s_addc_u32 s7, s7, 0
	s_add_u32 s56, s56, 0x100
	s_addc_u32 s57, s57, 0
	s_add_u32 s4, s4, 0x100
	s_addc_u32 s5, s5, 0
	s_cmpk_gt_u32 s58, 0x55
	s_cbranch_scc0 .LBB0_1317
	s_and_b64 vcc, exec, s[18:19]
	s_cbranch_vccz .LBB0_1320
	s_barrier

; #define PG8_STAGE(bufoff, gbase, voff) do { _Pragma("unroll") for (int _i = 0; _i < 2; ++_i) { unsigned keep_; \
;         asm volatile("s_mov_b32 %0, m0\n\ts_mov_b32 m0, %3\n\ts_nop 0\n\tglobal_load_lds_dwordx4 %1, %2\n\ts_mov_b32 m0, %0" \
;             : "=&s"(keep_) : "v"((voff)[_i]), "s"((const void*)(gbase)), "s"(ldsb0 + (unsigned)(bufoff) + (unsigned)(_i * 8192)) : "memory"); } } while (0)
; #define PG8_LDA(dst, b, h) do { _Pragma("unroll") for (int m = 0; m < 4; ++m) _Pragma("unroll") for (int k = 0; k < 2; ++k) dst[m][k] = *(const LAS bf16x8*)(lds + PG8_SA(b, h) + aoff + m * 2048 + k * 1024); } while (0)
; #define PG8_LDB(dst, b, h) do { _Pragma("unroll") for (int n = 0; n < 2; ++n) _Pragma("unroll") for (int k = 0; k < 2; ++k) dst[n][k] = *(const LAS bf16x8*)(lds + PG8_SB(b, h) + boff + n * 2048 + k * 1024); } while (0)
; #define PG8_MMA(ai, bj, At, Bt) do { __builtin_amdgcn_s_setprio(1); _Pragma("unroll") for (int m = 0; m < 4; ++m) _Pragma("unroll") for (int n = 0; n < 2; ++n) _Pragma("unroll") for (int k = 0; k < 2; ++k) \
;         acc[ai][bj][m][n] = __builtin_amdgcn_mfma_f32_16x16x32_bf16(Bt[n][k], At[m][k], acc[ai][bj][m][n], 0, 0, 0); __builtin_amdgcn_s_setprio(0); } while (0)
; #define PG8_WAIT_V(n) asm volatile("s_waitcnt vmcnt(" #n ")" ::: "memory")
; #define PG8_WAIT_L(n) asm volatile("s_waitcnt lgkmcnt(" #n ")" ::: "memory")
; template <class Epi, class Sched, bool ALIGN_EPI>
; __device__ __forceinline__ void gemm_phase(LAS unsigned char* lds, const Gemm g, const Sched& S, const Epi& E) {
;     ...
;             const bool last = (t == nt - 2);
;             const char* a1 = cA + (size_t)(t + 1) * kstep;
;             const char* a2 = last ? nA : cA + (size_t)(t + 2) * kstep; const char* b2 = last ? nB : cB + (size_t)(t + 2) * kstep;
;             const char* a3 = a2 + kstep; const char* b3 = b2 + kstep;
;             PG8_LDB(B0, 0, 0); PG8_LDB(B1, 0, 1); PG8_SCHED; PG8_LDA(At, 0, 0); PG8_STAGE(PG8_SA(1, 1), a1 + hstepA, voffA);
;             PG8_WAIT_V(8); PG8_WAIT_L(0); PG8_BAR; PG8_MMA(0, 0, At, B0); PG8_MMA(0, 1, At, B1); PG8_BAR; PG8_SCHED;
;             PG8_LDA(At, 0, 1); PG8_STAGE(PG8_SB(0, 0), b2, voffB); PG8_STAGE(PG8_SB(0, 1), b2 + hstepB, voffB); PG8_STAGE(PG8_SA(0, 0), a2, voffA);
;             PG8_WAIT_V(8); PG8_WAIT_L(0); PG8_BAR; PG8_MMA(1, 0, At, B0); PG8_MMA(1, 1, At, B1); PG8_BAR; PG8_SCHED;
.LBB0_1409:
	ds_read_b128 v[132:135], v146
	ds_read_b128 v[136:139], v146 offset:1024
	ds_read_b128 v[160:163], v146 offset:2048
	ds_read_b128 v[164:167], v146 offset:3072
	ds_read_b128 v[168:171], v147
	ds_read_b128 v[172:175], v147 offset:1024
	ds_read_b128 v[180:183], v147 offset:2048
	ds_read_b128 v[184:187], v147 offset:3072
	s_add_u32 s8, s4, 0x100
	s_addc_u32 s9, s5, 0
	s_cmp_eq_u32 s39, 28
	s_cselect_b32 s46, s3, s8
	s_cselect_b32 s47, s2, s9
	s_cselect_b32 s12, s7, s23
	s_cselect_b32 s13, s6, s37
	s_add_u32 s10, s46, 0x80
	s_addc_u32 s11, s47, 0
	ds_read_b128 v[188:191], v148
	ds_read_b128 v[192:195], v148 offset:1024
	ds_read_b128 v[196:199], v148 offset:2048
	ds_read_b128 v[204:207], v148 offset:3072
	ds_read_b128 v[208:211], v148 offset:4096
	ds_read_b128 v[212:215], v148 offset:5120
	ds_read_b128 v[216:219], v148 offset:6144
	ds_read_b128 v[220:223], v148 offset:7168
	s_add_u32 s4, s4, 0x80080
	s_addc_u32 s5, s5, 0
	s_mov_b32 m0, s68
	s_nop 0
	global_load_lds_dwordx4 v140, s[4:5]
	s_nop 0
	s_mov_b32 m0, s69
	s_nop 0
	global_load_lds_dwordx4 v142, s[4:5]
	s_waitcnt vmcnt(8)
	s_waitcnt lgkmcnt(0)
	s_setprio 1
	s_barrier
	v_mfma_f32_16x16x32_bf16 v[126:129], v[132:135], v[188:191], v[126:129]
	v_mfma_f32_16x16x32_bf16 v[122:125], v[160:163], v[188:191], v[122:125]
	v_mfma_f32_16x16x32_bf16 v[110:113], v[132:135], v[196:199], v[110:113]
	v_mfma_f32_16x16x32_bf16 v[106:109], v[160:163], v[196:199], v[106:109]
	v_mfma_f32_16x16x32_bf16 v[94:97], v[132:135], v[208:211], v[94:97]
	v_mfma_f32_16x16x32_bf16 v[90:93], v[160:163], v[208:211], v[90:93]
	v_mfma_f32_16x16x32_bf16 v[78:81], v[132:135], v[216:219], v[78:81]
	v_mfma_f32_16x16x32_bf16 v[74:77], v[160:163], v[216:219], v[74:77]
	v_mfma_f32_16x16x32_bf16 v[126:129], v[136:139], v[192:195], v[126:129]
	v_mfma_f32_16x16x32_bf16 v[122:125], v[164:167], v[192:195], v[122:125]
	v_mfma_f32_16x16x32_bf16 v[110:113], v[136:139], v[204:207], v[110:113]
	v_mfma_f32_16x16x32_bf16 v[106:109], v[164:167], v[204:207], v[106:109]
	v_mfma_f32_16x16x32_bf16 v[94:97], v[136:139], v[212:215], v[94:97]
	v_mfma_f32_16x16x32_bf16 v[90:93], v[164:167], v[212:215], v[90:93]
	v_mfma_f32_16x16x32_bf16 v[78:81], v[136:139], v[220:223], v[78:81]
	v_mfma_f32_16x16x32_bf16 v[74:77], v[164:167], v[220:223], v[74:77]
	v_mfma_f32_16x16x32_bf16 v[118:121], v[168:171], v[188:191], v[118:121]
	v_mfma_f32_16x16x32_bf16 v[114:117], v[180:183], v[188:191], v[114:117]
	v_mfma_f32_16x16x32_bf16 v[102:105], v[168:171], v[196:199], v[102:105]
	v_mfma_f32_16x16x32_bf16 v[98:101], v[180:183], v[196:199], v[98:101]
	v_mfma_f32_16x16x32_bf16 v[86:89], v[168:171], v[208:211], v[86:89]
	v_mfma_f32_16x16x32_bf16 v[82:85], v[180:183], v[208:211], v[82:85]
	v_mfma_f32_16x16x32_bf16 v[70:73], v[168:171], v[216:219], v[70:73]
	v_mfma_f32_16x16x32_bf16 v[66:69], v[180:183], v[216:219], v[66:69]
	v_mfma_f32_16x16x32_bf16 v[118:121], v[172:175], v[192:195], v[118:121]
	v_mfma_f32_16x16x32_bf16 v[114:117], v[184:187], v[192:195], v[114:117]
	v_mfma_f32_16x16x32_bf16 v[102:105], v[172:175], v[204:207], v[102:105]
	v_mfma_f32_16x16x32_bf16 v[98:101], v[184:187], v[204:207], v[98:101]
	v_mfma_f32_16x16x32_bf16 v[86:89], v[172:175], v[212:215], v[86:89]
	v_mfma_f32_16x16x32_bf16 v[82:85], v[184:187], v[212:215], v[82:85]
	v_mfma_f32_16x16x32_bf16 v[70:73], v[172:175], v[220:223], v[70:73]
	v_mfma_f32_16x16x32_bf16 v[66:69], v[184:187], v[220:223], v[66:69]
	s_barrier
	s_setprio 0
	ds_read_b128 v[188:191], v148 offset:16384
	ds_read_b128 v[192:195], v148 offset:17408
	ds_read_b128 v[196:199], v148 offset:18432
	ds_read_b128 v[204:207], v148 offset:19456
	ds_read_b128 v[208:211], v148 offset:20480
	ds_read_b128 v[212:215], v148 offset:21504
	ds_read_b128 v[216:219], v148 offset:22528
	ds_read_b128 v[220:223], v148 offset:23552
	s_mov_b32 m0, s53
	s_nop 0
	global_load_lds_dwordx4 v141, s[12:13]
	s_nop 0
	s_mov_b32 m0, s54
	s_nop 0
	global_load_lds_dwordx4 v143, s[12:13]
	s_add_u32 s4, s12, 0x80000
	s_addc_u32 s5, s13, 0
	s_mov_b32 m0, s55
	s_nop 0
	global_load_lds_dwordx4 v141, s[4:5]
	s_nop 0
	s_mov_b32 m0, s56
	s_nop 0
	global_load_lds_dwordx4 v143, s[4:5]
	s_mov_b32 m0, s52
	s_nop 0
	global_load_lds_dwordx4 v140, s[46:47]
	s_nop 0
	s_mov_b32 m0, s57
	s_nop 0
	global_load_lds_dwordx4 v142, s[46:47]
	s_waitcnt vmcnt(8)
	s_waitcnt lgkmcnt(0)
	s_setprio 1
	s_barrier
	v_mfma_f32_16x16x32_bf16 v[62:65], v[132:135], v[188:191], v[62:65]
	v_mfma_f32_16x16x32_bf16 v[58:61], v[160:163], v[188:191], v[58:61]
	v_mfma_f32_16x16x32_bf16 v[46:49], v[132:135], v[196:199], v[46:49]
	v_mfma_f32_16x16x32_bf16 v[42:45], v[160:163], v[196:199], v[42:45]
	v_mfma_f32_16x16x32_bf16 v[30:33], v[132:135], v[208:211], v[30:33]
	v_mfma_f32_16x16x32_bf16 v[26:29], v[160:163], v[208:211], v[26:29]
	v_mfma_f32_16x16x32_bf16 v[14:17], v[132:135], v[216:219], v[14:17]
	v_mfma_f32_16x16x32_bf16 v[10:13], v[160:163], v[216:219], v[10:13]
	v_mfma_f32_16x16x32_bf16 v[62:65], v[136:139], v[192:195], v[62:65]
	v_mfma_f32_16x16x32_bf16 v[58:61], v[164:167], v[192:195], v[58:61]
	v_mfma_f32_16x16x32_bf16 v[46:49], v[136:139], v[204:207], v[46:49]
	v_mfma_f32_16x16x32_bf16 v[42:45], v[164:167], v[204:207], v[42:45]
	v_mfma_f32_16x16x32_bf16 v[30:33], v[136:139], v[212:215], v[30:33]
	v_mfma_f32_16x16x32_bf16 v[26:29], v[164:167], v[212:215], v[26:29]
	v_mfma_f32_16x16x32_bf16 v[14:17], v[136:139], v[220:223], v[14:17]
	v_mfma_f32_16x16x32_bf16 v[10:13], v[164:167], v[220:223], v[10:13]
	v_mfma_f32_16x16x32_bf16 v[54:57], v[168:171], v[188:191], v[54:57]
	v_mfma_f32_16x16x32_bf16 v[50:53], v[180:183], v[188:191], v[50:53]
	v_mfma_f32_16x16x32_bf16 v[38:41], v[168:171], v[196:199], v[38:41]
	v_mfma_f32_16x16x32_bf16 v[34:37], v[180:183], v[196:199], v[34:37]
	v_mfma_f32_16x16x32_bf16 v[22:25], v[168:171], v[208:211], v[22:25]
	v_mfma_f32_16x16x32_bf16 v[18:21], v[180:183], v[208:211], v[18:21]
	v_mfma_f32_16x16x32_bf16 v[6:9], v[168:171], v[216:219], v[6:9]
	v_mfma_f32_16x16x32_bf16 v[2:5], v[180:183], v[216:219], v[2:5]
	v_mfma_f32_16x16x32_bf16 v[54:57], v[172:175], v[192:195], v[54:57]
	v_mfma_f32_16x16x32_bf16 v[50:53], v[184:187], v[192:195], v[50:53]
	v_mfma_f32_16x16x32_bf16 v[38:41], v[172:175], v[204:207], v[38:41]
	v_mfma_f32_16x16x32_bf16 v[34:37], v[184:187], v[204:207], v[34:37]
	v_mfma_f32_16x16x32_bf16 v[22:25], v[172:175], v[212:215], v[22:25]
	v_mfma_f32_16x16x32_bf16 v[18:21], v[184:187], v[212:215], v[18:21]
	v_mfma_f32_16x16x32_bf16 v[6:9], v[172:175], v[220:223], v[6:9]
	v_mfma_f32_16x16x32_bf16 v[2:5], v[184:187], v[220:223], v[2:5]
	s_barrier
; #define PG8_STAGE(bufoff, gbase, voff) do { _Pragma("unroll") for (int _i = 0; _i < 2; ++_i) { unsigned keep_; \
;         asm volatile("s_mov_b32 %0, m0\n\ts_mov_b32 m0, %3\n\ts_nop 0\n\tglobal_load_lds_dwordx4 %1, %2\n\ts_mov_b32 m0, %0" \
;             : "=&s"(keep_) : "v"((voff)[_i]), "s"((const void*)(gbase)), "s"(ldsb0 + (unsigned)(bufoff) + (unsigned)(_i * 8192)) : "memory"); } } while (0)
; #define PG8_LDA(dst, b, h) do { _Pragma("unroll") for (int m = 0; m < 4; ++m) _Pragma("unroll") for (int k = 0; k < 2; ++k) dst[m][k] = *(const LAS bf16x8*)(lds + PG8_SA(b, h) + aoff + m * 2048 + k * 1024); } while (0)
; #define PG8_LDB(dst, b, h) do { _Pragma("unroll") for (int n = 0; n < 2; ++n) _Pragma("unroll") for (int k = 0; k < 2; ++k) dst[n][k] = *(const LAS bf16x8*)(lds + PG8_SB(b, h) + boff + n * 2048 + k * 1024); } while (0)
; #define PG8_MMA(ai, bj, At, Bt) do { __builtin_amdgcn_s_setprio(1); _Pragma("unroll") for (int m = 0; m < 4; ++m) _Pragma("unroll") for (int n = 0; n < 2; ++n) _Pragma("unroll") for (int k = 0; k < 2; ++k) \
;         acc[ai][bj][m][n] = __builtin_amdgcn_mfma_f32_16x16x32_bf16(Bt[n][k], At[m][k], acc[ai][bj][m][n], 0, 0, 0); __builtin_amdgcn_s_setprio(0); } while (0)
; #define PG8_WAIT_V(n) asm volatile("s_waitcnt vmcnt(" #n ")" ::: "memory")
; #define PG8_WAIT_L(n) asm volatile("s_waitcnt lgkmcnt(" #n ")" ::: "memory")
; #define PG8_BAR __builtin_amdgcn_s_barrier()
; #define PG8_SCHED __builtin_amdgcn_sched_barrier(0)
; template <class Epi, class Sched, bool ALIGN_EPI>
; __device__ __forceinline__ void gemm_phase(LAS unsigned char* lds, const Gemm g, const Sched& S, const Epi& E) {
;     ...
;             PG8_LDB(B0, 1, 0); PG8_LDB(B1, 1, 1); PG8_SCHED; PG8_LDA(At, 1, 0); PG8_STAGE(PG8_SA(0, 1), a2 + hstepA, voffA);
;             PG8_WAIT_V(8); PG8_WAIT_L(0); PG8_BAR; PG8_MMA(0, 0, At, B0); PG8_MMA(0, 1, At, B1); PG8_BAR; PG8_SCHED;
;             PG8_LDA(At, 1, 1); PG8_STAGE(PG8_SB(1, 0), b3, voffB); PG8_STAGE(PG8_SB(1, 1), b3 + hstepB, voffB); PG8_STAGE(PG8_SA(1, 0), a3, voffA);
;             PG8_WAIT_V(8); PG8_WAIT_L(0); PG8_BAR; PG8_MMA(1, 0, At, B0); PG8_MMA(1, 1, At, B1); PG8_BAR; PG8_SCHED;
;         }
	s_setprio 0
	ds_read_b128 v[132:135], v149
	ds_read_b128 v[136:139], v149 offset:1024
	ds_read_b128 v[160:163], v149 offset:2048
	ds_read_b128 v[164:167], v149 offset:3072
	ds_read_b128 v[168:171], v150
	ds_read_b128 v[172:175], v150 offset:1024
	ds_read_b128 v[180:183], v150 offset:2048
	ds_read_b128 v[184:187], v150 offset:3072
	ds_read_b128 v[188:191], v148 offset:32768
	ds_read_b128 v[192:195], v148 offset:33792
	ds_read_b128 v[196:199], v148 offset:34816
	ds_read_b128 v[204:207], v148 offset:35840
	ds_read_b128 v[208:211], v148 offset:36864
	ds_read_b128 v[212:215], v148 offset:37888
	ds_read_b128 v[216:219], v148 offset:38912
	ds_read_b128 v[220:223], v148 offset:39936
	s_add_u32 s4, s46, 0x80000
	s_addc_u32 s5, s47, 0
	s_mov_b32 m0, s59
	s_nop 0
	global_load_lds_dwordx4 v140, s[4:5]
	s_nop 0
	s_mov_b32 m0, s61
	s_nop 0
	global_load_lds_dwordx4 v142, s[4:5]
	s_waitcnt vmcnt(8)
	s_waitcnt lgkmcnt(0)
	s_setprio 1
	s_barrier
	v_mfma_f32_16x16x32_bf16 v[126:129], v[132:135], v[188:191], v[126:129]
	v_mfma_f32_16x16x32_bf16 v[122:125], v[160:163], v[188:191], v[122:125]
	v_mfma_f32_16x16x32_bf16 v[110:113], v[132:135], v[196:199], v[110:113]
	v_mfma_f32_16x16x32_bf16 v[106:109], v[160:163], v[196:199], v[106:109]
	v_mfma_f32_16x16x32_bf16 v[94:97], v[132:135], v[208:211], v[94:97]
	v_mfma_f32_16x16x32_bf16 v[90:93], v[160:163], v[208:211], v[90:93]
	v_mfma_f32_16x16x32_bf16 v[78:81], v[132:135], v[216:219], v[78:81]
	v_mfma_f32_16x16x32_bf16 v[74:77], v[160:163], v[216:219], v[74:77]
	v_mfma_f32_16x16x32_bf16 v[126:129], v[136:139], v[192:195], v[126:129]
	v_mfma_f32_16x16x32_bf16 v[122:125], v[164:167], v[192:195], v[122:125]
	v_mfma_f32_16x16x32_bf16 v[110:113], v[136:139], v[204:207], v[110:113]
	v_mfma_f32_16x16x32_bf16 v[106:109], v[164:167], v[204:207], v[106:109]
	v_mfma_f32_16x16x32_bf16 v[94:97], v[136:139], v[212:215], v[94:97]
	v_mfma_f32_16x16x32_bf16 v[90:93], v[164:167], v[212:215], v[90:93]
	v_mfma_f32_16x16x32_bf16 v[78:81], v[136:139], v[220:223], v[78:81]
	v_mfma_f32_16x16x32_bf16 v[74:77], v[164:167], v[220:223], v[74:77]
	v_mfma_f32_16x16x32_bf16 v[118:121], v[168:171], v[188:191], v[118:121]
	v_mfma_f32_16x16x32_bf16 v[114:117], v[180:183], v[188:191], v[114:117]
	v_mfma_f32_16x16x32_bf16 v[102:105], v[168:171], v[196:199], v[102:105]
	v_mfma_f32_16x16x32_bf16 v[98:101], v[180:183], v[196:199], v[98:101]
	v_mfma_f32_16x16x32_bf16 v[86:89], v[168:171], v[208:211], v[86:89]
	v_mfma_f32_16x16x32_bf16 v[82:85], v[180:183], v[208:211], v[82:85]
	v_mfma_f32_16x16x32_bf16 v[70:73], v[168:171], v[216:219], v[70:73]
	v_mfma_f32_16x16x32_bf16 v[66:69], v[180:183], v[216:219], v[66:69]
	v_mfma_f32_16x16x32_bf16 v[118:121], v[172:175], v[192:195], v[118:121]
	v_mfma_f32_16x16x32_bf16 v[114:117], v[184:187], v[192:195], v[114:117]
	v_mfma_f32_16x16x32_bf16 v[102:105], v[172:175], v[204:207], v[102:105]
	v_mfma_f32_16x16x32_bf16 v[98:101], v[184:187], v[204:207], v[98:101]
	v_mfma_f32_16x16x32_bf16 v[86:89], v[172:175], v[212:215], v[86:89]
	v_mfma_f32_16x16x32_bf16 v[82:85], v[184:187], v[212:215], v[82:85]
	v_mfma_f32_16x16x32_bf16 v[70:73], v[172:175], v[220:223], v[70:73]
	v_mfma_f32_16x16x32_bf16 v[66:69], v[184:187], v[220:223], v[66:69]
	s_barrier
	s_setprio 0
	ds_read_b128 v[188:191], v148 offset:49152
	ds_read_b128 v[192:195], v148 offset:50176
	ds_read_b128 v[196:199], v148 offset:51200
	ds_read_b128 v[204:207], v148 offset:52224
	ds_read_b128 v[208:211], v148 offset:53248
	ds_read_b128 v[212:215], v148 offset:54272
	ds_read_b128 v[216:219], v148 offset:55296
	ds_read_b128 v[220:223], v148 offset:56320
	s_add_u32 s4, s12, 0x80
	s_addc_u32 s5, s13, 0
	s_mov_b32 m0, s62
	s_nop 0
	global_load_lds_dwordx4 v141, s[4:5]
	s_nop 0
	s_mov_b32 m0, s63
	s_nop 0
	global_load_lds_dwordx4 v143, s[4:5]
	s_add_u32 s4, s12, 0x80080
	s_addc_u32 s5, s13, 0
	s_mov_b32 m0, s66
	s_nop 0
	global_load_lds_dwordx4 v141, s[4:5]
	s_nop 0
	s_mov_b32 m0, s67
	s_nop 0
	global_load_lds_dwordx4 v143, s[4:5]
	s_mov_b32 m0, s64
	s_nop 0
	global_load_lds_dwordx4 v140, s[10:11]
	s_nop 0
	s_mov_b32 m0, s65
	s_nop 0
	global_load_lds_dwordx4 v142, s[10:11]
	s_waitcnt vmcnt(8)
	s_waitcnt lgkmcnt(0)
	s_setprio 1
	s_barrier
	v_mfma_f32_16x16x32_bf16 v[62:65], v[132:135], v[188:191], v[62:65]
	v_mfma_f32_16x16x32_bf16 v[58:61], v[160:163], v[188:191], v[58:61]
	v_mfma_f32_16x16x32_bf16 v[46:49], v[132:135], v[196:199], v[46:49]
	v_mfma_f32_16x16x32_bf16 v[42:45], v[160:163], v[196:199], v[42:45]
	v_mfma_f32_16x16x32_bf16 v[30:33], v[132:135], v[208:211], v[30:33]
	v_mfma_f32_16x16x32_bf16 v[26:29], v[160:163], v[208:211], v[26:29]
	v_mfma_f32_16x16x32_bf16 v[14:17], v[132:135], v[216:219], v[14:17]
	v_mfma_f32_16x16x32_bf16 v[10:13], v[160:163], v[216:219], v[10:13]
	v_mfma_f32_16x16x32_bf16 v[62:65], v[136:139], v[192:195], v[62:65]
	v_mfma_f32_16x16x32_bf16 v[58:61], v[164:167], v[192:195], v[58:61]
	v_mfma_f32_16x16x32_bf16 v[46:49], v[136:139], v[204:207], v[46:49]
	v_mfma_f32_16x16x32_bf16 v[42:45], v[164:167], v[204:207], v[42:45]
	v_mfma_f32_16x16x32_bf16 v[30:33], v[136:139], v[212:215], v[30:33]
	v_mfma_f32_16x16x32_bf16 v[26:29], v[164:167], v[212:215], v[26:29]
	v_mfma_f32_16x16x32_bf16 v[14:17], v[136:139], v[220:223], v[14:17]
	v_mfma_f32_16x16x32_bf16 v[10:13], v[164:167], v[220:223], v[10:13]
	v_mfma_f32_16x16x32_bf16 v[54:57], v[168:171], v[188:191], v[54:57]
	v_mfma_f32_16x16x32_bf16 v[50:53], v[180:183], v[188:191], v[50:53]
	v_mfma_f32_16x16x32_bf16 v[38:41], v[168:171], v[196:199], v[38:41]
	v_mfma_f32_16x16x32_bf16 v[34:37], v[180:183], v[196:199], v[34:37]
	v_mfma_f32_16x16x32_bf16 v[22:25], v[168:171], v[208:211], v[22:25]
	v_mfma_f32_16x16x32_bf16 v[18:21], v[180:183], v[208:211], v[18:21]
	v_mfma_f32_16x16x32_bf16 v[6:9], v[168:171], v[216:219], v[6:9]
	v_mfma_f32_16x16x32_bf16 v[2:5], v[180:183], v[216:219], v[2:5]
	v_mfma_f32_16x16x32_bf16 v[54:57], v[172:175], v[192:195], v[54:57]
	v_mfma_f32_16x16x32_bf16 v[50:53], v[184:187], v[192:195], v[50:53]
	v_mfma_f32_16x16x32_bf16 v[38:41], v[172:175], v[204:207], v[38:41]
	v_mfma_f32_16x16x32_bf16 v[34:37], v[184:187], v[204:207], v[34:37]
	v_mfma_f32_16x16x32_bf16 v[22:25], v[172:175], v[212:215], v[22:25]
	v_mfma_f32_16x16x32_bf16 v[18:21], v[184:187], v[212:215], v[18:21]
	v_mfma_f32_16x16x32_bf16 v[6:9], v[172:175], v[220:223], v[6:9]
	v_mfma_f32_16x16x32_bf16 v[2:5], v[184:187], v[220:223], v[2:5]
	s_barrier
	s_setprio 0
	s_add_i32 s39, s39, 2
	s_add_u32 s23, s23, 0x100
	s_addc_u32 s37, s37, 0
	s_cmp_gt_u32 s39, 29
	s_mov_b64 s[4:5], s[8:9]
	s_cbranch_scc0 .LBB0_1409
	s_and_b64 vcc, exec, s[34:35]
	s_cbranch_vccz .LBB0_1412
	s_barrier

; #define PG8_STAGE(bufoff, gbase, voff) do { _Pragma("unroll") for (int _i = 0; _i < 2; ++_i) { unsigned keep_; \
;         asm volatile("s_mov_b32 %0, m0\n\ts_mov_b32 m0, %3\n\ts_nop 0\n\tglobal_load_lds_dwordx4 %1, %2\n\ts_mov_b32 m0, %0" \
;             : "=&s"(keep_) : "v"((voff)[_i]), "s"((const void*)(gbase)), "s"(ldsb0 + (unsigned)(bufoff) + (unsigned)(_i * 8192)) : "memory"); } } while (0)
; #define PG8_LDA(dst, b, h) do { _Pragma("unroll") for (int m = 0; m < 4; ++m) _Pragma("unroll") for (int k = 0; k < 2; ++k) dst[m][k] = *(const LAS bf16x8*)(lds + PG8_SA(b, h) + aoff + m * 2048 + k * 1024); } while (0)
; #define PG8_LDB(dst, b, h) do { _Pragma("unroll") for (int n = 0; n < 2; ++n) _Pragma("unroll") for (int k = 0; k < 2; ++k) dst[n][k] = *(const LAS bf16x8*)(lds + PG8_SB(b, h) + boff + n * 2048 + k * 1024); } while (0)
; #define PG8_MMA(ai, bj, At, Bt) do { __builtin_amdgcn_s_setprio(1); _Pragma("unroll") for (int m = 0; m < 4; ++m) _Pragma("unroll") for (int n = 0; n < 2; ++n) _Pragma("unroll") for (int k = 0; k < 2; ++k) \
;         acc[ai][bj][m][n] = __builtin_amdgcn_mfma_f32_16x16x32_bf16(Bt[n][k], At[m][k], acc[ai][bj][m][n], 0, 0, 0); __builtin_amdgcn_s_setprio(0); } while (0)
; #define PG8_WAIT_V(n) asm volatile("s_waitcnt vmcnt(" #n ")" ::: "memory")
; #define PG8_WAIT_L(n) asm volatile("s_waitcnt lgkmcnt(" #n ")" ::: "memory")
; template <class Epi, class Sched, bool ALIGN_EPI>
; __device__ __forceinline__ void gemm_phase(LAS unsigned char* lds, const Gemm g, const Sched& S, const Epi& E) {
;     ...
;             const bool last = (t == nt - 2);
;             const char* a1 = cA + (size_t)(t + 1) * kstep;
;             const char* a2 = last ? nA : cA + (size_t)(t + 2) * kstep; const char* b2 = last ? nB : cB + (size_t)(t + 2) * kstep;
;             const char* a3 = a2 + kstep; const char* b3 = b2 + kstep;
;             PG8_LDB(B0, 0, 0); PG8_LDB(B1, 0, 1); PG8_SCHED; PG8_LDA(At, 0, 0); PG8_STAGE(PG8_SA(1, 1), a1 + hstepA, voffA);
;             PG8_WAIT_V(8); PG8_WAIT_L(0); PG8_BAR; PG8_MMA(0, 0, At, B0); PG8_MMA(0, 1, At, B1); PG8_BAR; PG8_SCHED;
;             PG8_LDA(At, 0, 1); PG8_STAGE(PG8_SB(0, 0), b2, voffB); PG8_STAGE(PG8_SB(0, 1), b2 + hstepB, voffB); PG8_STAGE(PG8_SA(0, 0), a2, voffA);
;             PG8_WAIT_V(8); PG8_WAIT_L(0); PG8_BAR; PG8_MMA(1, 0, At, B0); PG8_MMA(1, 1, At, B1); PG8_BAR; PG8_SCHED;
.LBB0_1994:
	ds_read_b128 v[110:113], v206
	ds_read_b128 v[126:129], v206 offset:1024
	ds_read_b128 v[130:133], v206 offset:2048
	ds_read_b128 v[142:145], v206 offset:3072
	ds_read_b128 v[146:149], v207
	ds_read_b128 v[150:153], v207 offset:1024
	ds_read_b128 v[154:157], v207 offset:2048
	ds_read_b128 v[158:161], v207 offset:3072
	s_cmp_eq_u32 s59, 28
	s_cselect_b32 s34, s5, s19
	s_cselect_b32 s35, s3, s21
	s_cselect_b32 s30, s7, s57
	s_cselect_b32 s31, s6, s58
	s_add_u32 s28, s34, 0x80
	s_addc_u32 s29, s35, 0
	ds_read_b128 v[162:165], v208
	ds_read_b128 v[166:169], v208 offset:1024
	ds_read_b128 v[170:173], v208 offset:2048
	ds_read_b128 v[174:177], v208 offset:3072
	ds_read_b128 v[188:191], v208 offset:4096
	ds_read_b128 v[192:195], v208 offset:5120
	ds_read_b128 v[196:199], v208 offset:6144
	ds_read_b128 v[212:215], v208 offset:7168
	s_mov_b32 m0, s55
	s_nop 0
	global_load_lds_dwordx4 v179, s[26:27]
	s_nop 0
	s_mov_b32 m0, s56
	s_nop 0
	global_load_lds_dwordx4 v201, s[26:27]
	s_waitcnt vmcnt(8)
	s_waitcnt lgkmcnt(0)
	s_setprio 1
	s_barrier
	v_mfma_f32_16x16x32_bf16 v[138:141], v[110:113], v[162:165], v[138:141]
	v_mfma_f32_16x16x32_bf16 v[134:137], v[130:133], v[162:165], v[134:137]
	v_mfma_f32_16x16x32_bf16 v[114:117], v[110:113], v[170:173], v[114:117]
	v_mfma_f32_16x16x32_bf16 v[106:109], v[130:133], v[170:173], v[106:109]
	v_mfma_f32_16x16x32_bf16 v[94:97], v[110:113], v[188:191], v[94:97]
	v_mfma_f32_16x16x32_bf16 v[90:93], v[130:133], v[188:191], v[90:93]
	v_mfma_f32_16x16x32_bf16 v[78:81], v[110:113], v[196:199], v[78:81]
	v_mfma_f32_16x16x32_bf16 v[74:77], v[130:133], v[196:199], v[74:77]
	v_mfma_f32_16x16x32_bf16 v[138:141], v[126:129], v[166:169], v[138:141]
	v_mfma_f32_16x16x32_bf16 v[134:137], v[142:145], v[166:169], v[134:137]
	v_mfma_f32_16x16x32_bf16 v[114:117], v[126:129], v[174:177], v[114:117]
	v_mfma_f32_16x16x32_bf16 v[106:109], v[142:145], v[174:177], v[106:109]
	v_mfma_f32_16x16x32_bf16 v[94:97], v[126:129], v[192:195], v[94:97]
	v_mfma_f32_16x16x32_bf16 v[90:93], v[142:145], v[192:195], v[90:93]
	v_mfma_f32_16x16x32_bf16 v[78:81], v[126:129], v[212:215], v[78:81]
	v_mfma_f32_16x16x32_bf16 v[74:77], v[142:145], v[212:215], v[74:77]
	v_mfma_f32_16x16x32_bf16 v[122:125], v[146:149], v[162:165], v[122:125]
	v_mfma_f32_16x16x32_bf16 v[118:121], v[154:157], v[162:165], v[118:121]
	v_mfma_f32_16x16x32_bf16 v[102:105], v[146:149], v[170:173], v[102:105]
	v_mfma_f32_16x16x32_bf16 v[98:101], v[154:157], v[170:173], v[98:101]
	v_mfma_f32_16x16x32_bf16 v[86:89], v[146:149], v[188:191], v[86:89]
	v_mfma_f32_16x16x32_bf16 v[82:85], v[154:157], v[188:191], v[82:85]
	v_mfma_f32_16x16x32_bf16 v[70:73], v[146:149], v[196:199], v[70:73]
	v_mfma_f32_16x16x32_bf16 v[66:69], v[154:157], v[196:199], v[66:69]
	v_mfma_f32_16x16x32_bf16 v[122:125], v[150:153], v[166:169], v[122:125]
	v_mfma_f32_16x16x32_bf16 v[118:121], v[158:161], v[166:169], v[118:121]
	v_mfma_f32_16x16x32_bf16 v[102:105], v[150:153], v[174:177], v[102:105]
	v_mfma_f32_16x16x32_bf16 v[98:101], v[158:161], v[174:177], v[98:101]
	v_mfma_f32_16x16x32_bf16 v[86:89], v[150:153], v[192:195], v[86:89]
	v_mfma_f32_16x16x32_bf16 v[82:85], v[158:161], v[192:195], v[82:85]
	v_mfma_f32_16x16x32_bf16 v[70:73], v[150:153], v[212:215], v[70:73]
	v_mfma_f32_16x16x32_bf16 v[66:69], v[158:161], v[212:215], v[66:69]
	s_barrier
	s_setprio 0
	ds_read_b128 v[162:165], v208 offset:16384
	ds_read_b128 v[166:169], v208 offset:17408
	ds_read_b128 v[170:173], v208 offset:18432
	ds_read_b128 v[174:177], v208 offset:19456
	ds_read_b128 v[188:191], v208 offset:20480
	ds_read_b128 v[192:195], v208 offset:21504
	ds_read_b128 v[196:199], v208 offset:22528
	ds_read_b128 v[212:215], v208 offset:23552
	s_mov_b32 m0, s42
	s_nop 0
	global_load_lds_dwordx4 v200, s[30:31]
	s_nop 0
	s_mov_b32 m0, s43
	s_nop 0
	global_load_lds_dwordx4 v203, s[30:31]
	s_add_u32 s60, s30, 0x80000
	s_addc_u32 s61, s31, 0
	s_mov_b32 m0, s44
	s_nop 0
	global_load_lds_dwordx4 v200, s[60:61]
	s_nop 0
	s_mov_b32 m0, s45
	s_nop 0
	global_load_lds_dwordx4 v203, s[60:61]
	s_mov_b32 m0, s41
	s_nop 0
	global_load_lds_dwordx4 v179, s[34:35]
	s_nop 0
	s_mov_b32 m0, s46
	s_nop 0
	global_load_lds_dwordx4 v201, s[34:35]
	s_waitcnt vmcnt(8)
	s_waitcnt lgkmcnt(0)
	s_setprio 1
	s_barrier
	v_mfma_f32_16x16x32_bf16 v[62:65], v[110:113], v[162:165], v[62:65]
	v_mfma_f32_16x16x32_bf16 v[58:61], v[130:133], v[162:165], v[58:61]
	v_mfma_f32_16x16x32_bf16 v[46:49], v[110:113], v[170:173], v[46:49]
	v_mfma_f32_16x16x32_bf16 v[42:45], v[130:133], v[170:173], v[42:45]
	v_mfma_f32_16x16x32_bf16 v[30:33], v[110:113], v[188:191], v[30:33]
	v_mfma_f32_16x16x32_bf16 v[26:29], v[130:133], v[188:191], v[26:29]
	v_mfma_f32_16x16x32_bf16 v[14:17], v[110:113], v[196:199], v[14:17]
	v_mfma_f32_16x16x32_bf16 v[10:13], v[130:133], v[196:199], v[10:13]
	v_mfma_f32_16x16x32_bf16 v[62:65], v[126:129], v[166:169], v[62:65]
	v_mfma_f32_16x16x32_bf16 v[58:61], v[142:145], v[166:169], v[58:61]
	v_mfma_f32_16x16x32_bf16 v[46:49], v[126:129], v[174:177], v[46:49]
	v_mfma_f32_16x16x32_bf16 v[42:45], v[142:145], v[174:177], v[42:45]
	v_mfma_f32_16x16x32_bf16 v[30:33], v[126:129], v[192:195], v[30:33]
	v_mfma_f32_16x16x32_bf16 v[26:29], v[142:145], v[192:195], v[26:29]
	v_mfma_f32_16x16x32_bf16 v[14:17], v[126:129], v[212:215], v[14:17]
	v_mfma_f32_16x16x32_bf16 v[10:13], v[142:145], v[212:215], v[10:13]
	v_mfma_f32_16x16x32_bf16 v[54:57], v[146:149], v[162:165], v[54:57]
	v_mfma_f32_16x16x32_bf16 v[50:53], v[154:157], v[162:165], v[50:53]
	v_mfma_f32_16x16x32_bf16 v[38:41], v[146:149], v[170:173], v[38:41]
	v_mfma_f32_16x16x32_bf16 v[34:37], v[154:157], v[170:173], v[34:37]
	v_mfma_f32_16x16x32_bf16 v[22:25], v[146:149], v[188:191], v[22:25]
	v_mfma_f32_16x16x32_bf16 v[18:21], v[154:157], v[188:191], v[18:21]
	v_mfma_f32_16x16x32_bf16 v[6:9], v[146:149], v[196:199], v[6:9]
	v_mfma_f32_16x16x32_bf16 v[2:5], v[154:157], v[196:199], v[2:5]
	v_mfma_f32_16x16x32_bf16 v[54:57], v[150:153], v[166:169], v[54:57]
	v_mfma_f32_16x16x32_bf16 v[50:53], v[158:161], v[166:169], v[50:53]
	v_mfma_f32_16x16x32_bf16 v[38:41], v[150:153], v[174:177], v[38:41]
	v_mfma_f32_16x16x32_bf16 v[34:37], v[158:161], v[174:177], v[34:37]
	v_mfma_f32_16x16x32_bf16 v[22:25], v[150:153], v[192:195], v[22:25]
	v_mfma_f32_16x16x32_bf16 v[18:21], v[158:161], v[192:195], v[18:21]
	v_mfma_f32_16x16x32_bf16 v[6:9], v[150:153], v[212:215], v[6:9]
	v_mfma_f32_16x16x32_bf16 v[2:5], v[158:161], v[212:215], v[2:5]
	s_barrier
; #define PG8_STAGE(bufoff, gbase, voff) do { _Pragma("unroll") for (int _i = 0; _i < 2; ++_i) { unsigned keep_; \
;         asm volatile("s_mov_b32 %0, m0\n\ts_mov_b32 m0, %3\n\ts_nop 0\n\tglobal_load_lds_dwordx4 %1, %2\n\ts_mov_b32 m0, %0" \
;             : "=&s"(keep_) : "v"((voff)[_i]), "s"((const void*)(gbase)), "s"(ldsb0 + (unsigned)(bufoff) + (unsigned)(_i * 8192)) : "memory"); } } while (0)
; #define PG8_LDA(dst, b, h) do { _Pragma("unroll") for (int m = 0; m < 4; ++m) _Pragma("unroll") for (int k = 0; k < 2; ++k) dst[m][k] = *(const LAS bf16x8*)(lds + PG8_SA(b, h) + aoff + m * 2048 + k * 1024); } while (0)
; #define PG8_LDB(dst, b, h) do { _Pragma("unroll") for (int n = 0; n < 2; ++n) _Pragma("unroll") for (int k = 0; k < 2; ++k) dst[n][k] = *(const LAS bf16x8*)(lds + PG8_SB(b, h) + boff + n * 2048 + k * 1024); } while (0)
; #define PG8_MMA(ai, bj, At, Bt) do { __builtin_amdgcn_s_setprio(1); _Pragma("unroll") for (int m = 0; m < 4; ++m) _Pragma("unroll") for (int n = 0; n < 2; ++n) _Pragma("unroll") for (int k = 0; k < 2; ++k) \
;         acc[ai][bj][m][n] = __builtin_amdgcn_mfma_f32_16x16x32_bf16(Bt[n][k], At[m][k], acc[ai][bj][m][n], 0, 0, 0); __builtin_amdgcn_s_setprio(0); } while (0)
; #define PG8_WAIT_V(n) asm volatile("s_waitcnt vmcnt(" #n ")" ::: "memory")
; #define PG8_WAIT_L(n) asm volatile("s_waitcnt lgkmcnt(" #n ")" ::: "memory")
; #define PG8_BAR __builtin_amdgcn_s_barrier()
; #define PG8_SCHED __builtin_amdgcn_sched_barrier(0)
; template <class Epi, class Sched, bool ALIGN_EPI>
; __device__ __forceinline__ void gemm_phase(LAS unsigned char* lds, const Gemm g, const Sched& S, const Epi& E) {
;     ...
;             PG8_LDB(B0, 1, 0); PG8_LDB(B1, 1, 1); PG8_SCHED; PG8_LDA(At, 1, 0); PG8_STAGE(PG8_SA(0, 1), a2 + hstepA, voffA);
;             PG8_WAIT_V(8); PG8_WAIT_L(0); PG8_BAR; PG8_MMA(0, 0, At, B0); PG8_MMA(0, 1, At, B1); PG8_BAR; PG8_SCHED;
;             PG8_LDA(At, 1, 1); PG8_STAGE(PG8_SB(1, 0), b3, voffB); PG8_STAGE(PG8_SB(1, 1), b3 + hstepB, voffB); PG8_STAGE(PG8_SA(1, 0), a3, voffA);
;             PG8_WAIT_V(8); PG8_WAIT_L(0); PG8_BAR; PG8_MMA(1, 0, At, B0); PG8_MMA(1, 1, At, B1); PG8_BAR; PG8_SCHED;
;         }
	s_setprio 0
	ds_read_b128 v[110:113], v209
	ds_read_b128 v[126:129], v209 offset:1024
	ds_read_b128 v[130:133], v209 offset:2048
	ds_read_b128 v[142:145], v209 offset:3072
	ds_read_b128 v[146:149], v210
	ds_read_b128 v[150:153], v210 offset:1024
	ds_read_b128 v[154:157], v210 offset:2048
	ds_read_b128 v[158:161], v210 offset:3072
	ds_read_b128 v[162:165], v208 offset:32768
	ds_read_b128 v[166:169], v208 offset:33792
	ds_read_b128 v[170:173], v208 offset:34816
	ds_read_b128 v[174:177], v208 offset:35840
	ds_read_b128 v[188:191], v208 offset:36864
	ds_read_b128 v[192:195], v208 offset:37888
	ds_read_b128 v[196:199], v208 offset:38912
	ds_read_b128 v[212:215], v208 offset:39936
	s_add_u32 s34, s34, 0x80000
	s_addc_u32 s35, s35, 0
	s_mov_b32 m0, s47
	s_nop 0
	global_load_lds_dwordx4 v179, s[34:35]
	s_nop 0
	s_mov_b32 m0, s48
	s_nop 0
	global_load_lds_dwordx4 v201, s[34:35]
	s_waitcnt vmcnt(8)
	s_waitcnt lgkmcnt(0)
	s_setprio 1
	s_barrier
	v_mfma_f32_16x16x32_bf16 v[138:141], v[110:113], v[162:165], v[138:141]
	v_mfma_f32_16x16x32_bf16 v[134:137], v[130:133], v[162:165], v[134:137]
	v_mfma_f32_16x16x32_bf16 v[114:117], v[110:113], v[170:173], v[114:117]
	v_mfma_f32_16x16x32_bf16 v[106:109], v[130:133], v[170:173], v[106:109]
	v_mfma_f32_16x16x32_bf16 v[94:97], v[110:113], v[188:191], v[94:97]
	v_mfma_f32_16x16x32_bf16 v[90:93], v[130:133], v[188:191], v[90:93]
	v_mfma_f32_16x16x32_bf16 v[78:81], v[110:113], v[196:199], v[78:81]
	v_mfma_f32_16x16x32_bf16 v[74:77], v[130:133], v[196:199], v[74:77]
	v_mfma_f32_16x16x32_bf16 v[138:141], v[126:129], v[166:169], v[138:141]
	v_mfma_f32_16x16x32_bf16 v[134:137], v[142:145], v[166:169], v[134:137]
	v_mfma_f32_16x16x32_bf16 v[114:117], v[126:129], v[174:177], v[114:117]
	v_mfma_f32_16x16x32_bf16 v[106:109], v[142:145], v[174:177], v[106:109]
	v_mfma_f32_16x16x32_bf16 v[94:97], v[126:129], v[192:195], v[94:97]
	v_mfma_f32_16x16x32_bf16 v[90:93], v[142:145], v[192:195], v[90:93]
	v_mfma_f32_16x16x32_bf16 v[78:81], v[126:129], v[212:215], v[78:81]
	v_mfma_f32_16x16x32_bf16 v[74:77], v[142:145], v[212:215], v[74:77]
	v_mfma_f32_16x16x32_bf16 v[122:125], v[146:149], v[162:165], v[122:125]
	v_mfma_f32_16x16x32_bf16 v[118:121], v[154:157], v[162:165], v[118:121]
	v_mfma_f32_16x16x32_bf16 v[102:105], v[146:149], v[170:173], v[102:105]
	v_mfma_f32_16x16x32_bf16 v[98:101], v[154:157], v[170:173], v[98:101]
	v_mfma_f32_16x16x32_bf16 v[86:89], v[146:149], v[188:191], v[86:89]
	v_mfma_f32_16x16x32_bf16 v[82:85], v[154:157], v[188:191], v[82:85]
	v_mfma_f32_16x16x32_bf16 v[70:73], v[146:149], v[196:199], v[70:73]
	v_mfma_f32_16x16x32_bf16 v[66:69], v[154:157], v[196:199], v[66:69]
	v_mfma_f32_16x16x32_bf16 v[122:125], v[150:153], v[166:169], v[122:125]
	v_mfma_f32_16x16x32_bf16 v[118:121], v[158:161], v[166:169], v[118:121]
	v_mfma_f32_16x16x32_bf16 v[102:105], v[150:153], v[174:177], v[102:105]
	v_mfma_f32_16x16x32_bf16 v[98:101], v[158:161], v[174:177], v[98:101]
	v_mfma_f32_16x16x32_bf16 v[86:89], v[150:153], v[192:195], v[86:89]
	v_mfma_f32_16x16x32_bf16 v[82:85], v[158:161], v[192:195], v[82:85]
	v_mfma_f32_16x16x32_bf16 v[70:73], v[150:153], v[212:215], v[70:73]
	v_mfma_f32_16x16x32_bf16 v[66:69], v[158:161], v[212:215], v[66:69]
	s_barrier
	s_setprio 0
	ds_read_b128 v[162:165], v208 offset:49152
	ds_read_b128 v[166:169], v208 offset:50176
	ds_read_b128 v[170:173], v208 offset:51200
	ds_read_b128 v[174:177], v208 offset:52224
	ds_read_b128 v[188:191], v208 offset:53248
	ds_read_b128 v[192:195], v208 offset:54272
	ds_read_b128 v[196:199], v208 offset:55296
	ds_read_b128 v[212:215], v208 offset:56320
	s_add_u32 s34, s30, 0x80
	s_addc_u32 s35, s31, 0
	s_mov_b32 m0, s49
	s_nop 0
	global_load_lds_dwordx4 v200, s[34:35]
	s_add_u32 s30, s30, 0x80080
	s_mov_b32 m0, s50
	s_nop 0
	global_load_lds_dwordx4 v203, s[34:35]
	s_addc_u32 s31, s31, 0
	s_mov_b32 m0, s53
	s_nop 0
	global_load_lds_dwordx4 v200, s[30:31]
	s_nop 0
	s_mov_b32 m0, s54
	s_nop 0
	global_load_lds_dwordx4 v203, s[30:31]
	s_mov_b32 m0, s51
	s_nop 0
	global_load_lds_dwordx4 v179, s[28:29]
	s_nop 0
	s_mov_b32 m0, s52
	s_nop 0
	global_load_lds_dwordx4 v201, s[28:29]
	s_waitcnt vmcnt(8)
	s_waitcnt lgkmcnt(0)
	s_setprio 1
	s_barrier
	v_mfma_f32_16x16x32_bf16 v[62:65], v[110:113], v[162:165], v[62:65]
	v_mfma_f32_16x16x32_bf16 v[58:61], v[130:133], v[162:165], v[58:61]
	v_mfma_f32_16x16x32_bf16 v[46:49], v[110:113], v[170:173], v[46:49]
	v_mfma_f32_16x16x32_bf16 v[42:45], v[130:133], v[170:173], v[42:45]
	v_mfma_f32_16x16x32_bf16 v[30:33], v[110:113], v[188:191], v[30:33]
	v_mfma_f32_16x16x32_bf16 v[26:29], v[130:133], v[188:191], v[26:29]
	v_mfma_f32_16x16x32_bf16 v[14:17], v[110:113], v[196:199], v[14:17]
	v_mfma_f32_16x16x32_bf16 v[10:13], v[130:133], v[196:199], v[10:13]
	v_mfma_f32_16x16x32_bf16 v[62:65], v[126:129], v[166:169], v[62:65]
	v_mfma_f32_16x16x32_bf16 v[58:61], v[142:145], v[166:169], v[58:61]
	v_mfma_f32_16x16x32_bf16 v[46:49], v[126:129], v[174:177], v[46:49]
	v_mfma_f32_16x16x32_bf16 v[42:45], v[142:145], v[174:177], v[42:45]
	v_mfma_f32_16x16x32_bf16 v[30:33], v[126:129], v[192:195], v[30:33]
	v_mfma_f32_16x16x32_bf16 v[26:29], v[142:145], v[192:195], v[26:29]
	v_mfma_f32_16x16x32_bf16 v[14:17], v[126:129], v[212:215], v[14:17]
	v_mfma_f32_16x16x32_bf16 v[10:13], v[142:145], v[212:215], v[10:13]
	v_mfma_f32_16x16x32_bf16 v[54:57], v[146:149], v[162:165], v[54:57]
	v_mfma_f32_16x16x32_bf16 v[50:53], v[154:157], v[162:165], v[50:53]
	v_mfma_f32_16x16x32_bf16 v[38:41], v[146:149], v[170:173], v[38:41]
	v_mfma_f32_16x16x32_bf16 v[34:37], v[154:157], v[170:173], v[34:37]
	v_mfma_f32_16x16x32_bf16 v[22:25], v[146:149], v[188:191], v[22:25]
	v_mfma_f32_16x16x32_bf16 v[18:21], v[154:157], v[188:191], v[18:21]
	v_mfma_f32_16x16x32_bf16 v[6:9], v[146:149], v[196:199], v[6:9]
	v_mfma_f32_16x16x32_bf16 v[2:5], v[154:157], v[196:199], v[2:5]
	v_mfma_f32_16x16x32_bf16 v[54:57], v[150:153], v[166:169], v[54:57]
	v_mfma_f32_16x16x32_bf16 v[50:53], v[158:161], v[166:169], v[50:53]
	v_mfma_f32_16x16x32_bf16 v[38:41], v[150:153], v[174:177], v[38:41]
	v_mfma_f32_16x16x32_bf16 v[34:37], v[158:161], v[174:177], v[34:37]
	v_mfma_f32_16x16x32_bf16 v[22:25], v[150:153], v[192:195], v[22:25]
	v_mfma_f32_16x16x32_bf16 v[18:21], v[158:161], v[192:195], v[18:21]
	v_mfma_f32_16x16x32_bf16 v[6:9], v[150:153], v[212:215], v[6:9]
	v_mfma_f32_16x16x32_bf16 v[2:5], v[158:161], v[212:215], v[2:5]
	s_barrier
	s_setprio 0
	s_add_i32 s59, s59, 2
	s_add_u32 s19, s19, 0x100
	s_addc_u32 s21, s21, 0
	s_add_u32 s57, s57, 0x100
	s_addc_u32 s58, s58, 0
	s_add_u32 s26, s26, 0x100
	s_addc_u32 s27, s27, 0
	s_cmp_gt_u32 s59, 29
	s_cbranch_scc0 .LBB0_1994
	s_and_b64 vcc, exec, s[16:17]
	s_cbranch_vccz .LBB0_1997
	s_barrier

; #define PG8_STAGE(bufoff, gbase, voff) do { _Pragma("unroll") for (int _i = 0; _i < 2; ++_i) { unsigned keep_; \
;         asm volatile("s_mov_b32 %0, m0\n\ts_mov_b32 m0, %3\n\ts_nop 0\n\tglobal_load_lds_dwordx4 %1, %2\n\ts_mov_b32 m0, %0" \
;             : "=&s"(keep_) : "v"((voff)[_i]), "s"((const void*)(gbase)), "s"(ldsb0 + (unsigned)(bufoff) + (unsigned)(_i * 8192)) : "memory"); } } while (0)
; #define PG8_LDA(dst, b, h) do { _Pragma("unroll") for (int m = 0; m < 4; ++m) _Pragma("unroll") for (int k = 0; k < 2; ++k) dst[m][k] = *(const LAS bf16x8*)(lds + PG8_SA(b, h) + aoff + m * 2048 + k * 1024); } while (0)
; #define PG8_LDB(dst, b, h) do { _Pragma("unroll") for (int n = 0; n < 2; ++n) _Pragma("unroll") for (int k = 0; k < 2; ++k) dst[n][k] = *(const LAS bf16x8*)(lds + PG8_SB(b, h) + boff + n * 2048 + k * 1024); } while (0)
; #define PG8_MMA(ai, bj, At, Bt) do { __builtin_amdgcn_s_setprio(1); _Pragma("unroll") for (int m = 0; m < 4; ++m) _Pragma("unroll") for (int n = 0; n < 2; ++n) _Pragma("unroll") for (int k = 0; k < 2; ++k) \
;         acc[ai][bj][m][n] = __builtin_amdgcn_mfma_f32_16x16x32_bf16(Bt[n][k], At[m][k], acc[ai][bj][m][n], 0, 0, 0); __builtin_amdgcn_s_setprio(0); } while (0)
; #define PG8_WAIT_V(n) asm volatile("s_waitcnt vmcnt(" #n ")" ::: "memory")
; #define PG8_WAIT_L(n) asm volatile("s_waitcnt lgkmcnt(" #n ")" ::: "memory")
; template <class Epi, class Sched, bool ALIGN_EPI>
; __device__ __forceinline__ void gemm_phase(LAS unsigned char* lds, const Gemm g, const Sched& S, const Epi& E) {
;     ...
;             const bool last = (t == nt - 2);
;             const char* a1 = cA + (size_t)(t + 1) * kstep;
;             const char* a2 = last ? nA : cA + (size_t)(t + 2) * kstep; const char* b2 = last ? nB : cB + (size_t)(t + 2) * kstep;
;             const char* a3 = a2 + kstep; const char* b3 = b2 + kstep;
;             PG8_LDB(B0, 0, 0); PG8_LDB(B1, 0, 1); PG8_SCHED; PG8_LDA(At, 0, 0); PG8_STAGE(PG8_SA(1, 1), a1 + hstepA, voffA);
;             PG8_WAIT_V(8); PG8_WAIT_L(0); PG8_BAR; PG8_MMA(0, 0, At, B0); PG8_MMA(0, 1, At, B1); PG8_BAR; PG8_SCHED;
;             PG8_LDA(At, 0, 1); PG8_STAGE(PG8_SB(0, 0), b2, voffB); PG8_STAGE(PG8_SB(0, 1), b2 + hstepB, voffB); PG8_STAGE(PG8_SA(0, 0), a2, voffA);
;             PG8_WAIT_V(8); PG8_WAIT_L(0); PG8_BAR; PG8_MMA(1, 0, At, B0); PG8_MMA(1, 1, At, B1); PG8_BAR; PG8_SCHED;
.LBB0_2075:
	ds_read_b128 v[154:157], v141
	ds_read_b128 v[158:161], v141 offset:1024
	ds_read_b128 v[162:165], v141 offset:2048
	ds_read_b128 v[166:169], v141 offset:3072
	ds_read_b128 v[170:173], v142
	ds_read_b128 v[174:177], v142 offset:1024
	ds_read_b128 v[180:183], v142 offset:2048
	ds_read_b128 v[184:187], v142 offset:3072
	s_add_u32 s28, s26, 0x100
	s_addc_u32 s29, s27, 0
	s_cmp_eq_u32 s60, 28
	s_cselect_b32 s36, s5, s28
	s_cselect_b32 s37, s3, s29
	s_cselect_b32 s34, s7, s19
	s_cselect_b32 s35, s6, s21
	s_add_u32 s30, s36, 0x80
	s_addc_u32 s31, s37, 0
	ds_read_b128 v[188:191], v143
	ds_read_b128 v[192:195], v143 offset:1024
	ds_read_b128 v[196:199], v143 offset:2048
	ds_read_b128 v[204:207], v143 offset:3072
	ds_read_b128 v[208:211], v143 offset:4096
	ds_read_b128 v[212:215], v143 offset:5120
	ds_read_b128 v[216:219], v143 offset:6144
	ds_read_b128 v[220:223], v143 offset:7168
	s_add_u32 s26, s26, 0x80080
	s_addc_u32 s27, s27, 0
	s_mov_b32 m0, s57
	s_nop 0
	global_load_lds_dwordx4 v134, s[26:27]
	s_nop 0
	s_mov_b32 m0, s58
	s_nop 0
	global_load_lds_dwordx4 v136, s[26:27]
	s_waitcnt vmcnt(8)
	s_waitcnt lgkmcnt(0)
	s_setprio 1
	s_barrier
	v_mfma_f32_16x16x32_bf16 v[126:129], v[154:157], v[188:191], v[126:129]
	v_mfma_f32_16x16x32_bf16 v[122:125], v[162:165], v[188:191], v[122:125]
	v_mfma_f32_16x16x32_bf16 v[110:113], v[154:157], v[196:199], v[110:113]
	v_mfma_f32_16x16x32_bf16 v[106:109], v[162:165], v[196:199], v[106:109]
	v_mfma_f32_16x16x32_bf16 v[94:97], v[154:157], v[208:211], v[94:97]
	v_mfma_f32_16x16x32_bf16 v[90:93], v[162:165], v[208:211], v[90:93]
	v_mfma_f32_16x16x32_bf16 v[78:81], v[154:157], v[216:219], v[78:81]
	v_mfma_f32_16x16x32_bf16 v[74:77], v[162:165], v[216:219], v[74:77]
	v_mfma_f32_16x16x32_bf16 v[126:129], v[158:161], v[192:195], v[126:129]
	v_mfma_f32_16x16x32_bf16 v[122:125], v[166:169], v[192:195], v[122:125]
	v_mfma_f32_16x16x32_bf16 v[110:113], v[158:161], v[204:207], v[110:113]
	v_mfma_f32_16x16x32_bf16 v[106:109], v[166:169], v[204:207], v[106:109]
	v_mfma_f32_16x16x32_bf16 v[94:97], v[158:161], v[212:215], v[94:97]
	v_mfma_f32_16x16x32_bf16 v[90:93], v[166:169], v[212:215], v[90:93]
	v_mfma_f32_16x16x32_bf16 v[78:81], v[158:161], v[220:223], v[78:81]
	v_mfma_f32_16x16x32_bf16 v[74:77], v[166:169], v[220:223], v[74:77]
	v_mfma_f32_16x16x32_bf16 v[118:121], v[170:173], v[188:191], v[118:121]
	v_mfma_f32_16x16x32_bf16 v[114:117], v[180:183], v[188:191], v[114:117]
	v_mfma_f32_16x16x32_bf16 v[102:105], v[170:173], v[196:199], v[102:105]
	v_mfma_f32_16x16x32_bf16 v[98:101], v[180:183], v[196:199], v[98:101]
	v_mfma_f32_16x16x32_bf16 v[86:89], v[170:173], v[208:211], v[86:89]
	v_mfma_f32_16x16x32_bf16 v[82:85], v[180:183], v[208:211], v[82:85]
	v_mfma_f32_16x16x32_bf16 v[70:73], v[170:173], v[216:219], v[70:73]
	v_mfma_f32_16x16x32_bf16 v[66:69], v[180:183], v[216:219], v[66:69]
	v_mfma_f32_16x16x32_bf16 v[118:121], v[174:177], v[192:195], v[118:121]
	v_mfma_f32_16x16x32_bf16 v[114:117], v[184:187], v[192:195], v[114:117]
	v_mfma_f32_16x16x32_bf16 v[102:105], v[174:177], v[204:207], v[102:105]
	v_mfma_f32_16x16x32_bf16 v[98:101], v[184:187], v[204:207], v[98:101]
	v_mfma_f32_16x16x32_bf16 v[86:89], v[174:177], v[212:215], v[86:89]
	v_mfma_f32_16x16x32_bf16 v[82:85], v[184:187], v[212:215], v[82:85]
	v_mfma_f32_16x16x32_bf16 v[70:73], v[174:177], v[220:223], v[70:73]
	v_mfma_f32_16x16x32_bf16 v[66:69], v[184:187], v[220:223], v[66:69]
	s_barrier
	s_setprio 0
	ds_read_b128 v[188:191], v143 offset:16384
	ds_read_b128 v[192:195], v143 offset:17408
	ds_read_b128 v[196:199], v143 offset:18432
	ds_read_b128 v[204:207], v143 offset:19456
	ds_read_b128 v[208:211], v143 offset:20480
	ds_read_b128 v[212:215], v143 offset:21504
	ds_read_b128 v[216:219], v143 offset:22528
	ds_read_b128 v[220:223], v143 offset:23552
	s_mov_b32 m0, s44
	s_nop 0
	global_load_lds_dwordx4 v135, s[34:35]
	s_nop 0
	s_mov_b32 m0, s45
	s_nop 0
	global_load_lds_dwordx4 v137, s[34:35]
	s_add_u32 s26, s34, 0x80000
	s_addc_u32 s27, s35, 0
	s_mov_b32 m0, s46
	s_nop 0
	global_load_lds_dwordx4 v135, s[26:27]
	s_nop 0
	s_mov_b32 m0, s47
	s_nop 0
	global_load_lds_dwordx4 v137, s[26:27]
	s_mov_b32 m0, s42
	s_nop 0
	global_load_lds_dwordx4 v134, s[36:37]
	s_nop 0
	s_mov_b32 m0, s48
	s_nop 0
	global_load_lds_dwordx4 v136, s[36:37]
	s_waitcnt vmcnt(8)
	s_waitcnt lgkmcnt(0)
	s_setprio 1
	s_barrier
	v_mfma_f32_16x16x32_bf16 v[62:65], v[154:157], v[188:191], v[62:65]
	v_mfma_f32_16x16x32_bf16 v[58:61], v[162:165], v[188:191], v[58:61]
	v_mfma_f32_16x16x32_bf16 v[46:49], v[154:157], v[196:199], v[46:49]
	v_mfma_f32_16x16x32_bf16 v[42:45], v[162:165], v[196:199], v[42:45]
	v_mfma_f32_16x16x32_bf16 v[30:33], v[154:157], v[208:211], v[30:33]
	v_mfma_f32_16x16x32_bf16 v[26:29], v[162:165], v[208:211], v[26:29]
	v_mfma_f32_16x16x32_bf16 v[14:17], v[154:157], v[216:219], v[14:17]
	v_mfma_f32_16x16x32_bf16 v[10:13], v[162:165], v[216:219], v[10:13]
	v_mfma_f32_16x16x32_bf16 v[62:65], v[158:161], v[192:195], v[62:65]
	v_mfma_f32_16x16x32_bf16 v[58:61], v[166:169], v[192:195], v[58:61]
	v_mfma_f32_16x16x32_bf16 v[46:49], v[158:161], v[204:207], v[46:49]
	v_mfma_f32_16x16x32_bf16 v[42:45], v[166:169], v[204:207], v[42:45]
	v_mfma_f32_16x16x32_bf16 v[30:33], v[158:161], v[212:215], v[30:33]
	v_mfma_f32_16x16x32_bf16 v[26:29], v[166:169], v[212:215], v[26:29]
	v_mfma_f32_16x16x32_bf16 v[14:17], v[158:161], v[220:223], v[14:17]
	v_mfma_f32_16x16x32_bf16 v[10:13], v[166:169], v[220:223], v[10:13]
	v_mfma_f32_16x16x32_bf16 v[54:57], v[170:173], v[188:191], v[54:57]
	v_mfma_f32_16x16x32_bf16 v[50:53], v[180:183], v[188:191], v[50:53]
	v_mfma_f32_16x16x32_bf16 v[38:41], v[170:173], v[196:199], v[38:41]
	v_mfma_f32_16x16x32_bf16 v[34:37], v[180:183], v[196:199], v[34:37]
	v_mfma_f32_16x16x32_bf16 v[22:25], v[170:173], v[208:211], v[22:25]
	v_mfma_f32_16x16x32_bf16 v[18:21], v[180:183], v[208:211], v[18:21]
	v_mfma_f32_16x16x32_bf16 v[6:9], v[170:173], v[216:219], v[6:9]
	v_mfma_f32_16x16x32_bf16 v[2:5], v[180:183], v[216:219], v[2:5]
	v_mfma_f32_16x16x32_bf16 v[54:57], v[174:177], v[192:195], v[54:57]
	v_mfma_f32_16x16x32_bf16 v[50:53], v[184:187], v[192:195], v[50:53]
	v_mfma_f32_16x16x32_bf16 v[38:41], v[174:177], v[204:207], v[38:41]
	v_mfma_f32_16x16x32_bf16 v[34:37], v[184:187], v[204:207], v[34:37]
	v_mfma_f32_16x16x32_bf16 v[22:25], v[174:177], v[212:215], v[22:25]
	v_mfma_f32_16x16x32_bf16 v[18:21], v[184:187], v[212:215], v[18:21]
	v_mfma_f32_16x16x32_bf16 v[6:9], v[174:177], v[220:223], v[6:9]
	v_mfma_f32_16x16x32_bf16 v[2:5], v[184:187], v[220:223], v[2:5]
	s_barrier
; #define PG8_STAGE(bufoff, gbase, voff) do { _Pragma("unroll") for (int _i = 0; _i < 2; ++_i) { unsigned keep_; \
;         asm volatile("s_mov_b32 %0, m0\n\ts_mov_b32 m0, %3\n\ts_nop 0\n\tglobal_load_lds_dwordx4 %1, %2\n\ts_mov_b32 m0, %0" \
;             : "=&s"(keep_) : "v"((voff)[_i]), "s"((const void*)(gbase)), "s"(ldsb0 + (unsigned)(bufoff) + (unsigned)(_i * 8192)) : "memory"); } } while (0)
; #define PG8_LDA(dst, b, h) do { _Pragma("unroll") for (int m = 0; m < 4; ++m) _Pragma("unroll") for (int k = 0; k < 2; ++k) dst[m][k] = *(const LAS bf16x8*)(lds + PG8_SA(b, h) + aoff + m * 2048 + k * 1024); } while (0)
; #define PG8_LDB(dst, b, h) do { _Pragma("unroll") for (int n = 0; n < 2; ++n) _Pragma("unroll") for (int k = 0; k < 2; ++k) dst[n][k] = *(const LAS bf16x8*)(lds + PG8_SB(b, h) + boff + n * 2048 + k * 1024); } while (0)
; #define PG8_MMA(ai, bj, At, Bt) do { __builtin_amdgcn_s_setprio(1); _Pragma("unroll") for (int m = 0; m < 4; ++m) _Pragma("unroll") for (int n = 0; n < 2; ++n) _Pragma("unroll") for (int k = 0; k < 2; ++k) \
;         acc[ai][bj][m][n] = __builtin_amdgcn_mfma_f32_16x16x32_bf16(Bt[n][k], At[m][k], acc[ai][bj][m][n], 0, 0, 0); __builtin_amdgcn_s_setprio(0); } while (0)
; #define PG8_WAIT_V(n) asm volatile("s_waitcnt vmcnt(" #n ")" ::: "memory")
; #define PG8_WAIT_L(n) asm volatile("s_waitcnt lgkmcnt(" #n ")" ::: "memory")
; #define PG8_BAR __builtin_amdgcn_s_barrier()
; #define PG8_SCHED __builtin_amdgcn_sched_barrier(0)
; template <class Epi, class Sched, bool ALIGN_EPI>
; __device__ __forceinline__ void gemm_phase(LAS unsigned char* lds, const Gemm g, const Sched& S, const Epi& E) {
;     ...
;             PG8_LDB(B0, 1, 0); PG8_LDB(B1, 1, 1); PG8_SCHED; PG8_LDA(At, 1, 0); PG8_STAGE(PG8_SA(0, 1), a2 + hstepA, voffA);
;             PG8_WAIT_V(8); PG8_WAIT_L(0); PG8_BAR; PG8_MMA(0, 0, At, B0); PG8_MMA(0, 1, At, B1); PG8_BAR; PG8_SCHED;
;             PG8_LDA(At, 1, 1); PG8_STAGE(PG8_SB(1, 0), b3, voffB); PG8_STAGE(PG8_SB(1, 1), b3 + hstepB, voffB); PG8_STAGE(PG8_SA(1, 0), a3, voffA);
;             PG8_WAIT_V(8); PG8_WAIT_L(0); PG8_BAR; PG8_MMA(1, 0, At, B0); PG8_MMA(1, 1, At, B1); PG8_BAR; PG8_SCHED;
;         }
	s_setprio 0
	ds_read_b128 v[154:157], v144
	ds_read_b128 v[158:161], v144 offset:1024
	ds_read_b128 v[162:165], v144 offset:2048
	ds_read_b128 v[166:169], v144 offset:3072
	ds_read_b128 v[170:173], v145
	ds_read_b128 v[174:177], v145 offset:1024
	ds_read_b128 v[180:183], v145 offset:2048
	ds_read_b128 v[184:187], v145 offset:3072
	ds_read_b128 v[188:191], v143 offset:32768
	ds_read_b128 v[192:195], v143 offset:33792
	ds_read_b128 v[196:199], v143 offset:34816
	ds_read_b128 v[204:207], v143 offset:35840
	ds_read_b128 v[208:211], v143 offset:36864
	ds_read_b128 v[212:215], v143 offset:37888
	ds_read_b128 v[216:219], v143 offset:38912
	ds_read_b128 v[220:223], v143 offset:39936
	s_add_u32 s26, s36, 0x80000
	s_addc_u32 s27, s37, 0
	s_mov_b32 m0, s49
	s_nop 0
	global_load_lds_dwordx4 v134, s[26:27]
	s_nop 0
	s_mov_b32 m0, s50
	s_nop 0
	global_load_lds_dwordx4 v136, s[26:27]
	s_waitcnt vmcnt(8)
	s_waitcnt lgkmcnt(0)
	s_setprio 1
	s_barrier
	v_mfma_f32_16x16x32_bf16 v[126:129], v[154:157], v[188:191], v[126:129]
	v_mfma_f32_16x16x32_bf16 v[122:125], v[162:165], v[188:191], v[122:125]
	v_mfma_f32_16x16x32_bf16 v[110:113], v[154:157], v[196:199], v[110:113]
	v_mfma_f32_16x16x32_bf16 v[106:109], v[162:165], v[196:199], v[106:109]
	v_mfma_f32_16x16x32_bf16 v[94:97], v[154:157], v[208:211], v[94:97]
	v_mfma_f32_16x16x32_bf16 v[90:93], v[162:165], v[208:211], v[90:93]
	v_mfma_f32_16x16x32_bf16 v[78:81], v[154:157], v[216:219], v[78:81]
	v_mfma_f32_16x16x32_bf16 v[74:77], v[162:165], v[216:219], v[74:77]
	v_mfma_f32_16x16x32_bf16 v[126:129], v[158:161], v[192:195], v[126:129]
	v_mfma_f32_16x16x32_bf16 v[122:125], v[166:169], v[192:195], v[122:125]
	v_mfma_f32_16x16x32_bf16 v[110:113], v[158:161], v[204:207], v[110:113]
	v_mfma_f32_16x16x32_bf16 v[106:109], v[166:169], v[204:207], v[106:109]
	v_mfma_f32_16x16x32_bf16 v[94:97], v[158:161], v[212:215], v[94:97]
	v_mfma_f32_16x16x32_bf16 v[90:93], v[166:169], v[212:215], v[90:93]
	v_mfma_f32_16x16x32_bf16 v[78:81], v[158:161], v[220:223], v[78:81]
	v_mfma_f32_16x16x32_bf16 v[74:77], v[166:169], v[220:223], v[74:77]
	v_mfma_f32_16x16x32_bf16 v[118:121], v[170:173], v[188:191], v[118:121]
	v_mfma_f32_16x16x32_bf16 v[114:117], v[180:183], v[188:191], v[114:117]
	v_mfma_f32_16x16x32_bf16 v[102:105], v[170:173], v[196:199], v[102:105]
	v_mfma_f32_16x16x32_bf16 v[98:101], v[180:183], v[196:199], v[98:101]
	v_mfma_f32_16x16x32_bf16 v[86:89], v[170:173], v[208:211], v[86:89]
	v_mfma_f32_16x16x32_bf16 v[82:85], v[180:183], v[208:211], v[82:85]
	v_mfma_f32_16x16x32_bf16 v[70:73], v[170:173], v[216:219], v[70:73]
	v_mfma_f32_16x16x32_bf16 v[66:69], v[180:183], v[216:219], v[66:69]
	v_mfma_f32_16x16x32_bf16 v[118:121], v[174:177], v[192:195], v[118:121]
	v_mfma_f32_16x16x32_bf16 v[114:117], v[184:187], v[192:195], v[114:117]
	v_mfma_f32_16x16x32_bf16 v[102:105], v[174:177], v[204:207], v[102:105]
	v_mfma_f32_16x16x32_bf16 v[98:101], v[184:187], v[204:207], v[98:101]
	v_mfma_f32_16x16x32_bf16 v[86:89], v[174:177], v[212:215], v[86:89]
	v_mfma_f32_16x16x32_bf16 v[82:85], v[184:187], v[212:215], v[82:85]
	v_mfma_f32_16x16x32_bf16 v[70:73], v[174:177], v[220:223], v[70:73]
	v_mfma_f32_16x16x32_bf16 v[66:69], v[184:187], v[220:223], v[66:69]
	s_barrier
	s_setprio 0
	ds_read_b128 v[188:191], v143 offset:49152
	ds_read_b128 v[192:195], v143 offset:50176
	ds_read_b128 v[196:199], v143 offset:51200
	ds_read_b128 v[204:207], v143 offset:52224
	ds_read_b128 v[208:211], v143 offset:53248
	ds_read_b128 v[212:215], v143 offset:54272
	ds_read_b128 v[216:219], v143 offset:55296
	ds_read_b128 v[220:223], v143 offset:56320
	s_add_u32 s26, s34, 0x80
	s_addc_u32 s27, s35, 0
	s_mov_b32 m0, s51
	s_nop 0
	global_load_lds_dwordx4 v135, s[26:27]
	s_nop 0
	s_mov_b32 m0, s52
	s_nop 0
	global_load_lds_dwordx4 v137, s[26:27]
	s_add_u32 s26, s34, 0x80080
	s_addc_u32 s27, s35, 0
	s_mov_b32 m0, s55
	s_nop 0
	global_load_lds_dwordx4 v135, s[26:27]
	s_nop 0
	s_mov_b32 m0, s56
	s_nop 0
	global_load_lds_dwordx4 v137, s[26:27]
	s_mov_b32 m0, s53
	s_nop 0
	global_load_lds_dwordx4 v134, s[30:31]
	s_nop 0
	s_mov_b32 m0, s54
	s_nop 0
	global_load_lds_dwordx4 v136, s[30:31]
	s_waitcnt vmcnt(8)
	s_waitcnt lgkmcnt(0)
	s_setprio 1
	s_barrier
	v_mfma_f32_16x16x32_bf16 v[62:65], v[154:157], v[188:191], v[62:65]
	v_mfma_f32_16x16x32_bf16 v[58:61], v[162:165], v[188:191], v[58:61]
	v_mfma_f32_16x16x32_bf16 v[46:49], v[154:157], v[196:199], v[46:49]
	v_mfma_f32_16x16x32_bf16 v[42:45], v[162:165], v[196:199], v[42:45]
	v_mfma_f32_16x16x32_bf16 v[30:33], v[154:157], v[208:211], v[30:33]
	v_mfma_f32_16x16x32_bf16 v[26:29], v[162:165], v[208:211], v[26:29]
	v_mfma_f32_16x16x32_bf16 v[14:17], v[154:157], v[216:219], v[14:17]
	v_mfma_f32_16x16x32_bf16 v[10:13], v[162:165], v[216:219], v[10:13]
	v_mfma_f32_16x16x32_bf16 v[62:65], v[158:161], v[192:195], v[62:65]
	v_mfma_f32_16x16x32_bf16 v[58:61], v[166:169], v[192:195], v[58:61]
	v_mfma_f32_16x16x32_bf16 v[46:49], v[158:161], v[204:207], v[46:49]
	v_mfma_f32_16x16x32_bf16 v[42:45], v[166:169], v[204:207], v[42:45]
	v_mfma_f32_16x16x32_bf16 v[30:33], v[158:161], v[212:215], v[30:33]
	v_mfma_f32_16x16x32_bf16 v[26:29], v[166:169], v[212:215], v[26:29]
	v_mfma_f32_16x16x32_bf16 v[14:17], v[158:161], v[220:223], v[14:17]
	v_mfma_f32_16x16x32_bf16 v[10:13], v[166:169], v[220:223], v[10:13]
	v_mfma_f32_16x16x32_bf16 v[54:57], v[170:173], v[188:191], v[54:57]
	v_mfma_f32_16x16x32_bf16 v[50:53], v[180:183], v[188:191], v[50:53]
	v_mfma_f32_16x16x32_bf16 v[38:41], v[170:173], v[196:199], v[38:41]
	v_mfma_f32_16x16x32_bf16 v[34:37], v[180:183], v[196:199], v[34:37]
	v_mfma_f32_16x16x32_bf16 v[22:25], v[170:173], v[208:211], v[22:25]
	v_mfma_f32_16x16x32_bf16 v[18:21], v[180:183], v[208:211], v[18:21]
	v_mfma_f32_16x16x32_bf16 v[6:9], v[170:173], v[216:219], v[6:9]
	v_mfma_f32_16x16x32_bf16 v[2:5], v[180:183], v[216:219], v[2:5]
	v_mfma_f32_16x16x32_bf16 v[54:57], v[174:177], v[192:195], v[54:57]
	v_mfma_f32_16x16x32_bf16 v[50:53], v[184:187], v[192:195], v[50:53]
	v_mfma_f32_16x16x32_bf16 v[38:41], v[174:177], v[204:207], v[38:41]
	v_mfma_f32_16x16x32_bf16 v[34:37], v[184:187], v[204:207], v[34:37]
	v_mfma_f32_16x16x32_bf16 v[22:25], v[174:177], v[212:215], v[22:25]
	v_mfma_f32_16x16x32_bf16 v[18:21], v[184:187], v[212:215], v[18:21]
	v_mfma_f32_16x16x32_bf16 v[6:9], v[174:177], v[220:223], v[6:9]
	v_mfma_f32_16x16x32_bf16 v[2:5], v[184:187], v[220:223], v[2:5]
	s_barrier
	s_setprio 0
	s_add_i32 s60, s60, 2
	s_add_u32 s19, s19, 0x100
	s_addc_u32 s21, s21, 0
	s_cmp_gt_u32 s60, 29
	s_mov_b64 s[26:27], s[28:29]
	s_cbranch_scc0 .LBB0_2075
	s_and_b64 vcc, exec, s[16:17]
	s_cbranch_vccz .LBB0_2078
	s_barrier

; #define PG8_STAGE(bufoff, gbase, voff) do { _Pragma("unroll") for (int _i = 0; _i < 2; ++_i) { unsigned keep_; \
;         asm volatile("s_mov_b32 %0, m0\n\ts_mov_b32 m0, %3\n\ts_nop 0\n\tglobal_load_lds_dwordx4 %1, %2\n\ts_mov_b32 m0, %0" \
;             : "=&s"(keep_) : "v"((voff)[_i]), "s"((const void*)(gbase)), "s"(ldsb0 + (unsigned)(bufoff) + (unsigned)(_i * 8192)) : "memory"); } } while (0)
; #define PG8_LDA(dst, b, h) do { _Pragma("unroll") for (int m = 0; m < 4; ++m) _Pragma("unroll") for (int k = 0; k < 2; ++k) dst[m][k] = *(const LAS bf16x8*)(lds + PG8_SA(b, h) + aoff + m * 2048 + k * 1024); } while (0)
; #define PG8_LDB(dst, b, h) do { _Pragma("unroll") for (int n = 0; n < 2; ++n) _Pragma("unroll") for (int k = 0; k < 2; ++k) dst[n][k] = *(const LAS bf16x8*)(lds + PG8_SB(b, h) + boff + n * 2048 + k * 1024); } while (0)
; #define PG8_MMA(ai, bj, At, Bt) do { __builtin_amdgcn_s_setprio(1); _Pragma("unroll") for (int m = 0; m < 4; ++m) _Pragma("unroll") for (int n = 0; n < 2; ++n) _Pragma("unroll") for (int k = 0; k < 2; ++k) \
;         acc[ai][bj][m][n] = __builtin_amdgcn_mfma_f32_16x16x32_bf16(Bt[n][k], At[m][k], acc[ai][bj][m][n], 0, 0, 0); __builtin_amdgcn_s_setprio(0); } while (0)
; #define PG8_WAIT_V(n) asm volatile("s_waitcnt vmcnt(" #n ")" ::: "memory")
; #define PG8_WAIT_L(n) asm volatile("s_waitcnt lgkmcnt(" #n ")" ::: "memory")
; template <class Epi, class Sched, bool ALIGN_EPI>
; __device__ __forceinline__ void gemm_phase(LAS unsigned char* lds, const Gemm g, const Sched& S, const Epi& E) {
;     ...
;             const bool last = (t == nt - 2);
;             const char* a1 = cA + (size_t)(t + 1) * kstep;
;             const char* a2 = last ? nA : cA + (size_t)(t + 2) * kstep; const char* b2 = last ? nB : cB + (size_t)(t + 2) * kstep;
;             const char* a3 = a2 + kstep; const char* b3 = b2 + kstep;
;             PG8_LDB(B0, 0, 0); PG8_LDB(B1, 0, 1); PG8_SCHED; PG8_LDA(At, 0, 0); PG8_STAGE(PG8_SA(1, 1), a1 + hstepA, voffA);
;             PG8_WAIT_V(8); PG8_WAIT_L(0); PG8_BAR; PG8_MMA(0, 0, At, B0); PG8_MMA(0, 1, At, B1); PG8_BAR; PG8_SCHED;
;             PG8_LDA(At, 0, 1); PG8_STAGE(PG8_SB(0, 0), b2, voffB); PG8_STAGE(PG8_SB(0, 1), b2 + hstepB, voffB); PG8_STAGE(PG8_SA(0, 0), a2, voffA);
;             PG8_WAIT_V(8); PG8_WAIT_L(0); PG8_BAR; PG8_MMA(1, 0, At, B0); PG8_MMA(1, 1, At, B1); PG8_BAR; PG8_SCHED;
.LBB0_2172:
	s_add_u32 s61, s22, s26
	s_addc_u32 s63, s23, s27
	s_add_u32 s28, s61, 0x100
	v_add_u32_e32 v141, 0x10000, v139
	s_addc_u32 s29, s63, 0
	ds_read_b128 v[142:145], v141
	ds_read_b128 v[146:149], v141 offset:1024
	ds_read_b128 v[150:153], v141 offset:2048
	ds_read_b128 v[154:157], v141 offset:3072
	v_add_u32_e32 v141, 0x14000, v139
	s_add_u32 s30, s20, s26
	ds_read_b128 v[158:161], v141
	ds_read_b128 v[162:165], v141 offset:1024
	ds_read_b128 v[166:169], v141 offset:2048
	ds_read_b128 v[170:173], v141 offset:3072
	s_addc_u32 s31, s21, s27
	s_add_u32 s30, s30, 0x100
	s_addc_u32 s31, s31, 0
	s_cmpk_eq_i32 s60, 0x54
	s_cselect_b32 s34, s12, s28
	s_cselect_b32 s35, s13, s29
	s_cselect_b32 s30, s24, s30
	s_cselect_b32 s31, s25, s31
	s_add_u32 s28, s34, 0x80
	s_addc_u32 s29, s35, 0
	ds_read_b128 v[174:177], v140
	ds_read_b128 v[178:181], v140 offset:1024
	ds_read_b128 v[182:185], v140 offset:2048
	ds_read_b128 v[186:189], v140 offset:3072
	ds_read_b128 v[190:193], v140 offset:4096
	ds_read_b128 v[194:197], v140 offset:5120
	ds_read_b128 v[198:201], v140 offset:6144
	ds_read_b128 v[204:207], v140 offset:7168
	s_add_u32 s62, s61, 0x160080
	s_addc_u32 s63, s63, 0
	s_mov_b32 m0, s54
	s_nop 0
	global_load_lds_dwordx4 v131, s[62:63]
	s_nop 0
	s_mov_b32 m0, s55
	s_nop 0
	global_load_lds_dwordx4 v137, s[62:63]
	s_waitcnt vmcnt(8)
	s_waitcnt lgkmcnt(0)
	s_setprio 1
	s_barrier
	v_mfma_f32_16x16x32_bf16 v[126:129], v[142:145], v[174:177], v[126:129]
	v_mfma_f32_16x16x32_bf16 v[122:125], v[150:153], v[174:177], v[122:125]
	v_mfma_f32_16x16x32_bf16 v[110:113], v[142:145], v[182:185], v[110:113]
	v_mfma_f32_16x16x32_bf16 v[106:109], v[150:153], v[182:185], v[106:109]
	v_mfma_f32_16x16x32_bf16 v[94:97], v[142:145], v[190:193], v[94:97]
	v_mfma_f32_16x16x32_bf16 v[90:93], v[150:153], v[190:193], v[90:93]
	v_mfma_f32_16x16x32_bf16 v[78:81], v[142:145], v[198:201], v[78:81]
	v_mfma_f32_16x16x32_bf16 v[74:77], v[150:153], v[198:201], v[74:77]
	v_mfma_f32_16x16x32_bf16 v[126:129], v[146:149], v[178:181], v[126:129]
	v_mfma_f32_16x16x32_bf16 v[122:125], v[154:157], v[178:181], v[122:125]
	v_mfma_f32_16x16x32_bf16 v[110:113], v[146:149], v[186:189], v[110:113]
	v_mfma_f32_16x16x32_bf16 v[106:109], v[154:157], v[186:189], v[106:109]
	v_mfma_f32_16x16x32_bf16 v[94:97], v[146:149], v[194:197], v[94:97]
	v_mfma_f32_16x16x32_bf16 v[90:93], v[154:157], v[194:197], v[90:93]
	v_mfma_f32_16x16x32_bf16 v[78:81], v[146:149], v[204:207], v[78:81]
	v_mfma_f32_16x16x32_bf16 v[74:77], v[154:157], v[204:207], v[74:77]
	v_mfma_f32_16x16x32_bf16 v[118:121], v[158:161], v[174:177], v[118:121]
	v_mfma_f32_16x16x32_bf16 v[114:117], v[166:169], v[174:177], v[114:117]
	v_mfma_f32_16x16x32_bf16 v[102:105], v[158:161], v[182:185], v[102:105]
	v_mfma_f32_16x16x32_bf16 v[98:101], v[166:169], v[182:185], v[98:101]
	v_mfma_f32_16x16x32_bf16 v[86:89], v[158:161], v[190:193], v[86:89]
	v_mfma_f32_16x16x32_bf16 v[82:85], v[166:169], v[190:193], v[82:85]
	v_mfma_f32_16x16x32_bf16 v[70:73], v[158:161], v[198:201], v[70:73]
	v_mfma_f32_16x16x32_bf16 v[66:69], v[166:169], v[198:201], v[66:69]
	v_mfma_f32_16x16x32_bf16 v[118:121], v[162:165], v[178:181], v[118:121]
	v_mfma_f32_16x16x32_bf16 v[114:117], v[170:173], v[178:181], v[114:117]
	v_mfma_f32_16x16x32_bf16 v[102:105], v[162:165], v[186:189], v[102:105]
	v_mfma_f32_16x16x32_bf16 v[98:101], v[170:173], v[186:189], v[98:101]
	v_mfma_f32_16x16x32_bf16 v[86:89], v[162:165], v[194:197], v[86:89]
	v_mfma_f32_16x16x32_bf16 v[82:85], v[170:173], v[194:197], v[82:85]
	v_mfma_f32_16x16x32_bf16 v[70:73], v[162:165], v[204:207], v[70:73]
	v_mfma_f32_16x16x32_bf16 v[66:69], v[170:173], v[204:207], v[66:69]
	s_barrier
	s_setprio 0
	ds_read_b128 v[174:177], v140 offset:16384
	ds_read_b128 v[178:181], v140 offset:17408
	ds_read_b128 v[182:185], v140 offset:18432
	ds_read_b128 v[186:189], v140 offset:19456
	ds_read_b128 v[190:193], v140 offset:20480
	ds_read_b128 v[194:197], v140 offset:21504
	ds_read_b128 v[198:201], v140 offset:22528
	ds_read_b128 v[204:207], v140 offset:23552
	s_mov_b32 m0, s3
	s_nop 0
	global_load_lds_dwordx4 v136, s[30:31]
	s_add_u32 s62, s30, 0x160000
	s_mov_b32 m0, s41
	s_nop 0
	global_load_lds_dwordx4 v138, s[30:31]
	s_addc_u32 s63, s31, 0
	s_mov_b32 m0, s42
	s_nop 0
	global_load_lds_dwordx4 v136, s[62:63]
	s_nop 0
	s_mov_b32 m0, s43
	s_nop 0
	global_load_lds_dwordx4 v138, s[62:63]
	s_nop 0
	s_mov_b32 m0, s2
	s_nop 0
	global_load_lds_dwordx4 v131, s[34:35]
	s_nop 0
	s_mov_b32 m0, s44
	s_nop 0
	global_load_lds_dwordx4 v137, s[34:35]
	s_waitcnt vmcnt(8)
	s_waitcnt lgkmcnt(0)
	s_setprio 1
	s_barrier
; #define PG8_STAGE(bufoff, gbase, voff) do { _Pragma("unroll") for (int _i = 0; _i < 2; ++_i) { unsigned keep_; \
;         asm volatile("s_mov_b32 %0, m0\n\ts_mov_b32 m0, %3\n\ts_nop 0\n\tglobal_load_lds_dwordx4 %1, %2\n\ts_mov_b32 m0, %0" \
;             : "=&s"(keep_) : "v"((voff)[_i]), "s"((const void*)(gbase)), "s"(ldsb0 + (unsigned)(bufoff) + (unsigned)(_i * 8192)) : "memory"); } } while (0)
; #define PG8_LDA(dst, b, h) do { _Pragma("unroll") for (int m = 0; m < 4; ++m) _Pragma("unroll") for (int k = 0; k < 2; ++k) dst[m][k] = *(const LAS bf16x8*)(lds + PG8_SA(b, h) + aoff + m * 2048 + k * 1024); } while (0)
; #define PG8_LDB(dst, b, h) do { _Pragma("unroll") for (int n = 0; n < 2; ++n) _Pragma("unroll") for (int k = 0; k < 2; ++k) dst[n][k] = *(const LAS bf16x8*)(lds + PG8_SB(b, h) + boff + n * 2048 + k * 1024); } while (0)
; #define PG8_MMA(ai, bj, At, Bt) do { __builtin_amdgcn_s_setprio(1); _Pragma("unroll") for (int m = 0; m < 4; ++m) _Pragma("unroll") for (int n = 0; n < 2; ++n) _Pragma("unroll") for (int k = 0; k < 2; ++k) \
;         acc[ai][bj][m][n] = __builtin_amdgcn_mfma_f32_16x16x32_bf16(Bt[n][k], At[m][k], acc[ai][bj][m][n], 0, 0, 0); __builtin_amdgcn_s_setprio(0); } while (0)
; #define PG8_WAIT_V(n) asm volatile("s_waitcnt vmcnt(" #n ")" ::: "memory")
; #define PG8_WAIT_L(n) asm volatile("s_waitcnt lgkmcnt(" #n ")" ::: "memory")
; #define PG8_BAR __builtin_amdgcn_s_barrier()
; #define PG8_SCHED __builtin_amdgcn_sched_barrier(0)
; template <class Epi, class Sched, bool ALIGN_EPI>
; __device__ __forceinline__ void gemm_phase(LAS unsigned char* lds, const Gemm g, const Sched& S, const Epi& E) {
;     ...
;             PG8_WAIT_V(8); PG8_WAIT_L(0); PG8_BAR; PG8_MMA(1, 0, At, B0); PG8_MMA(1, 1, At, B1); PG8_BAR; PG8_SCHED;
;             PG8_LDB(B0, 1, 0); PG8_LDB(B1, 1, 1); PG8_SCHED; PG8_LDA(At, 1, 0); PG8_STAGE(PG8_SA(0, 1), a2 + hstepA, voffA);
;             PG8_WAIT_V(8); PG8_WAIT_L(0); PG8_BAR; PG8_MMA(0, 0, At, B0); PG8_MMA(0, 1, At, B1); PG8_BAR; PG8_SCHED;
	v_mfma_f32_16x16x32_bf16 v[62:65], v[142:145], v[174:177], v[62:65]
	v_mfma_f32_16x16x32_bf16 v[58:61], v[150:153], v[174:177], v[58:61]
	v_mfma_f32_16x16x32_bf16 v[46:49], v[142:145], v[182:185], v[46:49]
	v_mfma_f32_16x16x32_bf16 v[42:45], v[150:153], v[182:185], v[42:45]
	v_mfma_f32_16x16x32_bf16 v[30:33], v[142:145], v[190:193], v[30:33]
	v_mfma_f32_16x16x32_bf16 v[26:29], v[150:153], v[190:193], v[26:29]
	v_mfma_f32_16x16x32_bf16 v[14:17], v[142:145], v[198:201], v[14:17]
	v_mfma_f32_16x16x32_bf16 v[10:13], v[150:153], v[198:201], v[10:13]
	v_mfma_f32_16x16x32_bf16 v[62:65], v[146:149], v[178:181], v[62:65]
	v_mfma_f32_16x16x32_bf16 v[58:61], v[154:157], v[178:181], v[58:61]
	v_mfma_f32_16x16x32_bf16 v[46:49], v[146:149], v[186:189], v[46:49]
	v_mfma_f32_16x16x32_bf16 v[42:45], v[154:157], v[186:189], v[42:45]
	v_mfma_f32_16x16x32_bf16 v[30:33], v[146:149], v[194:197], v[30:33]
	v_mfma_f32_16x16x32_bf16 v[26:29], v[154:157], v[194:197], v[26:29]
	v_mfma_f32_16x16x32_bf16 v[14:17], v[146:149], v[204:207], v[14:17]
	v_mfma_f32_16x16x32_bf16 v[10:13], v[154:157], v[204:207], v[10:13]
	v_mfma_f32_16x16x32_bf16 v[54:57], v[158:161], v[174:177], v[54:57]
	v_mfma_f32_16x16x32_bf16 v[50:53], v[166:169], v[174:177], v[50:53]
	v_mfma_f32_16x16x32_bf16 v[38:41], v[158:161], v[182:185], v[38:41]
	v_mfma_f32_16x16x32_bf16 v[34:37], v[166:169], v[182:185], v[34:37]
	v_mfma_f32_16x16x32_bf16 v[22:25], v[158:161], v[190:193], v[22:25]
	v_mfma_f32_16x16x32_bf16 v[18:21], v[166:169], v[190:193], v[18:21]
	v_mfma_f32_16x16x32_bf16 v[6:9], v[158:161], v[198:201], v[6:9]
	v_mfma_f32_16x16x32_bf16 v[2:5], v[166:169], v[198:201], v[2:5]
	v_mfma_f32_16x16x32_bf16 v[54:57], v[162:165], v[178:181], v[54:57]
	v_mfma_f32_16x16x32_bf16 v[50:53], v[170:173], v[178:181], v[50:53]
	v_mfma_f32_16x16x32_bf16 v[38:41], v[162:165], v[186:189], v[38:41]
	v_mfma_f32_16x16x32_bf16 v[34:37], v[170:173], v[186:189], v[34:37]
	v_mfma_f32_16x16x32_bf16 v[22:25], v[162:165], v[194:197], v[22:25]
	v_mfma_f32_16x16x32_bf16 v[18:21], v[170:173], v[194:197], v[18:21]
	v_mfma_f32_16x16x32_bf16 v[6:9], v[162:165], v[204:207], v[6:9]
	v_mfma_f32_16x16x32_bf16 v[2:5], v[170:173], v[204:207], v[2:5]
	s_barrier
	s_setprio 0
	v_add_u32_e32 v141, 0x18000, v139
	ds_read_b128 v[142:145], v141
	ds_read_b128 v[146:149], v141 offset:1024
	ds_read_b128 v[150:153], v141 offset:2048
	ds_read_b128 v[154:157], v141 offset:3072
	v_add_u32_e32 v141, 0x1c000, v139
	ds_read_b128 v[158:161], v141
	ds_read_b128 v[162:165], v141 offset:1024
	ds_read_b128 v[166:169], v141 offset:2048
	ds_read_b128 v[170:173], v141 offset:3072
	ds_read_b128 v[174:177], v140 offset:32768
	ds_read_b128 v[178:181], v140 offset:33792
	ds_read_b128 v[182:185], v140 offset:34816
	ds_read_b128 v[186:189], v140 offset:35840
	ds_read_b128 v[190:193], v140 offset:36864
	ds_read_b128 v[194:197], v140 offset:37888
	ds_read_b128 v[198:201], v140 offset:38912
	ds_read_b128 v[204:207], v140 offset:39936
	s_add_u32 s34, s34, 0x160000
	s_addc_u32 s35, s35, 0
	s_mov_b32 m0, s46
	s_nop 0
	global_load_lds_dwordx4 v131, s[34:35]
	s_nop 0
	s_mov_b32 m0, s47
	s_nop 0
	global_load_lds_dwordx4 v137, s[34:35]
	s_waitcnt vmcnt(8)
	s_waitcnt lgkmcnt(0)
	s_setprio 1
	s_barrier
	v_mfma_f32_16x16x32_bf16 v[126:129], v[142:145], v[174:177], v[126:129]
	v_mfma_f32_16x16x32_bf16 v[122:125], v[150:153], v[174:177], v[122:125]
	v_mfma_f32_16x16x32_bf16 v[110:113], v[142:145], v[182:185], v[110:113]
	v_mfma_f32_16x16x32_bf16 v[106:109], v[150:153], v[182:185], v[106:109]
	v_mfma_f32_16x16x32_bf16 v[94:97], v[142:145], v[190:193], v[94:97]
	v_mfma_f32_16x16x32_bf16 v[90:93], v[150:153], v[190:193], v[90:93]
	v_mfma_f32_16x16x32_bf16 v[78:81], v[142:145], v[198:201], v[78:81]
	v_mfma_f32_16x16x32_bf16 v[74:77], v[150:153], v[198:201], v[74:77]
	v_mfma_f32_16x16x32_bf16 v[126:129], v[146:149], v[178:181], v[126:129]
	v_mfma_f32_16x16x32_bf16 v[122:125], v[154:157], v[178:181], v[122:125]
	v_mfma_f32_16x16x32_bf16 v[110:113], v[146:149], v[186:189], v[110:113]
	v_mfma_f32_16x16x32_bf16 v[106:109], v[154:157], v[186:189], v[106:109]
	v_mfma_f32_16x16x32_bf16 v[94:97], v[146:149], v[194:197], v[94:97]
	v_mfma_f32_16x16x32_bf16 v[90:93], v[154:157], v[194:197], v[90:93]
	v_mfma_f32_16x16x32_bf16 v[78:81], v[146:149], v[204:207], v[78:81]
	v_mfma_f32_16x16x32_bf16 v[74:77], v[154:157], v[204:207], v[74:77]
	v_mfma_f32_16x16x32_bf16 v[118:121], v[158:161], v[174:177], v[118:121]
	v_mfma_f32_16x16x32_bf16 v[114:117], v[166:169], v[174:177], v[114:117]
	v_mfma_f32_16x16x32_bf16 v[102:105], v[158:161], v[182:185], v[102:105]
	v_mfma_f32_16x16x32_bf16 v[98:101], v[166:169], v[182:185], v[98:101]
	v_mfma_f32_16x16x32_bf16 v[86:89], v[158:161], v[190:193], v[86:89]
	v_mfma_f32_16x16x32_bf16 v[82:85], v[166:169], v[190:193], v[82:85]
	v_mfma_f32_16x16x32_bf16 v[70:73], v[158:161], v[198:201], v[70:73]
	v_mfma_f32_16x16x32_bf16 v[66:69], v[166:169], v[198:201], v[66:69]
	v_mfma_f32_16x16x32_bf16 v[118:121], v[162:165], v[178:181], v[118:121]
	v_mfma_f32_16x16x32_bf16 v[114:117], v[170:173], v[178:181], v[114:117]
	v_mfma_f32_16x16x32_bf16 v[102:105], v[162:165], v[186:189], v[102:105]
	v_mfma_f32_16x16x32_bf16 v[98:101], v[170:173], v[186:189], v[98:101]
	v_mfma_f32_16x16x32_bf16 v[86:89], v[162:165], v[194:197], v[86:89]
	v_mfma_f32_16x16x32_bf16 v[82:85], v[170:173], v[194:197], v[82:85]
	v_mfma_f32_16x16x32_bf16 v[70:73], v[162:165], v[204:207], v[70:73]
	v_mfma_f32_16x16x32_bf16 v[66:69], v[170:173], v[204:207], v[66:69]
	s_barrier
; #define PG8_STAGE(bufoff, gbase, voff) do { _Pragma("unroll") for (int _i = 0; _i < 2; ++_i) { unsigned keep_; \
;         asm volatile("s_mov_b32 %0, m0\n\ts_mov_b32 m0, %3\n\ts_nop 0\n\tglobal_load_lds_dwordx4 %1, %2\n\ts_mov_b32 m0, %0" \
;             : "=&s"(keep_) : "v"((voff)[_i]), "s"((const void*)(gbase)), "s"(ldsb0 + (unsigned)(bufoff) + (unsigned)(_i * 8192)) : "memory"); } } while (0)
; #define PG8_LDA(dst, b, h) do { _Pragma("unroll") for (int m = 0; m < 4; ++m) _Pragma("unroll") for (int k = 0; k < 2; ++k) dst[m][k] = *(const LAS bf16x8*)(lds + PG8_SA(b, h) + aoff + m * 2048 + k * 1024); } while (0)
; #define PG8_MMA(ai, bj, At, Bt) do { __builtin_amdgcn_s_setprio(1); _Pragma("unroll") for (int m = 0; m < 4; ++m) _Pragma("unroll") for (int n = 0; n < 2; ++n) _Pragma("unroll") for (int k = 0; k < 2; ++k) \
;         acc[ai][bj][m][n] = __builtin_amdgcn_mfma_f32_16x16x32_bf16(Bt[n][k], At[m][k], acc[ai][bj][m][n], 0, 0, 0); __builtin_amdgcn_s_setprio(0); } while (0)
; #define PG8_WAIT_V(n) asm volatile("s_waitcnt vmcnt(" #n ")" ::: "memory")
; #define PG8_WAIT_L(n) asm volatile("s_waitcnt lgkmcnt(" #n ")" ::: "memory")
; #define PG8_BAR __builtin_amdgcn_s_barrier()
; #define PG8_SCHED __builtin_amdgcn_sched_barrier(0)
; template <class Epi, class Sched, bool ALIGN_EPI>
; __device__ __forceinline__ void gemm_phase(LAS unsigned char* lds, const Gemm g, const Sched& S, const Epi& E) {
;     ...
;             PG8_LDA(At, 1, 1); PG8_STAGE(PG8_SB(1, 0), b3, voffB); PG8_STAGE(PG8_SB(1, 1), b3 + hstepB, voffB); PG8_STAGE(PG8_SA(1, 0), a3, voffA);
;             PG8_WAIT_V(8); PG8_WAIT_L(0); PG8_BAR; PG8_MMA(1, 0, At, B0); PG8_MMA(1, 1, At, B1); PG8_BAR; PG8_SCHED;
;     ...
; #pragma unroll
;         for (int a = 0; a < 2; ++a)
; #pragma unroll
;             for (int b = 0; b < 2; ++b)
; #pragma unroll
;                 for (int m = 0; m < 4; ++m)
; #pragma unroll
;                     for (int n = 0; n < 2; ++n) acc[a][b][m][n] = (f32x4){0.f, 0.f, 0.f, 0.f};
;         cur = nxt; cA = nA; cB = nB; ++ui;
	s_setprio 0
	ds_read_b128 v[174:177], v140 offset:49152
	ds_read_b128 v[178:181], v140 offset:50176
	ds_read_b128 v[182:185], v140 offset:51200
	ds_read_b128 v[186:189], v140 offset:52224
	ds_read_b128 v[190:193], v140 offset:53248
	ds_read_b128 v[194:197], v140 offset:54272
	ds_read_b128 v[198:201], v140 offset:55296
	ds_read_b128 v[204:207], v140 offset:56320
	s_add_u32 s34, s30, 0x80
	s_addc_u32 s35, s31, 0
	s_mov_b32 m0, s48
	s_nop 0
	global_load_lds_dwordx4 v136, s[34:35]
	s_add_u32 s30, s30, 0x160080
	s_mov_b32 m0, s49
	s_nop 0
	global_load_lds_dwordx4 v138, s[34:35]
	s_addc_u32 s31, s31, 0
	s_mov_b32 m0, s52
	s_nop 0
	global_load_lds_dwordx4 v136, s[30:31]
	s_nop 0
	s_mov_b32 m0, s53
	s_nop 0
	global_load_lds_dwordx4 v138, s[30:31]
	s_mov_b32 m0, s50
	s_nop 0
	global_load_lds_dwordx4 v131, s[28:29]
	s_nop 0
	s_mov_b32 m0, s51
	s_nop 0
	global_load_lds_dwordx4 v137, s[28:29]
	s_waitcnt vmcnt(8)
	s_waitcnt lgkmcnt(0)
	s_setprio 1
	s_barrier
	v_mfma_f32_16x16x32_bf16 v[62:65], v[142:145], v[174:177], v[62:65]
	v_mfma_f32_16x16x32_bf16 v[58:61], v[150:153], v[174:177], v[58:61]
	v_mfma_f32_16x16x32_bf16 v[46:49], v[142:145], v[182:185], v[46:49]
	v_mfma_f32_16x16x32_bf16 v[42:45], v[150:153], v[182:185], v[42:45]
	v_mfma_f32_16x16x32_bf16 v[30:33], v[142:145], v[190:193], v[30:33]
	v_mfma_f32_16x16x32_bf16 v[26:29], v[150:153], v[190:193], v[26:29]
	v_mfma_f32_16x16x32_bf16 v[14:17], v[142:145], v[198:201], v[14:17]
	v_mfma_f32_16x16x32_bf16 v[10:13], v[150:153], v[198:201], v[10:13]
	v_mfma_f32_16x16x32_bf16 v[62:65], v[146:149], v[178:181], v[62:65]
	v_mfma_f32_16x16x32_bf16 v[58:61], v[154:157], v[178:181], v[58:61]
	v_mfma_f32_16x16x32_bf16 v[46:49], v[146:149], v[186:189], v[46:49]
	v_mfma_f32_16x16x32_bf16 v[42:45], v[154:157], v[186:189], v[42:45]
	v_mfma_f32_16x16x32_bf16 v[30:33], v[146:149], v[194:197], v[30:33]
	v_mfma_f32_16x16x32_bf16 v[26:29], v[154:157], v[194:197], v[26:29]
	v_mfma_f32_16x16x32_bf16 v[14:17], v[146:149], v[204:207], v[14:17]
	v_mfma_f32_16x16x32_bf16 v[10:13], v[154:157], v[204:207], v[10:13]
	v_mfma_f32_16x16x32_bf16 v[54:57], v[158:161], v[174:177], v[54:57]
	v_mfma_f32_16x16x32_bf16 v[50:53], v[166:169], v[174:177], v[50:53]
	v_mfma_f32_16x16x32_bf16 v[38:41], v[158:161], v[182:185], v[38:41]
	v_mfma_f32_16x16x32_bf16 v[34:37], v[166:169], v[182:185], v[34:37]
	v_mfma_f32_16x16x32_bf16 v[22:25], v[158:161], v[190:193], v[22:25]
	v_mfma_f32_16x16x32_bf16 v[18:21], v[166:169], v[190:193], v[18:21]
	v_mfma_f32_16x16x32_bf16 v[6:9], v[158:161], v[198:201], v[6:9]
	v_mfma_f32_16x16x32_bf16 v[2:5], v[166:169], v[198:201], v[2:5]
	v_mfma_f32_16x16x32_bf16 v[54:57], v[162:165], v[178:181], v[54:57]
	v_mfma_f32_16x16x32_bf16 v[50:53], v[170:173], v[178:181], v[50:53]
	v_mfma_f32_16x16x32_bf16 v[38:41], v[162:165], v[186:189], v[38:41]
	v_mfma_f32_16x16x32_bf16 v[34:37], v[170:173], v[186:189], v[34:37]
	v_mfma_f32_16x16x32_bf16 v[22:25], v[162:165], v[194:197], v[22:25]
	v_mfma_f32_16x16x32_bf16 v[18:21], v[170:173], v[194:197], v[18:21]
	v_mfma_f32_16x16x32_bf16 v[6:9], v[162:165], v[204:207], v[6:9]
	v_mfma_f32_16x16x32_bf16 v[2:5], v[170:173], v[204:207], v[2:5]
	s_barrier
	s_setprio 0
	s_add_i32 s60, s60, 2
	s_add_u32 s26, s26, 0x100
	s_addc_u32 s27, s27, 0
	s_cmpk_gt_u32 s60, 0x55
	s_cbranch_scc0 .LBB0_2172
	s_and_b64 vcc, exec, s[10:11]
	s_cbranch_vccnz .LBB0_2160
	v_mov_b32_e32 v2, 0
	s_mov_b32 s45, s57
	s_mov_b32 s17, s58
	s_mov_b64 s[20:21], s[24:25]
	s_mov_b64 s[22:23], s[12:13]
	s_mov_b32 s56, s59
	v_mov_b32_e32 v3, v2
	v_mov_b32_e32 v4, v2
	v_mov_b32_e32 v5, v2
	v_mov_b32_e32 v6, v2
	v_mov_b32_e32 v7, v2
	v_mov_b32_e32 v8, v2
	v_mov_b32_e32 v9, v2
	v_mov_b32_e32 v18, v2
	v_mov_b32_e32 v19, v2
	v_mov_b32_e32 v20, v2
	v_mov_b32_e32 v21, v2
	v_mov_b32_e32 v22, v2
	v_mov_b32_e32 v23, v2
	v_mov_b32_e32 v24, v2
	v_mov_b32_e32 v25, v2
	v_mov_b32_e32 v34, v2
	v_mov_b32_e32 v35, v2
	v_mov_b32_e32 v36, v2
	v_mov_b32_e32 v37, v2
	v_mov_b32_e32 v38, v2
	v_mov_b32_e32 v39, v2
	v_mov_b32_e32 v40, v2
	v_mov_b32_e32 v41, v2
	v_mov_b32_e32 v50, v2
	v_mov_b32_e32 v51, v2
	v_mov_b32_e32 v52, v2
	v_mov_b32_e32 v53, v2
	v_mov_b32_e32 v54, v2
	v_mov_b32_e32 v55, v2
	v_mov_b32_e32 v56, v2
	v_mov_b32_e32 v57, v2
	v_mov_b32_e32 v10, v2
	v_mov_b32_e32 v11, v2
	v_mov_b32_e32 v12, v2
	v_mov_b32_e32 v13, v2
	v_mov_b32_e32 v14, v2
	v_mov_b32_e32 v15, v2
	v_mov_b32_e32 v16, v2
	v_mov_b32_e32 v17, v2
	v_mov_b32_e32 v26, v2
	v_mov_b32_e32 v27, v2
	v_mov_b32_e32 v28, v2
	v_mov_b32_e32 v29, v2
	v_mov_b32_e32 v30, v2
	v_mov_b32_e32 v31, v2
	v_mov_b32_e32 v32, v2
	v_mov_b32_e32 v33, v2
	v_mov_b32_e32 v42, v2
	v_mov_b32_e32 v43, v2
	v_mov_b32_e32 v44, v2
	v_mov_b32_e32 v45, v2
	v_mov_b32_e32 v46, v2
	v_mov_b32_e32 v47, v2
	v_mov_b32_e32 v48, v2
	v_mov_b32_e32 v49, v2
	v_mov_b32_e32 v58, v2
	v_mov_b32_e32 v59, v2
	v_mov_b32_e32 v60, v2
	v_mov_b32_e32 v61, v2
	v_mov_b32_e32 v62, v2
	v_mov_b32_e32 v63, v2
	v_mov_b32_e32 v64, v2
	v_mov_b32_e32 v65, v2
	v_mov_b32_e32 v66, v2
	v_mov_b32_e32 v67, v2
	v_mov_b32_e32 v68, v2
	v_mov_b32_e32 v69, v2
	v_mov_b32_e32 v70, v2
	v_mov_b32_e32 v71, v2
	v_mov_b32_e32 v72, v2
	v_mov_b32_e32 v73, v2
	v_mov_b32_e32 v82, v2
	v_mov_b32_e32 v83, v2
	v_mov_b32_e32 v84, v2
	v_mov_b32_e32 v85, v2
	v_mov_b32_e32 v86, v2
	v_mov_b32_e32 v87, v2
	v_mov_b32_e32 v88, v2
	v_mov_b32_e32 v89, v2
	v_mov_b32_e32 v98, v2
	v_mov_b32_e32 v99, v2
	v_mov_b32_e32 v100, v2
	v_mov_b32_e32 v101, v2
	v_mov_b32_e32 v102, v2
	v_mov_b32_e32 v103, v2
	v_mov_b32_e32 v104, v2
	v_mov_b32_e32 v105, v2
	v_mov_b32_e32 v114, v2
	v_mov_b32_e32 v115, v2
	v_mov_b32_e32 v116, v2
	v_mov_b32_e32 v117, v2
	v_mov_b32_e32 v118, v2
	v_mov_b32_e32 v119, v2
	v_mov_b32_e32 v120, v2
	v_mov_b32_e32 v121, v2
	v_mov_b32_e32 v74, v2
	v_mov_b32_e32 v75, v2
	v_mov_b32_e32 v76, v2
	v_mov_b32_e32 v77, v2
	v_mov_b32_e32 v78, v2
	v_mov_b32_e32 v79, v2
	v_mov_b32_e32 v80, v2
	v_mov_b32_e32 v81, v2
	v_mov_b32_e32 v90, v2
	v_mov_b32_e32 v91, v2
	v_mov_b32_e32 v92, v2
	v_mov_b32_e32 v93, v2
	v_mov_b32_e32 v94, v2
	v_mov_b32_e32 v95, v2
	v_mov_b32_e32 v96, v2
	v_mov_b32_e32 v97, v2
	v_mov_b32_e32 v106, v2
	v_mov_b32_e32 v107, v2
	v_mov_b32_e32 v108, v2
	v_mov_b32_e32 v109, v2
	v_mov_b32_e32 v110, v2
	v_mov_b32_e32 v111, v2
	v_mov_b32_e32 v112, v2
	v_mov_b32_e32 v113, v2
	v_mov_b32_e32 v122, v2
	v_mov_b32_e32 v123, v2
	v_mov_b32_e32 v124, v2
	v_mov_b32_e32 v125, v2
	v_mov_b32_e32 v126, v2
	v_mov_b32_e32 v127, v2
	v_mov_b32_e32 v128, v2
	v_mov_b32_e32 v129, v2
	s_branch .LBB0_2160
